# gemm K-loops: per-phase s_setprio 1/0 flips deleted (A/B of the flips; timing-only change)
# speedup vs baseline: 1.0105x; 1.0086x over previous
; #define PG8_STAGE(bufoff, gbase, voff) do { _Pragma("unroll") for (int _i = 0; _i < 2; ++_i) \
;         __builtin_amdgcn_global_load_lds((const unsigned*)((const char*)(gbase) + (voff)[_i]), (PG8_LAS unsigned*)(lds + (bufoff) + ldsw + _i * 8192), 16, 0, 0); } while (0)
; #define PG8_LDA(dst, b, h) do { _Pragma("unroll") for (int m = 0; m < 4; ++m) _Pragma("unroll") for (int k = 0; k < 2; ++k) dst[m][k] = *(const PG8_LAS bf16x8*)(lds + PG8_SA(b, h) + aoff + m * 2048 + k * 1024); } while (0)
; #define PG8_LDB(dst, b, h) do { _Pragma("unroll") for (int n = 0; n < 2; ++n) _Pragma("unroll") for (int k = 0; k < 2; ++k) dst[n][k] = *(const PG8_LAS bf16x8*)(lds + PG8_SB(b, h) + boff + n * 2048 + k * 1024); } while (0)
; #define PG8_MMA(ai, bj, At, Bt) do { __builtin_amdgcn_s_setprio(1); _Pragma("unroll") for (int m = 0; m < 4; ++m) _Pragma("unroll") for (int n = 0; n < 2; ++n) _Pragma("unroll") for (int k = 0; k < 2; ++k) \
;         acc[ai][bj][m][n] = __builtin_amdgcn_mfma_f32_16x16x32_bf16(Bt[n][k], At[m][k], acc[ai][bj][m][n], 0, 0, 0); __builtin_amdgcn_s_setprio(0); } while (0)
; #define PG8_WAIT_L(n) asm volatile("s_waitcnt lgkmcnt(" #n ")" ::: "memory")
; #define PG8_BAR __builtin_amdgcn_s_barrier()
; #define PG8_SCHED __builtin_amdgcn_sched_barrier(0)
; template <class Epi, class Sched>
; __device__ __forceinline__ void gemm_phase(PG8_LAS unsigned char* lds, const Gemm g, const Sched& S, const Epi& E) {
;     ...
;             const char* a2 = last ? nA : cA + (size_t)(t + 2) * kstep; const char* b2 = last ? nB : cB + (size_t)(t + 2) * kstep;
;             const char* a3 = a2 + kstep; const char* b3 = b2 + kstep;
;             if (last && has_next) S.a_ready(nxt);
;             PG8_LDB(B0, 0, 0); PG8_SCHED; PG8_LDA(At, 0, 0); PG8_STAGE(PG8_SA(1, 1), a1 + hstep, voffA);
;             PG8_WAIT_L(8); PG8_BAR; PG8_WAIT_L(0); PG8_MMA(0, 0, At, B0); PG8_BAR; PG8_SCHED;
;             PG8_LDB(B1, 0, 1); PG8_STAGE(PG8_SB(0, 0), b2, voffB);
;             PG8_BAR; PG8_WAIT_L(0); PG8_MMA(0, 1, At, B1); PG8_BAR;
;             PG8_LDA(At, 0, 1); PG8_STAGE(PG8_SA(0, 0), a2, voffA);
;             PG8_BAR; PG8_WAIT_L(0); PG8_MMA(1, 0, At, B0); PG8_BAR; PG8_SCHED;
.LBB0_267:
	s_add_u32 s16, s16, 0x80
	s_addc_u32 s17, s17, 0
	s_add_u32 s24, s20, 0x100
	s_addc_u32 s25, s21, 0
	s_mov_b32 s20, 0
	s_add_i32 s42, s20, 2
	s_add_u32 s22, s16, 0x80
	s_addc_u32 s21, s17, 0
	s_add_i32 s43, 0, 0x10000
	v_add_u32_e32 v142, s43, v170
	ds_read_b128 v[130:133], v142
	ds_read_b128 v[134:137], v142 offset:1024
	ds_read_b128 v[138:141], v142 offset:2048
	ds_read_b128 v[142:145], v142 offset:3072
	s_cmp_eq_u32 s66, s20
	s_cselect_b32 s20, s2, s22
	s_cselect_b32 s21, s3, s21
	s_cselect_b32 s23, s13, s25
	s_cselect_b32 s22, s12, s24
	v_lshl_add_u64 v[168:169], s[16:17], 0, v[164:165]
	s_add_i32 m0, s36, 0xc000
	ds_read_b128 v[176:179], v172
	ds_read_b128 v[180:183], v172 offset:1024
	ds_read_b128 v[184:187], v172 offset:2048
	ds_read_b128 v[188:191], v172 offset:3072
	ds_read_b128 v[192:195], v172 offset:4096
	ds_read_b128 v[196:199], v172 offset:5120
	ds_read_b128 v[200:203], v172 offset:6144
	ds_read_b128 v[204:207], v172 offset:7168
	global_load_lds_dwordx4 v[168:169], off
	v_lshl_add_u64 v[168:169], s[16:17], 0, v[166:167]
	s_add_i32 m0, s36, 0xe000
	s_nop 0
	global_load_lds_dwordx4 v[168:169], off
	s_waitcnt lgkmcnt(8)
	s_barrier
	s_waitcnt lgkmcnt(7)
	v_mfma_f32_16x16x32_bf16 v[126:129], v[130:133], v[176:179], 0
	v_mfma_f32_16x16x32_bf16 v[122:125], v[138:141], v[176:179], 0
	s_waitcnt lgkmcnt(5)
	v_mfma_f32_16x16x32_bf16 v[114:117], v[130:133], v[184:187], 0
	v_mfma_f32_16x16x32_bf16 v[110:113], v[138:141], v[184:187], 0
	s_waitcnt lgkmcnt(3)
	v_mfma_f32_16x16x32_bf16 v[98:101], v[130:133], v[192:195], 0
	v_mfma_f32_16x16x32_bf16 v[94:97], v[138:141], v[192:195], 0
	s_waitcnt lgkmcnt(1)
	v_mfma_f32_16x16x32_bf16 v[82:85], v[130:133], v[200:203], 0
	v_mfma_f32_16x16x32_bf16 v[78:81], v[138:141], v[200:203], 0
	v_mfma_f32_16x16x32_bf16 v[126:129], v[134:137], v[180:183], v[126:129]
	v_mfma_f32_16x16x32_bf16 v[122:125], v[142:145], v[180:183], v[122:125]
	v_mfma_f32_16x16x32_bf16 v[114:117], v[134:137], v[188:191], v[114:117]
	v_mfma_f32_16x16x32_bf16 v[110:113], v[142:145], v[188:191], v[110:113]
	v_mfma_f32_16x16x32_bf16 v[98:101], v[134:137], v[196:199], v[98:101]
	v_mfma_f32_16x16x32_bf16 v[94:97], v[142:145], v[196:199], v[94:97]
	s_waitcnt lgkmcnt(0)
	v_mfma_f32_16x16x32_bf16 v[82:85], v[134:137], v[204:207], v[82:85]
	v_mfma_f32_16x16x32_bf16 v[78:81], v[142:145], v[204:207], v[78:81]
	s_barrier
	s_add_i32 s44, 0, 0x14000
	v_add_u32_e32 v168, s44, v170
	s_add_i32 s43, s43, s35
	ds_read_b128 v[208:211], v168
	ds_read_b128 v[212:215], v168 offset:1024
	ds_read_b128 v[216:219], v168 offset:2048
	ds_read_b128 v[234:237], v168 offset:3072
	v_lshl_add_u64 v[168:169], s[22:23], 0, v[48:49]
	s_mov_b32 m0, s43
	v_lshl_add_u64 v[224:225], s[22:23], 0, v[146:147]
	global_load_lds_dwordx4 v[168:169], off
	s_add_i32 m0, s43, 0x2000
	s_nop 0
	global_load_lds_dwordx4 v[224:225], off
	s_barrier
	s_waitcnt lgkmcnt(3)
	v_mfma_f32_16x16x32_bf16 v[118:121], v[208:211], v[176:179], 0
	s_waitcnt lgkmcnt(1)
	v_mfma_f32_16x16x32_bf16 v[106:109], v[216:219], v[176:179], 0
	v_mfma_f32_16x16x32_bf16 v[102:105], v[208:211], v[184:187], 0
	v_mfma_f32_16x16x32_bf16 v[90:93], v[216:219], v[184:187], 0
	v_mfma_f32_16x16x32_bf16 v[86:89], v[208:211], v[192:195], 0
	v_mfma_f32_16x16x32_bf16 v[74:77], v[216:219], v[192:195], 0
	v_mfma_f32_16x16x32_bf16 v[70:73], v[208:211], v[200:203], 0
	v_mfma_f32_16x16x32_bf16 v[66:69], v[216:219], v[200:203], 0
	v_mfma_f32_16x16x32_bf16 v[118:121], v[212:215], v[180:183], v[118:121]
	s_waitcnt lgkmcnt(0)
	v_mfma_f32_16x16x32_bf16 v[106:109], v[234:237], v[180:183], v[106:109]
	v_mfma_f32_16x16x32_bf16 v[102:105], v[212:215], v[188:191], v[102:105]
	v_mfma_f32_16x16x32_bf16 v[90:93], v[234:237], v[188:191], v[90:93]
	v_mfma_f32_16x16x32_bf16 v[86:89], v[212:215], v[196:199], v[86:89]
	v_mfma_f32_16x16x32_bf16 v[74:77], v[234:237], v[196:199], v[74:77]
	v_mfma_f32_16x16x32_bf16 v[70:73], v[212:215], v[204:207], v[70:73]
	v_mfma_f32_16x16x32_bf16 v[66:69], v[234:237], v[204:207], v[66:69]
	s_mov_b32 m0, s36
	v_lshl_add_u64 v[228:229], s[20:21], 0, v[48:49]
	s_barrier
	ds_read_b128 v[176:179], v172 offset:16384
	ds_read_b128 v[180:183], v172 offset:17408
	ds_read_b128 v[184:187], v172 offset:18432
	ds_read_b128 v[188:191], v172 offset:19456
	ds_read_b128 v[192:195], v172 offset:20480
	ds_read_b128 v[196:199], v172 offset:21504
	ds_read_b128 v[200:203], v172 offset:22528
	ds_read_b128 v[204:207], v172 offset:23552
	global_load_lds_dwordx4 v[228:229], off
	v_lshl_add_u64 v[238:239], s[20:21], 0, v[146:147]
	s_mov_b32 m0, s37
	s_nop 0
	global_load_lds_dwordx4 v[238:239], off
	s_barrier
	s_waitcnt lgkmcnt(7)
	v_mfma_f32_16x16x32_bf16 v[62:65], v[130:133], v[176:179], 0
	v_mfma_f32_16x16x32_bf16 v[58:61], v[138:141], v[176:179], 0
	s_waitcnt lgkmcnt(5)
	v_mfma_f32_16x16x32_bf16 v[50:53], v[130:133], v[184:187], 0
	v_mfma_f32_16x16x32_bf16 v[44:47], v[138:141], v[184:187], 0
	s_waitcnt lgkmcnt(3)
	v_mfma_f32_16x16x32_bf16 v[32:35], v[130:133], v[192:195], 0
	v_mfma_f32_16x16x32_bf16 v[28:31], v[138:141], v[192:195], 0
	s_waitcnt lgkmcnt(1)
	v_mfma_f32_16x16x32_bf16 v[16:19], v[130:133], v[200:203], 0
	v_mfma_f32_16x16x32_bf16 v[12:15], v[138:141], v[200:203], 0
	v_mfma_f32_16x16x32_bf16 v[62:65], v[134:137], v[180:183], v[62:65]
	v_mfma_f32_16x16x32_bf16 v[58:61], v[142:145], v[180:183], v[58:61]
	v_mfma_f32_16x16x32_bf16 v[50:53], v[134:137], v[188:191], v[50:53]
	v_mfma_f32_16x16x32_bf16 v[44:47], v[142:145], v[188:191], v[44:47]
	v_mfma_f32_16x16x32_bf16 v[32:35], v[134:137], v[196:199], v[32:35]
	v_mfma_f32_16x16x32_bf16 v[28:31], v[142:145], v[196:199], v[28:31]
	s_waitcnt lgkmcnt(0)
	v_mfma_f32_16x16x32_bf16 v[16:19], v[134:137], v[204:207], v[16:19]
	v_mfma_f32_16x16x32_bf16 v[12:15], v[142:145], v[204:207], v[12:15]
	s_barrier
; #define PG8_STAGE(bufoff, gbase, voff) do { _Pragma("unroll") for (int _i = 0; _i < 2; ++_i) \
;         __builtin_amdgcn_global_load_lds((const unsigned*)((const char*)(gbase) + (voff)[_i]), (PG8_LAS unsigned*)(lds + (bufoff) + ldsw + _i * 8192), 16, 0, 0); } while (0)
; #define PG8_LDA(dst, b, h) do { _Pragma("unroll") for (int m = 0; m < 4; ++m) _Pragma("unroll") for (int k = 0; k < 2; ++k) dst[m][k] = *(const PG8_LAS bf16x8*)(lds + PG8_SA(b, h) + aoff + m * 2048 + k * 1024); } while (0)
; #define PG8_LDB(dst, b, h) do { _Pragma("unroll") for (int n = 0; n < 2; ++n) _Pragma("unroll") for (int k = 0; k < 2; ++k) dst[n][k] = *(const PG8_LAS bf16x8*)(lds + PG8_SB(b, h) + boff + n * 2048 + k * 1024); } while (0)
; #define PG8_MMA(ai, bj, At, Bt) do { __builtin_amdgcn_s_setprio(1); _Pragma("unroll") for (int m = 0; m < 4; ++m) _Pragma("unroll") for (int n = 0; n < 2; ++n) _Pragma("unroll") for (int k = 0; k < 2; ++k) \
;         acc[ai][bj][m][n] = __builtin_amdgcn_mfma_f32_16x16x32_bf16(Bt[n][k], At[m][k], acc[ai][bj][m][n], 0, 0, 0); __builtin_amdgcn_s_setprio(0); } while (0)
; #define PG8_WAIT_V(n) asm volatile("s_waitcnt vmcnt(" #n ")" ::: "memory")
; #define PG8_WAIT_L(n) asm volatile("s_waitcnt lgkmcnt(" #n ")" ::: "memory")
; #define PG8_BAR __builtin_amdgcn_s_barrier()
; #define PG8_SCHED __builtin_amdgcn_sched_barrier(0)
; template <class Epi, class Sched>
; __device__ __forceinline__ void gemm_phase(PG8_LAS unsigned char* lds, const Gemm g, const Sched& S, const Epi& E) {
;     ...
;             PG8_STAGE(PG8_SB(0, 1), b2 + hstep, voffB);
;             PG8_WAIT_V(6); PG8_BAR; PG8_MMA(1, 1, At, B1); PG8_BAR;
;             PG8_LDB(B0, 1, 0); PG8_SCHED; PG8_LDA(At, 1, 0); PG8_STAGE(PG8_SA(0, 1), a2 + hstep, voffA);
;             PG8_WAIT_L(8); PG8_BAR; PG8_WAIT_L(0); PG8_MMA(0, 0, At, B0); PG8_BAR; PG8_SCHED;
;             PG8_LDB(B1, 1, 1); PG8_STAGE(PG8_SB(1, 0), b3, voffB);
;             PG8_BAR; PG8_WAIT_L(0); PG8_MMA(0, 1, At, B1); PG8_BAR;
;             PG8_LDA(At, 1, 1); PG8_STAGE(PG8_SA(1, 0), a3, voffA);
	s_add_u32 s22, s22, s10
	s_addc_u32 s23, s23, 0
	s_add_i32 s43, s44, s35
	v_lshl_add_u64 v[240:241], s[22:23], 0, v[48:49]
	s_mov_b32 m0, s43
	v_lshl_add_u64 v[242:243], s[22:23], 0, v[146:147]
	global_load_lds_dwordx4 v[240:241], off
	s_add_i32 m0, s43, 0x2000
	s_nop 0
	global_load_lds_dwordx4 v[242:243], off
	s_waitcnt vmcnt(6)
	s_barrier
	v_mfma_f32_16x16x32_bf16 v[54:57], v[208:211], v[176:179], 0
	v_mfma_f32_16x16x32_bf16 v[40:43], v[216:219], v[176:179], 0
	v_mfma_f32_16x16x32_bf16 v[36:39], v[208:211], v[184:187], 0
	v_mfma_f32_16x16x32_bf16 v[24:27], v[216:219], v[184:187], 0
	v_mfma_f32_16x16x32_bf16 v[20:23], v[208:211], v[192:195], 0
	v_mfma_f32_16x16x32_bf16 v[8:11], v[216:219], v[192:195], 0
	v_mfma_f32_16x16x32_bf16 v[4:7], v[208:211], v[200:203], 0
	v_mfma_f32_16x16x32_bf16 v[0:3], v[216:219], v[200:203], 0
	v_mfma_f32_16x16x32_bf16 v[54:57], v[212:215], v[180:183], v[54:57]
	v_mfma_f32_16x16x32_bf16 v[40:43], v[234:237], v[180:183], v[40:43]
	v_mfma_f32_16x16x32_bf16 v[36:39], v[212:215], v[188:191], v[36:39]
	v_mfma_f32_16x16x32_bf16 v[24:27], v[234:237], v[188:191], v[24:27]
	v_mfma_f32_16x16x32_bf16 v[20:23], v[212:215], v[196:199], v[20:23]
	v_mfma_f32_16x16x32_bf16 v[8:11], v[234:237], v[196:199], v[8:11]
	v_mfma_f32_16x16x32_bf16 v[4:7], v[212:215], v[204:207], v[4:7]
	v_mfma_f32_16x16x32_bf16 v[0:3], v[234:237], v[204:207], v[0:3]
	s_add_i32 s22, 0, 0x18000
	v_add_u32_e32 v142, s22, v170
	s_barrier
	ds_read_b128 v[130:133], v142
	ds_read_b128 v[134:137], v142 offset:1024
	ds_read_b128 v[138:141], v142 offset:2048
	ds_read_b128 v[142:145], v142 offset:3072
	s_add_u32 s20, s20, s10
	s_addc_u32 s21, s21, 0
	s_mov_b32 m0, s38
	v_lshl_add_u64 v[208:209], s[20:21], 0, v[48:49]
	ds_read_b128 v[176:179], v172 offset:32768
	ds_read_b128 v[180:183], v172 offset:33792
	ds_read_b128 v[184:187], v172 offset:34816
	ds_read_b128 v[188:191], v172 offset:35840
	ds_read_b128 v[192:195], v172 offset:36864
	ds_read_b128 v[196:199], v172 offset:37888
	ds_read_b128 v[200:203], v172 offset:38912
	ds_read_b128 v[204:207], v172 offset:39936
	global_load_lds_dwordx4 v[208:209], off
	v_lshl_add_u64 v[208:209], s[20:21], 0, v[146:147]
	s_mov_b32 m0, s39
	s_nop 0
	global_load_lds_dwordx4 v[208:209], off
	s_waitcnt lgkmcnt(8)
	s_barrier
	s_waitcnt lgkmcnt(7)
	v_mfma_f32_16x16x32_bf16 v[126:129], v[130:133], v[176:179], v[126:129]
	v_mfma_f32_16x16x32_bf16 v[122:125], v[138:141], v[176:179], v[122:125]
	s_waitcnt lgkmcnt(5)
	v_mfma_f32_16x16x32_bf16 v[114:117], v[130:133], v[184:187], v[114:117]
	v_mfma_f32_16x16x32_bf16 v[110:113], v[138:141], v[184:187], v[110:113]
	s_waitcnt lgkmcnt(3)
	v_mfma_f32_16x16x32_bf16 v[98:101], v[130:133], v[192:195], v[98:101]
	v_mfma_f32_16x16x32_bf16 v[94:97], v[138:141], v[192:195], v[94:97]
	s_waitcnt lgkmcnt(1)
	v_mfma_f32_16x16x32_bf16 v[82:85], v[130:133], v[200:203], v[82:85]
	v_mfma_f32_16x16x32_bf16 v[78:81], v[138:141], v[200:203], v[78:81]
	v_mfma_f32_16x16x32_bf16 v[126:129], v[134:137], v[180:183], v[126:129]
	v_mfma_f32_16x16x32_bf16 v[122:125], v[142:145], v[180:183], v[122:125]
	v_mfma_f32_16x16x32_bf16 v[114:117], v[134:137], v[188:191], v[114:117]
	v_mfma_f32_16x16x32_bf16 v[110:113], v[142:145], v[188:191], v[110:113]
	v_mfma_f32_16x16x32_bf16 v[98:101], v[134:137], v[196:199], v[98:101]
	v_mfma_f32_16x16x32_bf16 v[94:97], v[142:145], v[196:199], v[94:97]
	s_waitcnt lgkmcnt(0)
	v_mfma_f32_16x16x32_bf16 v[82:85], v[134:137], v[204:207], v[82:85]
	v_mfma_f32_16x16x32_bf16 v[78:81], v[142:145], v[204:207], v[78:81]
	s_barrier
	s_add_i32 s20, 0, 0x1c000
	s_add_i32 s21, s22, s35
	v_add_u32_e32 v173, s20, v170
	v_lshl_add_u64 v[168:169], v[168:169], 0, s[0:1]
	s_mov_b32 m0, s21
	ds_read_b128 v[208:211], v173
	ds_read_b128 v[212:215], v173 offset:1024
	ds_read_b128 v[216:219], v173 offset:2048
	ds_read_b128 v[234:237], v173 offset:3072
	global_load_lds_dwordx4 v[168:169], off
	v_lshl_add_u64 v[168:169], v[224:225], 0, s[0:1]
	s_add_i32 m0, s21, 0x2000
	s_nop 0
	global_load_lds_dwordx4 v[168:169], off
	s_barrier
	s_waitcnt lgkmcnt(3)
	v_mfma_f32_16x16x32_bf16 v[118:121], v[208:211], v[176:179], v[118:121]
	s_waitcnt lgkmcnt(1)
	v_mfma_f32_16x16x32_bf16 v[106:109], v[216:219], v[176:179], v[106:109]
	v_mfma_f32_16x16x32_bf16 v[102:105], v[208:211], v[184:187], v[102:105]
	v_mfma_f32_16x16x32_bf16 v[90:93], v[216:219], v[184:187], v[90:93]
	v_mfma_f32_16x16x32_bf16 v[86:89], v[208:211], v[192:195], v[86:89]
	v_mfma_f32_16x16x32_bf16 v[74:77], v[216:219], v[192:195], v[74:77]
	v_mfma_f32_16x16x32_bf16 v[70:73], v[208:211], v[200:203], v[70:73]
	v_mfma_f32_16x16x32_bf16 v[66:69], v[216:219], v[200:203], v[66:69]
	v_mfma_f32_16x16x32_bf16 v[118:121], v[212:215], v[180:183], v[118:121]
	s_waitcnt lgkmcnt(0)
	v_mfma_f32_16x16x32_bf16 v[106:109], v[234:237], v[180:183], v[106:109]
	v_mfma_f32_16x16x32_bf16 v[102:105], v[212:215], v[188:191], v[102:105]
	v_mfma_f32_16x16x32_bf16 v[90:93], v[234:237], v[188:191], v[90:93]
	v_mfma_f32_16x16x32_bf16 v[86:89], v[212:215], v[196:199], v[86:89]
	v_mfma_f32_16x16x32_bf16 v[74:77], v[234:237], v[196:199], v[74:77]
	v_mfma_f32_16x16x32_bf16 v[70:73], v[212:215], v[204:207], v[70:73]
	v_mfma_f32_16x16x32_bf16 v[66:69], v[234:237], v[204:207], v[66:69]
	s_mov_b32 m0, s64
	v_lshl_add_u64 v[168:169], v[228:229], 0, s[0:1]
	s_barrier
	ds_read_b128 v[176:179], v172 offset:49152
	ds_read_b128 v[180:183], v172 offset:50176
	ds_read_b128 v[184:187], v172 offset:51200
	ds_read_b128 v[188:191], v172 offset:52224
	ds_read_b128 v[192:195], v172 offset:53248
	ds_read_b128 v[196:199], v172 offset:54272
	ds_read_b128 v[200:203], v172 offset:55296
	ds_read_b128 v[204:207], v172 offset:56320
	global_load_lds_dwordx4 v[168:169], off
	v_lshl_add_u64 v[168:169], v[238:239], 0, s[0:1]
	s_mov_b32 m0, s65
	s_nop 0
	global_load_lds_dwordx4 v[168:169], off
	s_barrier
; #define PG8_STAGE(bufoff, gbase, voff) do { _Pragma("unroll") for (int _i = 0; _i < 2; ++_i) \
;         __builtin_amdgcn_global_load_lds((const unsigned*)((const char*)(gbase) + (voff)[_i]), (PG8_LAS unsigned*)(lds + (bufoff) + ldsw + _i * 8192), 16, 0, 0); } while (0)
; #define PG8_LDA(dst, b, h) do { _Pragma("unroll") for (int m = 0; m < 4; ++m) _Pragma("unroll") for (int k = 0; k < 2; ++k) dst[m][k] = *(const PG8_LAS bf16x8*)(lds + PG8_SA(b, h) + aoff + m * 2048 + k * 1024); } while (0)
; #define PG8_LDB(dst, b, h) do { _Pragma("unroll") for (int n = 0; n < 2; ++n) _Pragma("unroll") for (int k = 0; k < 2; ++k) dst[n][k] = *(const PG8_LAS bf16x8*)(lds + PG8_SB(b, h) + boff + n * 2048 + k * 1024); } while (0)
; #define PG8_MMA(ai, bj, At, Bt) do { __builtin_amdgcn_s_setprio(1); _Pragma("unroll") for (int m = 0; m < 4; ++m) _Pragma("unroll") for (int n = 0; n < 2; ++n) _Pragma("unroll") for (int k = 0; k < 2; ++k) \
;         acc[ai][bj][m][n] = __builtin_amdgcn_mfma_f32_16x16x32_bf16(Bt[n][k], At[m][k], acc[ai][bj][m][n], 0, 0, 0); __builtin_amdgcn_s_setprio(0); } while (0)
; #define PG8_WAIT_V(n) asm volatile("s_waitcnt vmcnt(" #n ")" ::: "memory")
; #define PG8_WAIT_L(n) asm volatile("s_waitcnt lgkmcnt(" #n ")" ::: "memory")
; template <class Epi, class Sched>
; __device__ __forceinline__ void gemm_phase(PG8_LAS unsigned char* lds, const Gemm g, const Sched& S, const Epi& E) {
;     ...
;         for (int t = 0; t < nt; t += 2) {
;             const bool last = (t == nt - 2);
;             const char* a1 = cA + (size_t)(t + 1) * kstep;
;             const char* a2 = last ? nA : cA + (size_t)(t + 2) * kstep; const char* b2 = last ? nB : cB + (size_t)(t + 2) * kstep;
;             const char* a3 = a2 + kstep; const char* b3 = b2 + kstep;
;             if (last && has_next) S.a_ready(nxt);
;             PG8_LDB(B0, 0, 0); PG8_SCHED; PG8_LDA(At, 0, 0); PG8_STAGE(PG8_SA(1, 1), a1 + hstep, voffA);
;             PG8_WAIT_L(8); PG8_BAR; PG8_WAIT_L(0); PG8_MMA(0, 0, At, B0); PG8_BAR; PG8_SCHED;
;             PG8_LDB(B1, 0, 1); PG8_STAGE(PG8_SB(0, 0), b2, voffB);
;     ...
;             PG8_LDA(At, 1, 1); PG8_STAGE(PG8_SA(1, 0), a3, voffA);
;             PG8_BAR; PG8_WAIT_L(0); PG8_MMA(1, 0, At, B0); PG8_BAR; PG8_SCHED;
;             PG8_STAGE(PG8_SB(1, 1), b3 + hstep, voffB);
;             PG8_WAIT_V(6); PG8_BAR; PG8_MMA(1, 1, At, B1); PG8_BAR;
	s_waitcnt lgkmcnt(7)
	v_mfma_f32_16x16x32_bf16 v[62:65], v[130:133], v[176:179], v[62:65]
	v_mfma_f32_16x16x32_bf16 v[58:61], v[138:141], v[176:179], v[58:61]
	s_waitcnt lgkmcnt(5)
	v_mfma_f32_16x16x32_bf16 v[50:53], v[130:133], v[184:187], v[50:53]
	v_mfma_f32_16x16x32_bf16 v[44:47], v[138:141], v[184:187], v[44:47]
	s_waitcnt lgkmcnt(3)
	v_mfma_f32_16x16x32_bf16 v[32:35], v[130:133], v[192:195], v[32:35]
	v_mfma_f32_16x16x32_bf16 v[28:31], v[138:141], v[192:195], v[28:31]
	s_waitcnt lgkmcnt(1)
	v_mfma_f32_16x16x32_bf16 v[16:19], v[130:133], v[200:203], v[16:19]
	v_mfma_f32_16x16x32_bf16 v[12:15], v[138:141], v[200:203], v[12:15]
	v_mfma_f32_16x16x32_bf16 v[62:65], v[134:137], v[180:183], v[62:65]
	v_mfma_f32_16x16x32_bf16 v[58:61], v[142:145], v[180:183], v[58:61]
	v_mfma_f32_16x16x32_bf16 v[50:53], v[134:137], v[188:191], v[50:53]
	v_mfma_f32_16x16x32_bf16 v[44:47], v[142:145], v[188:191], v[44:47]
	v_mfma_f32_16x16x32_bf16 v[32:35], v[134:137], v[196:199], v[32:35]
	v_mfma_f32_16x16x32_bf16 v[28:31], v[142:145], v[196:199], v[28:31]
	s_waitcnt lgkmcnt(0)
	v_mfma_f32_16x16x32_bf16 v[16:19], v[134:137], v[204:207], v[16:19]
	v_mfma_f32_16x16x32_bf16 v[12:15], v[142:145], v[204:207], v[12:15]
	s_barrier
	s_add_i32 s20, s20, s35
	v_lshl_add_u64 v[130:131], v[240:241], 0, s[0:1]
	s_mov_b32 m0, s20
	s_nop 0
	global_load_lds_dwordx4 v[130:131], off
	v_lshl_add_u64 v[130:131], v[242:243], 0, s[0:1]
	s_add_i32 m0, s20, 0x2000
	s_nop 0
	global_load_lds_dwordx4 v[130:131], off
	s_waitcnt vmcnt(6)
	s_barrier
	v_mfma_f32_16x16x32_bf16 v[54:57], v[208:211], v[176:179], v[54:57]
	v_mfma_f32_16x16x32_bf16 v[40:43], v[216:219], v[176:179], v[40:43]
	v_mfma_f32_16x16x32_bf16 v[36:39], v[208:211], v[184:187], v[36:39]
	v_mfma_f32_16x16x32_bf16 v[24:27], v[216:219], v[184:187], v[24:27]
	v_mfma_f32_16x16x32_bf16 v[20:23], v[208:211], v[192:195], v[20:23]
	v_mfma_f32_16x16x32_bf16 v[8:11], v[216:219], v[192:195], v[8:11]
	v_mfma_f32_16x16x32_bf16 v[4:7], v[208:211], v[200:203], v[4:7]
	v_mfma_f32_16x16x32_bf16 v[0:3], v[216:219], v[200:203], v[0:3]
	v_mfma_f32_16x16x32_bf16 v[54:57], v[212:215], v[180:183], v[54:57]
	v_mfma_f32_16x16x32_bf16 v[40:43], v[234:237], v[180:183], v[40:43]
	v_mfma_f32_16x16x32_bf16 v[36:39], v[212:215], v[188:191], v[36:39]
	v_mfma_f32_16x16x32_bf16 v[24:27], v[234:237], v[188:191], v[24:27]
	v_mfma_f32_16x16x32_bf16 v[20:23], v[212:215], v[196:199], v[20:23]
	v_mfma_f32_16x16x32_bf16 v[8:11], v[234:237], v[196:199], v[8:11]
	v_mfma_f32_16x16x32_bf16 v[4:7], v[212:215], v[204:207], v[4:7]
	v_mfma_f32_16x16x32_bf16 v[0:3], v[234:237], v[204:207], v[0:3]
	s_add_u32 s16, s16, 0x100
	s_addc_u32 s17, s17, 0
	s_add_u32 s24, s24, 0x100
	s_addc_u32 s25, s25, 0
	s_cmp_ge_u32 s42, s54
	s_mov_b32 s20, s42
	s_barrier
	s_cbranch_scc1 .Lkpeel_exit_268
.LBB0_268:
	s_add_i32 s42, s20, 2
	s_add_u32 s22, s16, 0x80
	s_addc_u32 s21, s17, 0
	s_add_i32 s43, 0, 0x10000
	v_add_u32_e32 v142, s43, v170
	ds_read_b128 v[130:133], v142
	ds_read_b128 v[134:137], v142 offset:1024
	ds_read_b128 v[138:141], v142 offset:2048
	ds_read_b128 v[142:145], v142 offset:3072
	s_cmp_eq_u32 s66, s20
	s_cselect_b32 s20, s2, s22
	s_cselect_b32 s21, s3, s21
	s_cselect_b32 s23, s13, s25
	s_cselect_b32 s22, s12, s24
	v_lshl_add_u64 v[168:169], s[16:17], 0, v[164:165]
	s_add_i32 m0, s36, 0xc000
	ds_read_b128 v[176:179], v172
	ds_read_b128 v[180:183], v172 offset:1024
	ds_read_b128 v[184:187], v172 offset:2048
	ds_read_b128 v[188:191], v172 offset:3072
	ds_read_b128 v[192:195], v172 offset:4096
	ds_read_b128 v[196:199], v172 offset:5120
	ds_read_b128 v[200:203], v172 offset:6144
	ds_read_b128 v[204:207], v172 offset:7168
	global_load_lds_dwordx4 v[168:169], off
	v_lshl_add_u64 v[168:169], s[16:17], 0, v[166:167]
	s_add_i32 m0, s36, 0xe000
	s_nop 0
	global_load_lds_dwordx4 v[168:169], off
	s_waitcnt lgkmcnt(8)
	s_barrier
	s_waitcnt lgkmcnt(7)
	v_mfma_f32_16x16x32_bf16 v[126:129], v[130:133], v[176:179], v[126:129]
	v_mfma_f32_16x16x32_bf16 v[122:125], v[138:141], v[176:179], v[122:125]
	s_waitcnt lgkmcnt(5)
	v_mfma_f32_16x16x32_bf16 v[114:117], v[130:133], v[184:187], v[114:117]
	v_mfma_f32_16x16x32_bf16 v[110:113], v[138:141], v[184:187], v[110:113]
	s_waitcnt lgkmcnt(3)
	v_mfma_f32_16x16x32_bf16 v[98:101], v[130:133], v[192:195], v[98:101]
	v_mfma_f32_16x16x32_bf16 v[94:97], v[138:141], v[192:195], v[94:97]
	s_waitcnt lgkmcnt(1)
	v_mfma_f32_16x16x32_bf16 v[82:85], v[130:133], v[200:203], v[82:85]
	v_mfma_f32_16x16x32_bf16 v[78:81], v[138:141], v[200:203], v[78:81]
	v_mfma_f32_16x16x32_bf16 v[126:129], v[134:137], v[180:183], v[126:129]
	v_mfma_f32_16x16x32_bf16 v[122:125], v[142:145], v[180:183], v[122:125]
	v_mfma_f32_16x16x32_bf16 v[114:117], v[134:137], v[188:191], v[114:117]
	v_mfma_f32_16x16x32_bf16 v[110:113], v[142:145], v[188:191], v[110:113]
	v_mfma_f32_16x16x32_bf16 v[98:101], v[134:137], v[196:199], v[98:101]
	v_mfma_f32_16x16x32_bf16 v[94:97], v[142:145], v[196:199], v[94:97]
	s_waitcnt lgkmcnt(0)
	v_mfma_f32_16x16x32_bf16 v[82:85], v[134:137], v[204:207], v[82:85]
	v_mfma_f32_16x16x32_bf16 v[78:81], v[142:145], v[204:207], v[78:81]
	s_barrier
	s_add_i32 s44, 0, 0x14000
	v_add_u32_e32 v168, s44, v170
	s_add_i32 s43, s43, s35
	ds_read_b128 v[208:211], v168
	ds_read_b128 v[212:215], v168 offset:1024
	ds_read_b128 v[216:219], v168 offset:2048
	ds_read_b128 v[234:237], v168 offset:3072
	v_lshl_add_u64 v[168:169], s[22:23], 0, v[48:49]
	s_mov_b32 m0, s43
	v_lshl_add_u64 v[224:225], s[22:23], 0, v[146:147]
	global_load_lds_dwordx4 v[168:169], off
	s_add_i32 m0, s43, 0x2000
	s_nop 0
	global_load_lds_dwordx4 v[224:225], off
	s_barrier
; #define PG8_STAGE(bufoff, gbase, voff) do { _Pragma("unroll") for (int _i = 0; _i < 2; ++_i) \
;         __builtin_amdgcn_global_load_lds((const unsigned*)((const char*)(gbase) + (voff)[_i]), (PG8_LAS unsigned*)(lds + (bufoff) + ldsw + _i * 8192), 16, 0, 0); } while (0)
; #define PG8_LDA(dst, b, h) do { _Pragma("unroll") for (int m = 0; m < 4; ++m) _Pragma("unroll") for (int k = 0; k < 2; ++k) dst[m][k] = *(const PG8_LAS bf16x8*)(lds + PG8_SA(b, h) + aoff + m * 2048 + k * 1024); } while (0)
; #define PG8_LDB(dst, b, h) do { _Pragma("unroll") for (int n = 0; n < 2; ++n) _Pragma("unroll") for (int k = 0; k < 2; ++k) dst[n][k] = *(const PG8_LAS bf16x8*)(lds + PG8_SB(b, h) + boff + n * 2048 + k * 1024); } while (0)
; #define PG8_MMA(ai, bj, At, Bt) do { __builtin_amdgcn_s_setprio(1); _Pragma("unroll") for (int m = 0; m < 4; ++m) _Pragma("unroll") for (int n = 0; n < 2; ++n) _Pragma("unroll") for (int k = 0; k < 2; ++k) \
;         acc[ai][bj][m][n] = __builtin_amdgcn_mfma_f32_16x16x32_bf16(Bt[n][k], At[m][k], acc[ai][bj][m][n], 0, 0, 0); __builtin_amdgcn_s_setprio(0); } while (0)
; #define PG8_WAIT_V(n) asm volatile("s_waitcnt vmcnt(" #n ")" ::: "memory")
; #define PG8_WAIT_L(n) asm volatile("s_waitcnt lgkmcnt(" #n ")" ::: "memory")
; #define PG8_BAR __builtin_amdgcn_s_barrier()
; #define PG8_SCHED __builtin_amdgcn_sched_barrier(0)
; template <class Epi, class Sched>
; __device__ __forceinline__ void gemm_phase(PG8_LAS unsigned char* lds, const Gemm g, const Sched& S, const Epi& E) {
;     ...
;             PG8_LDB(B1, 0, 1); PG8_STAGE(PG8_SB(0, 0), b2, voffB);
;             PG8_BAR; PG8_WAIT_L(0); PG8_MMA(0, 1, At, B1); PG8_BAR;
;             PG8_LDA(At, 0, 1); PG8_STAGE(PG8_SA(0, 0), a2, voffA);
;             PG8_BAR; PG8_WAIT_L(0); PG8_MMA(1, 0, At, B0); PG8_BAR; PG8_SCHED;
;             PG8_STAGE(PG8_SB(0, 1), b2 + hstep, voffB);
;             PG8_WAIT_V(6); PG8_BAR; PG8_MMA(1, 1, At, B1); PG8_BAR;
;             PG8_LDB(B0, 1, 0); PG8_SCHED; PG8_LDA(At, 1, 0); PG8_STAGE(PG8_SA(0, 1), a2 + hstep, voffA);
	s_waitcnt lgkmcnt(3)
	v_mfma_f32_16x16x32_bf16 v[118:121], v[208:211], v[176:179], v[118:121]
	s_waitcnt lgkmcnt(1)
	v_mfma_f32_16x16x32_bf16 v[106:109], v[216:219], v[176:179], v[106:109]
	v_mfma_f32_16x16x32_bf16 v[102:105], v[208:211], v[184:187], v[102:105]
	v_mfma_f32_16x16x32_bf16 v[90:93], v[216:219], v[184:187], v[90:93]
	v_mfma_f32_16x16x32_bf16 v[86:89], v[208:211], v[192:195], v[86:89]
	v_mfma_f32_16x16x32_bf16 v[74:77], v[216:219], v[192:195], v[74:77]
	v_mfma_f32_16x16x32_bf16 v[70:73], v[208:211], v[200:203], v[70:73]
	v_mfma_f32_16x16x32_bf16 v[66:69], v[216:219], v[200:203], v[66:69]
	v_mfma_f32_16x16x32_bf16 v[118:121], v[212:215], v[180:183], v[118:121]
	s_waitcnt lgkmcnt(0)
	v_mfma_f32_16x16x32_bf16 v[106:109], v[234:237], v[180:183], v[106:109]
	v_mfma_f32_16x16x32_bf16 v[102:105], v[212:215], v[188:191], v[102:105]
	v_mfma_f32_16x16x32_bf16 v[90:93], v[234:237], v[188:191], v[90:93]
	v_mfma_f32_16x16x32_bf16 v[86:89], v[212:215], v[196:199], v[86:89]
	v_mfma_f32_16x16x32_bf16 v[74:77], v[234:237], v[196:199], v[74:77]
	v_mfma_f32_16x16x32_bf16 v[70:73], v[212:215], v[204:207], v[70:73]
	v_mfma_f32_16x16x32_bf16 v[66:69], v[234:237], v[204:207], v[66:69]
	s_mov_b32 m0, s36
	v_lshl_add_u64 v[228:229], s[20:21], 0, v[48:49]
	s_barrier
	ds_read_b128 v[176:179], v172 offset:16384
	ds_read_b128 v[180:183], v172 offset:17408
	ds_read_b128 v[184:187], v172 offset:18432
	ds_read_b128 v[188:191], v172 offset:19456
	ds_read_b128 v[192:195], v172 offset:20480
	ds_read_b128 v[196:199], v172 offset:21504
	ds_read_b128 v[200:203], v172 offset:22528
	ds_read_b128 v[204:207], v172 offset:23552
	global_load_lds_dwordx4 v[228:229], off
	v_lshl_add_u64 v[238:239], s[20:21], 0, v[146:147]
	s_mov_b32 m0, s37
	s_nop 0
	global_load_lds_dwordx4 v[238:239], off
	s_barrier
	s_waitcnt lgkmcnt(7)
	v_mfma_f32_16x16x32_bf16 v[62:65], v[130:133], v[176:179], v[62:65]
	v_mfma_f32_16x16x32_bf16 v[58:61], v[138:141], v[176:179], v[58:61]
	s_waitcnt lgkmcnt(5)
	v_mfma_f32_16x16x32_bf16 v[50:53], v[130:133], v[184:187], v[50:53]
	v_mfma_f32_16x16x32_bf16 v[44:47], v[138:141], v[184:187], v[44:47]
	s_waitcnt lgkmcnt(3)
	v_mfma_f32_16x16x32_bf16 v[32:35], v[130:133], v[192:195], v[32:35]
	v_mfma_f32_16x16x32_bf16 v[28:31], v[138:141], v[192:195], v[28:31]
	s_waitcnt lgkmcnt(1)
	v_mfma_f32_16x16x32_bf16 v[16:19], v[130:133], v[200:203], v[16:19]
	v_mfma_f32_16x16x32_bf16 v[12:15], v[138:141], v[200:203], v[12:15]
	v_mfma_f32_16x16x32_bf16 v[62:65], v[134:137], v[180:183], v[62:65]
	v_mfma_f32_16x16x32_bf16 v[58:61], v[142:145], v[180:183], v[58:61]
	v_mfma_f32_16x16x32_bf16 v[50:53], v[134:137], v[188:191], v[50:53]
	v_mfma_f32_16x16x32_bf16 v[44:47], v[142:145], v[188:191], v[44:47]
	v_mfma_f32_16x16x32_bf16 v[32:35], v[134:137], v[196:199], v[32:35]
	v_mfma_f32_16x16x32_bf16 v[28:31], v[142:145], v[196:199], v[28:31]
	s_waitcnt lgkmcnt(0)
	v_mfma_f32_16x16x32_bf16 v[16:19], v[134:137], v[204:207], v[16:19]
	v_mfma_f32_16x16x32_bf16 v[12:15], v[142:145], v[204:207], v[12:15]
	s_barrier
	s_add_u32 s22, s22, s10
	s_addc_u32 s23, s23, 0
	s_add_i32 s43, s44, s35
	v_lshl_add_u64 v[240:241], s[22:23], 0, v[48:49]
	s_mov_b32 m0, s43
	v_lshl_add_u64 v[242:243], s[22:23], 0, v[146:147]
	global_load_lds_dwordx4 v[240:241], off
	s_add_i32 m0, s43, 0x2000
	s_nop 0
	global_load_lds_dwordx4 v[242:243], off
	s_waitcnt vmcnt(6)
	s_barrier
	v_mfma_f32_16x16x32_bf16 v[54:57], v[208:211], v[176:179], v[54:57]
	v_mfma_f32_16x16x32_bf16 v[40:43], v[216:219], v[176:179], v[40:43]
	v_mfma_f32_16x16x32_bf16 v[36:39], v[208:211], v[184:187], v[36:39]
	v_mfma_f32_16x16x32_bf16 v[24:27], v[216:219], v[184:187], v[24:27]
	v_mfma_f32_16x16x32_bf16 v[20:23], v[208:211], v[192:195], v[20:23]
	v_mfma_f32_16x16x32_bf16 v[8:11], v[216:219], v[192:195], v[8:11]
	v_mfma_f32_16x16x32_bf16 v[4:7], v[208:211], v[200:203], v[4:7]
	v_mfma_f32_16x16x32_bf16 v[0:3], v[216:219], v[200:203], v[0:3]
	v_mfma_f32_16x16x32_bf16 v[54:57], v[212:215], v[180:183], v[54:57]
	v_mfma_f32_16x16x32_bf16 v[40:43], v[234:237], v[180:183], v[40:43]
	v_mfma_f32_16x16x32_bf16 v[36:39], v[212:215], v[188:191], v[36:39]
	v_mfma_f32_16x16x32_bf16 v[24:27], v[234:237], v[188:191], v[24:27]
	v_mfma_f32_16x16x32_bf16 v[20:23], v[212:215], v[196:199], v[20:23]
	v_mfma_f32_16x16x32_bf16 v[8:11], v[234:237], v[196:199], v[8:11]
	v_mfma_f32_16x16x32_bf16 v[4:7], v[212:215], v[204:207], v[4:7]
	v_mfma_f32_16x16x32_bf16 v[0:3], v[234:237], v[204:207], v[0:3]
	s_add_i32 s22, 0, 0x18000
	v_add_u32_e32 v142, s22, v170
	s_barrier
	ds_read_b128 v[130:133], v142
	ds_read_b128 v[134:137], v142 offset:1024
	ds_read_b128 v[138:141], v142 offset:2048
	ds_read_b128 v[142:145], v142 offset:3072
	s_add_u32 s20, s20, s10
	s_addc_u32 s21, s21, 0
	s_mov_b32 m0, s38
	v_lshl_add_u64 v[208:209], s[20:21], 0, v[48:49]
	ds_read_b128 v[176:179], v172 offset:32768
	ds_read_b128 v[180:183], v172 offset:33792
	ds_read_b128 v[184:187], v172 offset:34816
	ds_read_b128 v[188:191], v172 offset:35840
	ds_read_b128 v[192:195], v172 offset:36864
	ds_read_b128 v[196:199], v172 offset:37888
	ds_read_b128 v[200:203], v172 offset:38912
	ds_read_b128 v[204:207], v172 offset:39936
	global_load_lds_dwordx4 v[208:209], off
	v_lshl_add_u64 v[208:209], s[20:21], 0, v[146:147]
	s_mov_b32 m0, s39
	s_nop 0
	global_load_lds_dwordx4 v[208:209], off
	s_waitcnt lgkmcnt(8)
	s_barrier
; #define PG8_STAGE(bufoff, gbase, voff) do { _Pragma("unroll") for (int _i = 0; _i < 2; ++_i) \
;         __builtin_amdgcn_global_load_lds((const unsigned*)((const char*)(gbase) + (voff)[_i]), (PG8_LAS unsigned*)(lds + (bufoff) + ldsw + _i * 8192), 16, 0, 0); } while (0)
; #define PG8_LDA(dst, b, h) do { _Pragma("unroll") for (int m = 0; m < 4; ++m) _Pragma("unroll") for (int k = 0; k < 2; ++k) dst[m][k] = *(const PG8_LAS bf16x8*)(lds + PG8_SA(b, h) + aoff + m * 2048 + k * 1024); } while (0)
; #define PG8_LDB(dst, b, h) do { _Pragma("unroll") for (int n = 0; n < 2; ++n) _Pragma("unroll") for (int k = 0; k < 2; ++k) dst[n][k] = *(const PG8_LAS bf16x8*)(lds + PG8_SB(b, h) + boff + n * 2048 + k * 1024); } while (0)
; #define PG8_MMA(ai, bj, At, Bt) do { __builtin_amdgcn_s_setprio(1); _Pragma("unroll") for (int m = 0; m < 4; ++m) _Pragma("unroll") for (int n = 0; n < 2; ++n) _Pragma("unroll") for (int k = 0; k < 2; ++k) \
;         acc[ai][bj][m][n] = __builtin_amdgcn_mfma_f32_16x16x32_bf16(Bt[n][k], At[m][k], acc[ai][bj][m][n], 0, 0, 0); __builtin_amdgcn_s_setprio(0); } while (0)
; #define PG8_WAIT_V(n) asm volatile("s_waitcnt vmcnt(" #n ")" ::: "memory")
; #define PG8_WAIT_L(n) asm volatile("s_waitcnt lgkmcnt(" #n ")" ::: "memory")
; #define PG8_BAR __builtin_amdgcn_s_barrier()
; #define PG8_SCHED __builtin_amdgcn_sched_barrier(0)
; template <class Epi, class Sched>
; __device__ __forceinline__ void gemm_phase(PG8_LAS unsigned char* lds, const Gemm g, const Sched& S, const Epi& E) {
;     ...
;             PG8_LDB(B0, 1, 0); PG8_SCHED; PG8_LDA(At, 1, 0); PG8_STAGE(PG8_SA(0, 1), a2 + hstep, voffA);
;             PG8_WAIT_L(8); PG8_BAR; PG8_WAIT_L(0); PG8_MMA(0, 0, At, B0); PG8_BAR; PG8_SCHED;
;             PG8_LDB(B1, 1, 1); PG8_STAGE(PG8_SB(1, 0), b3, voffB);
;             PG8_BAR; PG8_WAIT_L(0); PG8_MMA(0, 1, At, B1); PG8_BAR;
;             PG8_LDA(At, 1, 1); PG8_STAGE(PG8_SA(1, 0), a3, voffA);
;             PG8_BAR; PG8_WAIT_L(0); PG8_MMA(1, 0, At, B0); PG8_BAR; PG8_SCHED;
;             PG8_STAGE(PG8_SB(1, 1), b3 + hstep, voffB);
;             PG8_WAIT_V(6); PG8_BAR; PG8_MMA(1, 1, At, B1); PG8_BAR;
	s_waitcnt lgkmcnt(7)
	v_mfma_f32_16x16x32_bf16 v[126:129], v[130:133], v[176:179], v[126:129]
	v_mfma_f32_16x16x32_bf16 v[122:125], v[138:141], v[176:179], v[122:125]
	s_waitcnt lgkmcnt(5)
	v_mfma_f32_16x16x32_bf16 v[114:117], v[130:133], v[184:187], v[114:117]
	v_mfma_f32_16x16x32_bf16 v[110:113], v[138:141], v[184:187], v[110:113]
	s_waitcnt lgkmcnt(3)
	v_mfma_f32_16x16x32_bf16 v[98:101], v[130:133], v[192:195], v[98:101]
	v_mfma_f32_16x16x32_bf16 v[94:97], v[138:141], v[192:195], v[94:97]
	s_waitcnt lgkmcnt(1)
	v_mfma_f32_16x16x32_bf16 v[82:85], v[130:133], v[200:203], v[82:85]
	v_mfma_f32_16x16x32_bf16 v[78:81], v[138:141], v[200:203], v[78:81]
	v_mfma_f32_16x16x32_bf16 v[126:129], v[134:137], v[180:183], v[126:129]
	v_mfma_f32_16x16x32_bf16 v[122:125], v[142:145], v[180:183], v[122:125]
	v_mfma_f32_16x16x32_bf16 v[114:117], v[134:137], v[188:191], v[114:117]
	v_mfma_f32_16x16x32_bf16 v[110:113], v[142:145], v[188:191], v[110:113]
	v_mfma_f32_16x16x32_bf16 v[98:101], v[134:137], v[196:199], v[98:101]
	v_mfma_f32_16x16x32_bf16 v[94:97], v[142:145], v[196:199], v[94:97]
	s_waitcnt lgkmcnt(0)
	v_mfma_f32_16x16x32_bf16 v[82:85], v[134:137], v[204:207], v[82:85]
	v_mfma_f32_16x16x32_bf16 v[78:81], v[142:145], v[204:207], v[78:81]
	s_barrier
	s_add_i32 s20, 0, 0x1c000
	s_add_i32 s21, s22, s35
	v_add_u32_e32 v173, s20, v170
	v_lshl_add_u64 v[168:169], v[168:169], 0, s[0:1]
	s_mov_b32 m0, s21
	ds_read_b128 v[208:211], v173
	ds_read_b128 v[212:215], v173 offset:1024
	ds_read_b128 v[216:219], v173 offset:2048
	ds_read_b128 v[234:237], v173 offset:3072
	global_load_lds_dwordx4 v[168:169], off
	v_lshl_add_u64 v[168:169], v[224:225], 0, s[0:1]
	s_add_i32 m0, s21, 0x2000
	s_nop 0
	global_load_lds_dwordx4 v[168:169], off
	s_barrier
	s_waitcnt lgkmcnt(3)
	v_mfma_f32_16x16x32_bf16 v[118:121], v[208:211], v[176:179], v[118:121]
	s_waitcnt lgkmcnt(1)
	v_mfma_f32_16x16x32_bf16 v[106:109], v[216:219], v[176:179], v[106:109]
	v_mfma_f32_16x16x32_bf16 v[102:105], v[208:211], v[184:187], v[102:105]
	v_mfma_f32_16x16x32_bf16 v[90:93], v[216:219], v[184:187], v[90:93]
	v_mfma_f32_16x16x32_bf16 v[86:89], v[208:211], v[192:195], v[86:89]
	v_mfma_f32_16x16x32_bf16 v[74:77], v[216:219], v[192:195], v[74:77]
	v_mfma_f32_16x16x32_bf16 v[70:73], v[208:211], v[200:203], v[70:73]
	v_mfma_f32_16x16x32_bf16 v[66:69], v[216:219], v[200:203], v[66:69]
	v_mfma_f32_16x16x32_bf16 v[118:121], v[212:215], v[180:183], v[118:121]
	s_waitcnt lgkmcnt(0)
	v_mfma_f32_16x16x32_bf16 v[106:109], v[234:237], v[180:183], v[106:109]
	v_mfma_f32_16x16x32_bf16 v[102:105], v[212:215], v[188:191], v[102:105]
	v_mfma_f32_16x16x32_bf16 v[90:93], v[234:237], v[188:191], v[90:93]
	v_mfma_f32_16x16x32_bf16 v[86:89], v[212:215], v[196:199], v[86:89]
	v_mfma_f32_16x16x32_bf16 v[74:77], v[234:237], v[196:199], v[74:77]
	v_mfma_f32_16x16x32_bf16 v[70:73], v[212:215], v[204:207], v[70:73]
	v_mfma_f32_16x16x32_bf16 v[66:69], v[234:237], v[204:207], v[66:69]
	s_mov_b32 m0, s64
	v_lshl_add_u64 v[168:169], v[228:229], 0, s[0:1]
	s_barrier
	ds_read_b128 v[176:179], v172 offset:49152
	ds_read_b128 v[180:183], v172 offset:50176
	ds_read_b128 v[184:187], v172 offset:51200
	ds_read_b128 v[188:191], v172 offset:52224
	ds_read_b128 v[192:195], v172 offset:53248
	ds_read_b128 v[196:199], v172 offset:54272
	ds_read_b128 v[200:203], v172 offset:55296
	ds_read_b128 v[204:207], v172 offset:56320
	global_load_lds_dwordx4 v[168:169], off
	v_lshl_add_u64 v[168:169], v[238:239], 0, s[0:1]
	s_mov_b32 m0, s65
	s_nop 0
	global_load_lds_dwordx4 v[168:169], off
	s_barrier
	s_waitcnt lgkmcnt(7)
	v_mfma_f32_16x16x32_bf16 v[62:65], v[130:133], v[176:179], v[62:65]
	v_mfma_f32_16x16x32_bf16 v[58:61], v[138:141], v[176:179], v[58:61]
	s_waitcnt lgkmcnt(5)
	v_mfma_f32_16x16x32_bf16 v[50:53], v[130:133], v[184:187], v[50:53]
	v_mfma_f32_16x16x32_bf16 v[44:47], v[138:141], v[184:187], v[44:47]
	s_waitcnt lgkmcnt(3)
	v_mfma_f32_16x16x32_bf16 v[32:35], v[130:133], v[192:195], v[32:35]
	v_mfma_f32_16x16x32_bf16 v[28:31], v[138:141], v[192:195], v[28:31]
	s_waitcnt lgkmcnt(1)
	v_mfma_f32_16x16x32_bf16 v[16:19], v[130:133], v[200:203], v[16:19]
	v_mfma_f32_16x16x32_bf16 v[12:15], v[138:141], v[200:203], v[12:15]
	v_mfma_f32_16x16x32_bf16 v[62:65], v[134:137], v[180:183], v[62:65]
	v_mfma_f32_16x16x32_bf16 v[58:61], v[142:145], v[180:183], v[58:61]
	v_mfma_f32_16x16x32_bf16 v[50:53], v[134:137], v[188:191], v[50:53]
	v_mfma_f32_16x16x32_bf16 v[44:47], v[142:145], v[188:191], v[44:47]
	v_mfma_f32_16x16x32_bf16 v[32:35], v[134:137], v[196:199], v[32:35]
	v_mfma_f32_16x16x32_bf16 v[28:31], v[142:145], v[196:199], v[28:31]
	s_waitcnt lgkmcnt(0)
	v_mfma_f32_16x16x32_bf16 v[16:19], v[134:137], v[204:207], v[16:19]
	v_mfma_f32_16x16x32_bf16 v[12:15], v[142:145], v[204:207], v[12:15]
	s_barrier
	s_add_i32 s20, s20, s35
	v_lshl_add_u64 v[130:131], v[240:241], 0, s[0:1]
	s_mov_b32 m0, s20
	s_nop 0
	global_load_lds_dwordx4 v[130:131], off
	v_lshl_add_u64 v[130:131], v[242:243], 0, s[0:1]
	s_add_i32 m0, s20, 0x2000
	s_nop 0
	global_load_lds_dwordx4 v[130:131], off
	s_waitcnt vmcnt(6)
	s_barrier
	v_mfma_f32_16x16x32_bf16 v[54:57], v[208:211], v[176:179], v[54:57]
	v_mfma_f32_16x16x32_bf16 v[40:43], v[216:219], v[176:179], v[40:43]
	v_mfma_f32_16x16x32_bf16 v[36:39], v[208:211], v[184:187], v[36:39]
	v_mfma_f32_16x16x32_bf16 v[24:27], v[216:219], v[184:187], v[24:27]
	v_mfma_f32_16x16x32_bf16 v[20:23], v[208:211], v[192:195], v[20:23]
	v_mfma_f32_16x16x32_bf16 v[8:11], v[216:219], v[192:195], v[8:11]
	v_mfma_f32_16x16x32_bf16 v[4:7], v[208:211], v[200:203], v[4:7]
	v_mfma_f32_16x16x32_bf16 v[0:3], v[216:219], v[200:203], v[0:3]
	v_mfma_f32_16x16x32_bf16 v[54:57], v[212:215], v[180:183], v[54:57]
	v_mfma_f32_16x16x32_bf16 v[40:43], v[234:237], v[180:183], v[40:43]
	v_mfma_f32_16x16x32_bf16 v[36:39], v[212:215], v[188:191], v[36:39]
	v_mfma_f32_16x16x32_bf16 v[24:27], v[234:237], v[188:191], v[24:27]
	v_mfma_f32_16x16x32_bf16 v[20:23], v[212:215], v[196:199], v[20:23]
	v_mfma_f32_16x16x32_bf16 v[8:11], v[234:237], v[196:199], v[8:11]
	v_mfma_f32_16x16x32_bf16 v[4:7], v[212:215], v[204:207], v[4:7]
	v_mfma_f32_16x16x32_bf16 v[0:3], v[234:237], v[204:207], v[0:3]
	s_add_u32 s16, s16, 0x100
	s_addc_u32 s17, s17, 0
	s_add_u32 s24, s24, 0x100
	s_addc_u32 s25, s25, 0
	s_cmp_ge_u32 s42, s54
	s_mov_b32 s20, s42
	s_barrier
	s_cbranch_scc0 .LBB0_268

; #define PG8_STAGE(bufoff, gbase, voff) do { _Pragma("unroll") for (int _i = 0; _i < 2; ++_i) \
;         __builtin_amdgcn_global_load_lds((const unsigned*)((const char*)(gbase) + (voff)[_i]), (PG8_LAS unsigned*)(lds + (bufoff) + ldsw + _i * 8192), 16, 0, 0); } while (0)
; #define PG8_LDA(dst, b, h) do { _Pragma("unroll") for (int m = 0; m < 4; ++m) _Pragma("unroll") for (int k = 0; k < 2; ++k) dst[m][k] = *(const PG8_LAS bf16x8*)(lds + PG8_SA(b, h) + aoff + m * 2048 + k * 1024); } while (0)
; #define PG8_LDB(dst, b, h) do { _Pragma("unroll") for (int n = 0; n < 2; ++n) _Pragma("unroll") for (int k = 0; k < 2; ++k) dst[n][k] = *(const PG8_LAS bf16x8*)(lds + PG8_SB(b, h) + boff + n * 2048 + k * 1024); } while (0)
; #define PG8_MMA(ai, bj, At, Bt) do { __builtin_amdgcn_s_setprio(1); _Pragma("unroll") for (int m = 0; m < 4; ++m) _Pragma("unroll") for (int n = 0; n < 2; ++n) _Pragma("unroll") for (int k = 0; k < 2; ++k) \
;         acc[ai][bj][m][n] = __builtin_amdgcn_mfma_f32_16x16x32_bf16(Bt[n][k], At[m][k], acc[ai][bj][m][n], 0, 0, 0); __builtin_amdgcn_s_setprio(0); } while (0)
; #define PG8_WAIT_L(n) asm volatile("s_waitcnt lgkmcnt(" #n ")" ::: "memory")
; #define PG8_BAR __builtin_amdgcn_s_barrier()
; #define PG8_SCHED __builtin_amdgcn_sched_barrier(0)
; template <class Epi, class Sched>
; __device__ __forceinline__ void gemm_phase(PG8_LAS unsigned char* lds, const Gemm g, const Sched& S, const Epi& E) {
;     ...
;             const char* a2 = last ? nA : cA + (size_t)(t + 2) * kstep; const char* b2 = last ? nB : cB + (size_t)(t + 2) * kstep;
;             const char* a3 = a2 + kstep; const char* b3 = b2 + kstep;
;             if (last && has_next) S.a_ready(nxt);
;             PG8_LDB(B0, 0, 0); PG8_SCHED; PG8_LDA(At, 0, 0); PG8_STAGE(PG8_SA(1, 1), a1 + hstep, voffA);
;             PG8_WAIT_L(8); PG8_BAR; PG8_WAIT_L(0); PG8_MMA(0, 0, At, B0); PG8_BAR; PG8_SCHED;
;             PG8_LDB(B1, 0, 1); PG8_STAGE(PG8_SB(0, 0), b2, voffB);
;             PG8_BAR; PG8_WAIT_L(0); PG8_MMA(0, 1, At, B1); PG8_BAR;
;             PG8_LDA(At, 0, 1); PG8_STAGE(PG8_SA(0, 0), a2, voffA);
;             PG8_BAR; PG8_WAIT_L(0); PG8_MMA(1, 0, At, B0); PG8_BAR; PG8_SCHED;
.LBB0_287:
	s_add_u32 s20, s20, 0x80
	s_addc_u32 s21, s21, 0
	s_add_u32 s3, s22, 0x100
	s_addc_u32 s40, s23, 0
	s_mov_b32 s22, 0
	s_add_i32 s41, s22, 2
	s_add_u32 s24, s20, 0x80
	s_addc_u32 s23, s21, 0
	s_add_i32 s63, 0, 0x10000
	v_add_u32_e32 v155, s63, v152
	ds_read_b128 v[156:159], v155
	ds_read_b128 v[160:163], v155 offset:1024
	ds_read_b128 v[164:167], v155 offset:2048
	ds_read_b128 v[168:171], v155 offset:3072
	s_cmp_eq_u32 s55, s22
	s_cselect_b32 s22, s12, s24
	s_cselect_b32 s23, s13, s23
	s_cselect_b32 s25, s17, s40
	s_cselect_b32 s24, s16, s3
	v_lshl_add_u64 v[172:173], s[20:21], 0, v[148:149]
	s_add_i32 m0, s43, 0xc000
	ds_read_b128 v[176:179], v154
	ds_read_b128 v[180:183], v154 offset:1024
	ds_read_b128 v[184:187], v154 offset:2048
	ds_read_b128 v[188:191], v154 offset:3072
	ds_read_b128 v[192:195], v154 offset:4096
	ds_read_b128 v[196:199], v154 offset:5120
	ds_read_b128 v[200:203], v154 offset:6144
	ds_read_b128 v[204:207], v154 offset:7168
	global_load_lds_dwordx4 v[172:173], off
	v_lshl_add_u64 v[172:173], s[20:21], 0, v[150:151]
	s_add_i32 m0, s43, 0xe000
	s_nop 0
	global_load_lds_dwordx4 v[172:173], off
	s_waitcnt lgkmcnt(8)
	s_barrier
	s_waitcnt lgkmcnt(7)
	v_mfma_f32_16x16x32_bf16 v[126:129], v[156:159], v[176:179], 0
	v_mfma_f32_16x16x32_bf16 v[122:125], v[164:167], v[176:179], 0
	s_waitcnt lgkmcnt(5)
	v_mfma_f32_16x16x32_bf16 v[118:121], v[156:159], v[184:187], 0
	v_mfma_f32_16x16x32_bf16 v[114:117], v[164:167], v[184:187], 0
	s_waitcnt lgkmcnt(3)
	v_mfma_f32_16x16x32_bf16 v[110:113], v[156:159], v[192:195], 0
	v_mfma_f32_16x16x32_bf16 v[106:109], v[164:167], v[192:195], 0
	s_waitcnt lgkmcnt(1)
	v_mfma_f32_16x16x32_bf16 v[98:101], v[156:159], v[200:203], 0
	v_mfma_f32_16x16x32_bf16 v[90:93], v[164:167], v[200:203], 0
	v_mfma_f32_16x16x32_bf16 v[126:129], v[160:163], v[180:183], v[126:129]
	v_mfma_f32_16x16x32_bf16 v[122:125], v[168:171], v[180:183], v[122:125]
	v_mfma_f32_16x16x32_bf16 v[118:121], v[160:163], v[188:191], v[118:121]
	v_mfma_f32_16x16x32_bf16 v[114:117], v[168:171], v[188:191], v[114:117]
	v_mfma_f32_16x16x32_bf16 v[110:113], v[160:163], v[196:199], v[110:113]
	v_mfma_f32_16x16x32_bf16 v[106:109], v[168:171], v[196:199], v[106:109]
	s_waitcnt lgkmcnt(0)
	v_mfma_f32_16x16x32_bf16 v[98:101], v[160:163], v[204:207], v[98:101]
	v_mfma_f32_16x16x32_bf16 v[90:93], v[168:171], v[204:207], v[90:93]
	s_barrier
	s_add_i32 s64, 0, 0x14000
	s_add_i32 s63, s63, s37
	v_add_u32_e32 v155, s64, v152
	v_lshl_add_u64 v[172:173], s[24:25], 0, v[48:49]
	s_mov_b32 m0, s63
	ds_read_b128 v[208:211], v155
	ds_read_b128 v[212:215], v155 offset:1024
	ds_read_b128 v[216:219], v155 offset:2048
	ds_read_b128 v[234:237], v155 offset:3072
	global_load_lds_dwordx4 v[172:173], off
	v_lshl_add_u64 v[224:225], s[24:25], 0, v[130:131]
	s_add_i32 m0, s63, 0x2000
	s_nop 0
	global_load_lds_dwordx4 v[224:225], off
	s_barrier
	s_waitcnt lgkmcnt(3)
	v_mfma_f32_16x16x32_bf16 v[102:105], v[208:211], v[176:179], 0
	s_waitcnt lgkmcnt(1)
	v_mfma_f32_16x16x32_bf16 v[94:97], v[216:219], v[176:179], 0
	v_mfma_f32_16x16x32_bf16 v[86:89], v[208:211], v[184:187], 0
	v_mfma_f32_16x16x32_bf16 v[82:85], v[216:219], v[184:187], 0
	v_mfma_f32_16x16x32_bf16 v[78:81], v[208:211], v[192:195], 0
	v_mfma_f32_16x16x32_bf16 v[74:77], v[216:219], v[192:195], 0
	v_mfma_f32_16x16x32_bf16 v[70:73], v[208:211], v[200:203], 0
	v_mfma_f32_16x16x32_bf16 v[66:69], v[216:219], v[200:203], 0
	v_mfma_f32_16x16x32_bf16 v[102:105], v[212:215], v[180:183], v[102:105]
	s_waitcnt lgkmcnt(0)
	v_mfma_f32_16x16x32_bf16 v[94:97], v[234:237], v[180:183], v[94:97]
	v_mfma_f32_16x16x32_bf16 v[86:89], v[212:215], v[188:191], v[86:89]
	v_mfma_f32_16x16x32_bf16 v[82:85], v[234:237], v[188:191], v[82:85]
	v_mfma_f32_16x16x32_bf16 v[78:81], v[212:215], v[196:199], v[78:81]
	v_mfma_f32_16x16x32_bf16 v[74:77], v[234:237], v[196:199], v[74:77]
	v_mfma_f32_16x16x32_bf16 v[70:73], v[212:215], v[204:207], v[70:73]
	v_mfma_f32_16x16x32_bf16 v[66:69], v[234:237], v[204:207], v[66:69]
	s_mov_b32 m0, s43
	v_lshl_add_u64 v[228:229], s[22:23], 0, v[48:49]
	s_barrier
	ds_read_b128 v[176:179], v154 offset:16384
	ds_read_b128 v[180:183], v154 offset:17408
	ds_read_b128 v[184:187], v154 offset:18432
	ds_read_b128 v[188:191], v154 offset:19456
	ds_read_b128 v[192:195], v154 offset:20480
	ds_read_b128 v[196:199], v154 offset:21504
	ds_read_b128 v[200:203], v154 offset:22528
	ds_read_b128 v[204:207], v154 offset:23552
	global_load_lds_dwordx4 v[228:229], off
	v_lshl_add_u64 v[238:239], s[22:23], 0, v[130:131]
	s_mov_b32 m0, s44
	s_nop 0
	global_load_lds_dwordx4 v[238:239], off
	s_barrier
	s_waitcnt lgkmcnt(7)
	v_mfma_f32_16x16x32_bf16 v[62:65], v[156:159], v[176:179], 0
	v_mfma_f32_16x16x32_bf16 v[58:61], v[164:167], v[176:179], 0
	s_waitcnt lgkmcnt(5)
	v_mfma_f32_16x16x32_bf16 v[54:57], v[156:159], v[184:187], 0
	v_mfma_f32_16x16x32_bf16 v[50:53], v[164:167], v[184:187], 0
	s_waitcnt lgkmcnt(3)
	v_mfma_f32_16x16x32_bf16 v[44:47], v[156:159], v[192:195], 0
	v_mfma_f32_16x16x32_bf16 v[40:43], v[164:167], v[192:195], 0
	s_waitcnt lgkmcnt(1)
	v_mfma_f32_16x16x32_bf16 v[32:35], v[156:159], v[200:203], 0
	v_mfma_f32_16x16x32_bf16 v[24:27], v[164:167], v[200:203], 0
	v_mfma_f32_16x16x32_bf16 v[62:65], v[160:163], v[180:183], v[62:65]
	v_mfma_f32_16x16x32_bf16 v[58:61], v[168:171], v[180:183], v[58:61]
	v_mfma_f32_16x16x32_bf16 v[54:57], v[160:163], v[188:191], v[54:57]
	v_mfma_f32_16x16x32_bf16 v[50:53], v[168:171], v[188:191], v[50:53]
	v_mfma_f32_16x16x32_bf16 v[44:47], v[160:163], v[196:199], v[44:47]
	v_mfma_f32_16x16x32_bf16 v[40:43], v[168:171], v[196:199], v[40:43]
	s_waitcnt lgkmcnt(0)
	v_mfma_f32_16x16x32_bf16 v[32:35], v[160:163], v[204:207], v[32:35]
	v_mfma_f32_16x16x32_bf16 v[24:27], v[168:171], v[204:207], v[24:27]
	s_barrier
; #define PG8_STAGE(bufoff, gbase, voff) do { _Pragma("unroll") for (int _i = 0; _i < 2; ++_i) \
;         __builtin_amdgcn_global_load_lds((const unsigned*)((const char*)(gbase) + (voff)[_i]), (PG8_LAS unsigned*)(lds + (bufoff) + ldsw + _i * 8192), 16, 0, 0); } while (0)
; #define PG8_LDA(dst, b, h) do { _Pragma("unroll") for (int m = 0; m < 4; ++m) _Pragma("unroll") for (int k = 0; k < 2; ++k) dst[m][k] = *(const PG8_LAS bf16x8*)(lds + PG8_SA(b, h) + aoff + m * 2048 + k * 1024); } while (0)
; #define PG8_LDB(dst, b, h) do { _Pragma("unroll") for (int n = 0; n < 2; ++n) _Pragma("unroll") for (int k = 0; k < 2; ++k) dst[n][k] = *(const PG8_LAS bf16x8*)(lds + PG8_SB(b, h) + boff + n * 2048 + k * 1024); } while (0)
; #define PG8_MMA(ai, bj, At, Bt) do { __builtin_amdgcn_s_setprio(1); _Pragma("unroll") for (int m = 0; m < 4; ++m) _Pragma("unroll") for (int n = 0; n < 2; ++n) _Pragma("unroll") for (int k = 0; k < 2; ++k) \
;         acc[ai][bj][m][n] = __builtin_amdgcn_mfma_f32_16x16x32_bf16(Bt[n][k], At[m][k], acc[ai][bj][m][n], 0, 0, 0); __builtin_amdgcn_s_setprio(0); } while (0)
; #define PG8_WAIT_V(n) asm volatile("s_waitcnt vmcnt(" #n ")" ::: "memory")
; #define PG8_WAIT_L(n) asm volatile("s_waitcnt lgkmcnt(" #n ")" ::: "memory")
; #define PG8_BAR __builtin_amdgcn_s_barrier()
; #define PG8_SCHED __builtin_amdgcn_sched_barrier(0)
; template <class Epi, class Sched>
; __device__ __forceinline__ void gemm_phase(PG8_LAS unsigned char* lds, const Gemm g, const Sched& S, const Epi& E) {
;     ...
;             PG8_STAGE(PG8_SB(0, 1), b2 + hstep, voffB);
;             PG8_WAIT_V(6); PG8_BAR; PG8_MMA(1, 1, At, B1); PG8_BAR;
;             PG8_LDB(B0, 1, 0); PG8_SCHED; PG8_LDA(At, 1, 0); PG8_STAGE(PG8_SA(0, 1), a2 + hstep, voffA);
;             PG8_WAIT_L(8); PG8_BAR; PG8_WAIT_L(0); PG8_MMA(0, 0, At, B0); PG8_BAR; PG8_SCHED;
;             PG8_LDB(B1, 1, 1); PG8_STAGE(PG8_SB(1, 0), b3, voffB);
;             PG8_BAR; PG8_WAIT_L(0); PG8_MMA(0, 1, At, B1); PG8_BAR;
;             PG8_LDA(At, 1, 1); PG8_STAGE(PG8_SA(1, 0), a3, voffA);
	s_add_u32 s24, s24, s10
	s_addc_u32 s25, s25, 0
	s_add_i32 s63, s64, s37
	v_lshl_add_u64 v[240:241], s[24:25], 0, v[48:49]
	s_mov_b32 m0, s63
	v_lshl_add_u64 v[242:243], s[24:25], 0, v[130:131]
	global_load_lds_dwordx4 v[240:241], off
	s_add_i32 m0, s63, 0x2000
	s_nop 0
	global_load_lds_dwordx4 v[242:243], off
	s_waitcnt vmcnt(6)
	s_barrier
	v_mfma_f32_16x16x32_bf16 v[36:39], v[208:211], v[176:179], 0
	v_mfma_f32_16x16x32_bf16 v[28:31], v[216:219], v[176:179], 0
	v_mfma_f32_16x16x32_bf16 v[20:23], v[208:211], v[184:187], 0
	v_mfma_f32_16x16x32_bf16 v[16:19], v[216:219], v[184:187], 0
	v_mfma_f32_16x16x32_bf16 v[12:15], v[208:211], v[192:195], 0
	v_mfma_f32_16x16x32_bf16 v[8:11], v[216:219], v[192:195], 0
	v_mfma_f32_16x16x32_bf16 v[4:7], v[208:211], v[200:203], 0
	v_mfma_f32_16x16x32_bf16 v[0:3], v[216:219], v[200:203], 0
	v_mfma_f32_16x16x32_bf16 v[36:39], v[212:215], v[180:183], v[36:39]
	v_mfma_f32_16x16x32_bf16 v[28:31], v[234:237], v[180:183], v[28:31]
	v_mfma_f32_16x16x32_bf16 v[20:23], v[212:215], v[188:191], v[20:23]
	v_mfma_f32_16x16x32_bf16 v[16:19], v[234:237], v[188:191], v[16:19]
	v_mfma_f32_16x16x32_bf16 v[12:15], v[212:215], v[196:199], v[12:15]
	v_mfma_f32_16x16x32_bf16 v[8:11], v[234:237], v[196:199], v[8:11]
	v_mfma_f32_16x16x32_bf16 v[4:7], v[212:215], v[204:207], v[4:7]
	v_mfma_f32_16x16x32_bf16 v[0:3], v[234:237], v[204:207], v[0:3]
	s_add_i32 s24, 0, 0x18000
	v_add_u32_e32 v155, s24, v152
	s_barrier
	ds_read_b128 v[156:159], v155
	ds_read_b128 v[160:163], v155 offset:1024
	ds_read_b128 v[164:167], v155 offset:2048
	ds_read_b128 v[168:171], v155 offset:3072
	s_add_u32 s22, s22, s10
	s_addc_u32 s23, s23, 0
	s_mov_b32 m0, s46
	v_lshl_add_u64 v[208:209], s[22:23], 0, v[48:49]
	ds_read_b128 v[176:179], v154 offset:32768
	ds_read_b128 v[180:183], v154 offset:33792
	ds_read_b128 v[184:187], v154 offset:34816
	ds_read_b128 v[188:191], v154 offset:35840
	ds_read_b128 v[192:195], v154 offset:36864
	ds_read_b128 v[196:199], v154 offset:37888
	ds_read_b128 v[200:203], v154 offset:38912
	ds_read_b128 v[204:207], v154 offset:39936
	global_load_lds_dwordx4 v[208:209], off
	v_lshl_add_u64 v[208:209], s[22:23], 0, v[130:131]
	s_mov_b32 m0, s47
	s_nop 0
	global_load_lds_dwordx4 v[208:209], off
	s_waitcnt lgkmcnt(8)
	s_barrier
	s_waitcnt lgkmcnt(7)
	v_mfma_f32_16x16x32_bf16 v[126:129], v[156:159], v[176:179], v[126:129]
	v_mfma_f32_16x16x32_bf16 v[122:125], v[164:167], v[176:179], v[122:125]
	s_waitcnt lgkmcnt(5)
	v_mfma_f32_16x16x32_bf16 v[118:121], v[156:159], v[184:187], v[118:121]
	v_mfma_f32_16x16x32_bf16 v[114:117], v[164:167], v[184:187], v[114:117]
	s_waitcnt lgkmcnt(3)
	v_mfma_f32_16x16x32_bf16 v[110:113], v[156:159], v[192:195], v[110:113]
	v_mfma_f32_16x16x32_bf16 v[106:109], v[164:167], v[192:195], v[106:109]
	s_waitcnt lgkmcnt(1)
	v_mfma_f32_16x16x32_bf16 v[98:101], v[156:159], v[200:203], v[98:101]
	v_mfma_f32_16x16x32_bf16 v[90:93], v[164:167], v[200:203], v[90:93]
	v_mfma_f32_16x16x32_bf16 v[126:129], v[160:163], v[180:183], v[126:129]
	v_mfma_f32_16x16x32_bf16 v[122:125], v[168:171], v[180:183], v[122:125]
	v_mfma_f32_16x16x32_bf16 v[118:121], v[160:163], v[188:191], v[118:121]
	v_mfma_f32_16x16x32_bf16 v[114:117], v[168:171], v[188:191], v[114:117]
	v_mfma_f32_16x16x32_bf16 v[110:113], v[160:163], v[196:199], v[110:113]
	v_mfma_f32_16x16x32_bf16 v[106:109], v[168:171], v[196:199], v[106:109]
	s_waitcnt lgkmcnt(0)
	v_mfma_f32_16x16x32_bf16 v[98:101], v[160:163], v[204:207], v[98:101]
	v_mfma_f32_16x16x32_bf16 v[90:93], v[168:171], v[204:207], v[90:93]
	s_barrier
	s_add_i32 s22, 0, 0x1c000
	s_add_i32 s23, s24, s37
	v_add_u32_e32 v155, s22, v152
	v_lshl_add_u64 v[172:173], v[172:173], 0, s[0:1]
	s_mov_b32 m0, s23
	ds_read_b128 v[208:211], v155
	ds_read_b128 v[212:215], v155 offset:1024
	ds_read_b128 v[216:219], v155 offset:2048
	ds_read_b128 v[234:237], v155 offset:3072
	global_load_lds_dwordx4 v[172:173], off
	v_lshl_add_u64 v[172:173], v[224:225], 0, s[0:1]
	s_add_i32 m0, s23, 0x2000
	s_nop 0
	global_load_lds_dwordx4 v[172:173], off
	s_barrier
	s_waitcnt lgkmcnt(3)
	v_mfma_f32_16x16x32_bf16 v[102:105], v[208:211], v[176:179], v[102:105]
	s_waitcnt lgkmcnt(1)
	v_mfma_f32_16x16x32_bf16 v[94:97], v[216:219], v[176:179], v[94:97]
	v_mfma_f32_16x16x32_bf16 v[86:89], v[208:211], v[184:187], v[86:89]
	v_mfma_f32_16x16x32_bf16 v[82:85], v[216:219], v[184:187], v[82:85]
	v_mfma_f32_16x16x32_bf16 v[78:81], v[208:211], v[192:195], v[78:81]
	v_mfma_f32_16x16x32_bf16 v[74:77], v[216:219], v[192:195], v[74:77]
	v_mfma_f32_16x16x32_bf16 v[70:73], v[208:211], v[200:203], v[70:73]
	v_mfma_f32_16x16x32_bf16 v[66:69], v[216:219], v[200:203], v[66:69]
	v_mfma_f32_16x16x32_bf16 v[102:105], v[212:215], v[180:183], v[102:105]
	s_waitcnt lgkmcnt(0)
	v_mfma_f32_16x16x32_bf16 v[94:97], v[234:237], v[180:183], v[94:97]
	v_mfma_f32_16x16x32_bf16 v[86:89], v[212:215], v[188:191], v[86:89]
	v_mfma_f32_16x16x32_bf16 v[82:85], v[234:237], v[188:191], v[82:85]
	v_mfma_f32_16x16x32_bf16 v[78:81], v[212:215], v[196:199], v[78:81]
	v_mfma_f32_16x16x32_bf16 v[74:77], v[234:237], v[196:199], v[74:77]
	v_mfma_f32_16x16x32_bf16 v[70:73], v[212:215], v[204:207], v[70:73]
	v_mfma_f32_16x16x32_bf16 v[66:69], v[234:237], v[204:207], v[66:69]
	s_mov_b32 m0, s50
	v_lshl_add_u64 v[172:173], v[228:229], 0, s[0:1]
	s_barrier
	ds_read_b128 v[176:179], v154 offset:49152
	ds_read_b128 v[180:183], v154 offset:50176
	ds_read_b128 v[184:187], v154 offset:51200
	ds_read_b128 v[188:191], v154 offset:52224
	ds_read_b128 v[192:195], v154 offset:53248
	ds_read_b128 v[196:199], v154 offset:54272
	ds_read_b128 v[200:203], v154 offset:55296
	ds_read_b128 v[204:207], v154 offset:56320
	global_load_lds_dwordx4 v[172:173], off
	v_lshl_add_u64 v[172:173], v[238:239], 0, s[0:1]
	s_mov_b32 m0, s51
	s_nop 0
	global_load_lds_dwordx4 v[172:173], off
	s_barrier
; #define PG8_STAGE(bufoff, gbase, voff) do { _Pragma("unroll") for (int _i = 0; _i < 2; ++_i) \
;         __builtin_amdgcn_global_load_lds((const unsigned*)((const char*)(gbase) + (voff)[_i]), (PG8_LAS unsigned*)(lds + (bufoff) + ldsw + _i * 8192), 16, 0, 0); } while (0)
; #define PG8_LDA(dst, b, h) do { _Pragma("unroll") for (int m = 0; m < 4; ++m) _Pragma("unroll") for (int k = 0; k < 2; ++k) dst[m][k] = *(const PG8_LAS bf16x8*)(lds + PG8_SA(b, h) + aoff + m * 2048 + k * 1024); } while (0)
; #define PG8_LDB(dst, b, h) do { _Pragma("unroll") for (int n = 0; n < 2; ++n) _Pragma("unroll") for (int k = 0; k < 2; ++k) dst[n][k] = *(const PG8_LAS bf16x8*)(lds + PG8_SB(b, h) + boff + n * 2048 + k * 1024); } while (0)
; #define PG8_MMA(ai, bj, At, Bt) do { __builtin_amdgcn_s_setprio(1); _Pragma("unroll") for (int m = 0; m < 4; ++m) _Pragma("unroll") for (int n = 0; n < 2; ++n) _Pragma("unroll") for (int k = 0; k < 2; ++k) \
;         acc[ai][bj][m][n] = __builtin_amdgcn_mfma_f32_16x16x32_bf16(Bt[n][k], At[m][k], acc[ai][bj][m][n], 0, 0, 0); __builtin_amdgcn_s_setprio(0); } while (0)
; #define PG8_WAIT_V(n) asm volatile("s_waitcnt vmcnt(" #n ")" ::: "memory")
; #define PG8_WAIT_L(n) asm volatile("s_waitcnt lgkmcnt(" #n ")" ::: "memory")
; template <class Epi, class Sched>
; __device__ __forceinline__ void gemm_phase(PG8_LAS unsigned char* lds, const Gemm g, const Sched& S, const Epi& E) {
;     ...
;         for (int t = 0; t < nt; t += 2) {
;             const bool last = (t == nt - 2);
;             const char* a1 = cA + (size_t)(t + 1) * kstep;
;             const char* a2 = last ? nA : cA + (size_t)(t + 2) * kstep; const char* b2 = last ? nB : cB + (size_t)(t + 2) * kstep;
;             const char* a3 = a2 + kstep; const char* b3 = b2 + kstep;
;             if (last && has_next) S.a_ready(nxt);
;             PG8_LDB(B0, 0, 0); PG8_SCHED; PG8_LDA(At, 0, 0); PG8_STAGE(PG8_SA(1, 1), a1 + hstep, voffA);
;             PG8_WAIT_L(8); PG8_BAR; PG8_WAIT_L(0); PG8_MMA(0, 0, At, B0); PG8_BAR; PG8_SCHED;
;             PG8_LDB(B1, 0, 1); PG8_STAGE(PG8_SB(0, 0), b2, voffB);
;     ...
;             PG8_LDA(At, 1, 1); PG8_STAGE(PG8_SA(1, 0), a3, voffA);
;             PG8_BAR; PG8_WAIT_L(0); PG8_MMA(1, 0, At, B0); PG8_BAR; PG8_SCHED;
;             PG8_STAGE(PG8_SB(1, 1), b3 + hstep, voffB);
;             PG8_WAIT_V(6); PG8_BAR; PG8_MMA(1, 1, At, B1); PG8_BAR;
	s_waitcnt lgkmcnt(7)
	v_mfma_f32_16x16x32_bf16 v[62:65], v[156:159], v[176:179], v[62:65]
	v_mfma_f32_16x16x32_bf16 v[58:61], v[164:167], v[176:179], v[58:61]
	s_waitcnt lgkmcnt(5)
	v_mfma_f32_16x16x32_bf16 v[54:57], v[156:159], v[184:187], v[54:57]
	v_mfma_f32_16x16x32_bf16 v[50:53], v[164:167], v[184:187], v[50:53]
	s_waitcnt lgkmcnt(3)
	v_mfma_f32_16x16x32_bf16 v[44:47], v[156:159], v[192:195], v[44:47]
	v_mfma_f32_16x16x32_bf16 v[40:43], v[164:167], v[192:195], v[40:43]
	s_waitcnt lgkmcnt(1)
	v_mfma_f32_16x16x32_bf16 v[32:35], v[156:159], v[200:203], v[32:35]
	v_mfma_f32_16x16x32_bf16 v[24:27], v[164:167], v[200:203], v[24:27]
	v_mfma_f32_16x16x32_bf16 v[62:65], v[160:163], v[180:183], v[62:65]
	v_mfma_f32_16x16x32_bf16 v[58:61], v[168:171], v[180:183], v[58:61]
	v_mfma_f32_16x16x32_bf16 v[54:57], v[160:163], v[188:191], v[54:57]
	v_mfma_f32_16x16x32_bf16 v[50:53], v[168:171], v[188:191], v[50:53]
	v_mfma_f32_16x16x32_bf16 v[44:47], v[160:163], v[196:199], v[44:47]
	v_mfma_f32_16x16x32_bf16 v[40:43], v[168:171], v[196:199], v[40:43]
	s_waitcnt lgkmcnt(0)
	v_mfma_f32_16x16x32_bf16 v[32:35], v[160:163], v[204:207], v[32:35]
	v_mfma_f32_16x16x32_bf16 v[24:27], v[168:171], v[204:207], v[24:27]
	s_barrier
	s_add_i32 s22, s22, s37
	v_lshl_add_u64 v[156:157], v[240:241], 0, s[0:1]
	s_mov_b32 m0, s22
	s_nop 0
	global_load_lds_dwordx4 v[156:157], off
	v_lshl_add_u64 v[156:157], v[242:243], 0, s[0:1]
	s_add_i32 m0, s22, 0x2000
	s_nop 0
	global_load_lds_dwordx4 v[156:157], off
	s_waitcnt vmcnt(6)
	s_barrier
	v_mfma_f32_16x16x32_bf16 v[36:39], v[208:211], v[176:179], v[36:39]
	v_mfma_f32_16x16x32_bf16 v[28:31], v[216:219], v[176:179], v[28:31]
	v_mfma_f32_16x16x32_bf16 v[20:23], v[208:211], v[184:187], v[20:23]
	v_mfma_f32_16x16x32_bf16 v[16:19], v[216:219], v[184:187], v[16:19]
	v_mfma_f32_16x16x32_bf16 v[12:15], v[208:211], v[192:195], v[12:15]
	v_mfma_f32_16x16x32_bf16 v[8:11], v[216:219], v[192:195], v[8:11]
	v_mfma_f32_16x16x32_bf16 v[4:7], v[208:211], v[200:203], v[4:7]
	v_mfma_f32_16x16x32_bf16 v[0:3], v[216:219], v[200:203], v[0:3]
	v_mfma_f32_16x16x32_bf16 v[36:39], v[212:215], v[180:183], v[36:39]
	v_mfma_f32_16x16x32_bf16 v[28:31], v[234:237], v[180:183], v[28:31]
	v_mfma_f32_16x16x32_bf16 v[20:23], v[212:215], v[188:191], v[20:23]
	v_mfma_f32_16x16x32_bf16 v[16:19], v[234:237], v[188:191], v[16:19]
	v_mfma_f32_16x16x32_bf16 v[12:15], v[212:215], v[196:199], v[12:15]
	v_mfma_f32_16x16x32_bf16 v[8:11], v[234:237], v[196:199], v[8:11]
	v_mfma_f32_16x16x32_bf16 v[4:7], v[212:215], v[204:207], v[4:7]
	v_mfma_f32_16x16x32_bf16 v[0:3], v[234:237], v[204:207], v[0:3]
	s_add_u32 s20, s20, 0x100
	s_addc_u32 s21, s21, 0
	s_add_u32 s3, s3, 0x100
	s_addc_u32 s40, s40, 0
	s_cmp_ge_u32 s41, s54
	s_mov_b32 s22, s41
	s_barrier
	s_cbranch_scc1 .Lkpeel_exit_288
.LBB0_288:
	s_add_i32 s41, s22, 2
	s_add_u32 s24, s20, 0x80
	s_addc_u32 s23, s21, 0
	s_add_i32 s63, 0, 0x10000
	v_add_u32_e32 v155, s63, v152
	ds_read_b128 v[156:159], v155
	ds_read_b128 v[160:163], v155 offset:1024
	ds_read_b128 v[164:167], v155 offset:2048
	ds_read_b128 v[168:171], v155 offset:3072
	s_cmp_eq_u32 s55, s22
	s_cselect_b32 s22, s12, s24
	s_cselect_b32 s23, s13, s23
	s_cselect_b32 s25, s17, s40
	s_cselect_b32 s24, s16, s3
	v_lshl_add_u64 v[172:173], s[20:21], 0, v[148:149]
	s_add_i32 m0, s43, 0xc000
	ds_read_b128 v[176:179], v154
	ds_read_b128 v[180:183], v154 offset:1024
	ds_read_b128 v[184:187], v154 offset:2048
	ds_read_b128 v[188:191], v154 offset:3072
	ds_read_b128 v[192:195], v154 offset:4096
	ds_read_b128 v[196:199], v154 offset:5120
	ds_read_b128 v[200:203], v154 offset:6144
	ds_read_b128 v[204:207], v154 offset:7168
	global_load_lds_dwordx4 v[172:173], off
	v_lshl_add_u64 v[172:173], s[20:21], 0, v[150:151]
	s_add_i32 m0, s43, 0xe000
	s_nop 0
	global_load_lds_dwordx4 v[172:173], off
	s_waitcnt lgkmcnt(8)
	s_barrier
	s_waitcnt lgkmcnt(7)
	v_mfma_f32_16x16x32_bf16 v[126:129], v[156:159], v[176:179], v[126:129]
	v_mfma_f32_16x16x32_bf16 v[122:125], v[164:167], v[176:179], v[122:125]
	s_waitcnt lgkmcnt(5)
	v_mfma_f32_16x16x32_bf16 v[118:121], v[156:159], v[184:187], v[118:121]
	v_mfma_f32_16x16x32_bf16 v[114:117], v[164:167], v[184:187], v[114:117]
	s_waitcnt lgkmcnt(3)
	v_mfma_f32_16x16x32_bf16 v[110:113], v[156:159], v[192:195], v[110:113]
	v_mfma_f32_16x16x32_bf16 v[106:109], v[164:167], v[192:195], v[106:109]
	s_waitcnt lgkmcnt(1)
	v_mfma_f32_16x16x32_bf16 v[98:101], v[156:159], v[200:203], v[98:101]
	v_mfma_f32_16x16x32_bf16 v[90:93], v[164:167], v[200:203], v[90:93]
	v_mfma_f32_16x16x32_bf16 v[126:129], v[160:163], v[180:183], v[126:129]
	v_mfma_f32_16x16x32_bf16 v[122:125], v[168:171], v[180:183], v[122:125]
	v_mfma_f32_16x16x32_bf16 v[118:121], v[160:163], v[188:191], v[118:121]
	v_mfma_f32_16x16x32_bf16 v[114:117], v[168:171], v[188:191], v[114:117]
	v_mfma_f32_16x16x32_bf16 v[110:113], v[160:163], v[196:199], v[110:113]
	v_mfma_f32_16x16x32_bf16 v[106:109], v[168:171], v[196:199], v[106:109]
	s_waitcnt lgkmcnt(0)
	v_mfma_f32_16x16x32_bf16 v[98:101], v[160:163], v[204:207], v[98:101]
	v_mfma_f32_16x16x32_bf16 v[90:93], v[168:171], v[204:207], v[90:93]
	s_barrier
	s_add_i32 s64, 0, 0x14000
	s_add_i32 s63, s63, s37
	v_add_u32_e32 v155, s64, v152
	v_lshl_add_u64 v[172:173], s[24:25], 0, v[48:49]
	s_mov_b32 m0, s63
	ds_read_b128 v[208:211], v155
	ds_read_b128 v[212:215], v155 offset:1024
	ds_read_b128 v[216:219], v155 offset:2048
	ds_read_b128 v[234:237], v155 offset:3072
	global_load_lds_dwordx4 v[172:173], off
	v_lshl_add_u64 v[224:225], s[24:25], 0, v[130:131]
	s_add_i32 m0, s63, 0x2000
	s_nop 0
	global_load_lds_dwordx4 v[224:225], off
	s_barrier
; #define PG8_STAGE(bufoff, gbase, voff) do { _Pragma("unroll") for (int _i = 0; _i < 2; ++_i) \
;         __builtin_amdgcn_global_load_lds((const unsigned*)((const char*)(gbase) + (voff)[_i]), (PG8_LAS unsigned*)(lds + (bufoff) + ldsw + _i * 8192), 16, 0, 0); } while (0)
; #define PG8_LDA(dst, b, h) do { _Pragma("unroll") for (int m = 0; m < 4; ++m) _Pragma("unroll") for (int k = 0; k < 2; ++k) dst[m][k] = *(const PG8_LAS bf16x8*)(lds + PG8_SA(b, h) + aoff + m * 2048 + k * 1024); } while (0)
; #define PG8_LDB(dst, b, h) do { _Pragma("unroll") for (int n = 0; n < 2; ++n) _Pragma("unroll") for (int k = 0; k < 2; ++k) dst[n][k] = *(const PG8_LAS bf16x8*)(lds + PG8_SB(b, h) + boff + n * 2048 + k * 1024); } while (0)
; #define PG8_MMA(ai, bj, At, Bt) do { __builtin_amdgcn_s_setprio(1); _Pragma("unroll") for (int m = 0; m < 4; ++m) _Pragma("unroll") for (int n = 0; n < 2; ++n) _Pragma("unroll") for (int k = 0; k < 2; ++k) \
;         acc[ai][bj][m][n] = __builtin_amdgcn_mfma_f32_16x16x32_bf16(Bt[n][k], At[m][k], acc[ai][bj][m][n], 0, 0, 0); __builtin_amdgcn_s_setprio(0); } while (0)
; #define PG8_WAIT_V(n) asm volatile("s_waitcnt vmcnt(" #n ")" ::: "memory")
; #define PG8_WAIT_L(n) asm volatile("s_waitcnt lgkmcnt(" #n ")" ::: "memory")
; #define PG8_BAR __builtin_amdgcn_s_barrier()
; #define PG8_SCHED __builtin_amdgcn_sched_barrier(0)
; template <class Epi, class Sched>
; __device__ __forceinline__ void gemm_phase(PG8_LAS unsigned char* lds, const Gemm g, const Sched& S, const Epi& E) {
;     ...
;             PG8_LDB(B1, 0, 1); PG8_STAGE(PG8_SB(0, 0), b2, voffB);
;             PG8_BAR; PG8_WAIT_L(0); PG8_MMA(0, 1, At, B1); PG8_BAR;
;             PG8_LDA(At, 0, 1); PG8_STAGE(PG8_SA(0, 0), a2, voffA);
;             PG8_BAR; PG8_WAIT_L(0); PG8_MMA(1, 0, At, B0); PG8_BAR; PG8_SCHED;
;             PG8_STAGE(PG8_SB(0, 1), b2 + hstep, voffB);
;             PG8_WAIT_V(6); PG8_BAR; PG8_MMA(1, 1, At, B1); PG8_BAR;
;             PG8_LDB(B0, 1, 0); PG8_SCHED; PG8_LDA(At, 1, 0); PG8_STAGE(PG8_SA(0, 1), a2 + hstep, voffA);
	s_waitcnt lgkmcnt(3)
	v_mfma_f32_16x16x32_bf16 v[102:105], v[208:211], v[176:179], v[102:105]
	s_waitcnt lgkmcnt(1)
	v_mfma_f32_16x16x32_bf16 v[94:97], v[216:219], v[176:179], v[94:97]
	v_mfma_f32_16x16x32_bf16 v[86:89], v[208:211], v[184:187], v[86:89]
	v_mfma_f32_16x16x32_bf16 v[82:85], v[216:219], v[184:187], v[82:85]
	v_mfma_f32_16x16x32_bf16 v[78:81], v[208:211], v[192:195], v[78:81]
	v_mfma_f32_16x16x32_bf16 v[74:77], v[216:219], v[192:195], v[74:77]
	v_mfma_f32_16x16x32_bf16 v[70:73], v[208:211], v[200:203], v[70:73]
	v_mfma_f32_16x16x32_bf16 v[66:69], v[216:219], v[200:203], v[66:69]
	v_mfma_f32_16x16x32_bf16 v[102:105], v[212:215], v[180:183], v[102:105]
	s_waitcnt lgkmcnt(0)
	v_mfma_f32_16x16x32_bf16 v[94:97], v[234:237], v[180:183], v[94:97]
	v_mfma_f32_16x16x32_bf16 v[86:89], v[212:215], v[188:191], v[86:89]
	v_mfma_f32_16x16x32_bf16 v[82:85], v[234:237], v[188:191], v[82:85]
	v_mfma_f32_16x16x32_bf16 v[78:81], v[212:215], v[196:199], v[78:81]
	v_mfma_f32_16x16x32_bf16 v[74:77], v[234:237], v[196:199], v[74:77]
	v_mfma_f32_16x16x32_bf16 v[70:73], v[212:215], v[204:207], v[70:73]
	v_mfma_f32_16x16x32_bf16 v[66:69], v[234:237], v[204:207], v[66:69]
	s_mov_b32 m0, s43
	v_lshl_add_u64 v[228:229], s[22:23], 0, v[48:49]
	s_barrier
	ds_read_b128 v[176:179], v154 offset:16384
	ds_read_b128 v[180:183], v154 offset:17408
	ds_read_b128 v[184:187], v154 offset:18432
	ds_read_b128 v[188:191], v154 offset:19456
	ds_read_b128 v[192:195], v154 offset:20480
	ds_read_b128 v[196:199], v154 offset:21504
	ds_read_b128 v[200:203], v154 offset:22528
	ds_read_b128 v[204:207], v154 offset:23552
	global_load_lds_dwordx4 v[228:229], off
	v_lshl_add_u64 v[238:239], s[22:23], 0, v[130:131]
	s_mov_b32 m0, s44
	s_nop 0
	global_load_lds_dwordx4 v[238:239], off
	s_barrier
	s_waitcnt lgkmcnt(7)
	v_mfma_f32_16x16x32_bf16 v[62:65], v[156:159], v[176:179], v[62:65]
	v_mfma_f32_16x16x32_bf16 v[58:61], v[164:167], v[176:179], v[58:61]
	s_waitcnt lgkmcnt(5)
	v_mfma_f32_16x16x32_bf16 v[54:57], v[156:159], v[184:187], v[54:57]
	v_mfma_f32_16x16x32_bf16 v[50:53], v[164:167], v[184:187], v[50:53]
	s_waitcnt lgkmcnt(3)
	v_mfma_f32_16x16x32_bf16 v[44:47], v[156:159], v[192:195], v[44:47]
	v_mfma_f32_16x16x32_bf16 v[40:43], v[164:167], v[192:195], v[40:43]
	s_waitcnt lgkmcnt(1)
	v_mfma_f32_16x16x32_bf16 v[32:35], v[156:159], v[200:203], v[32:35]
	v_mfma_f32_16x16x32_bf16 v[24:27], v[164:167], v[200:203], v[24:27]
	v_mfma_f32_16x16x32_bf16 v[62:65], v[160:163], v[180:183], v[62:65]
	v_mfma_f32_16x16x32_bf16 v[58:61], v[168:171], v[180:183], v[58:61]
	v_mfma_f32_16x16x32_bf16 v[54:57], v[160:163], v[188:191], v[54:57]
	v_mfma_f32_16x16x32_bf16 v[50:53], v[168:171], v[188:191], v[50:53]
	v_mfma_f32_16x16x32_bf16 v[44:47], v[160:163], v[196:199], v[44:47]
	v_mfma_f32_16x16x32_bf16 v[40:43], v[168:171], v[196:199], v[40:43]
	s_waitcnt lgkmcnt(0)
	v_mfma_f32_16x16x32_bf16 v[32:35], v[160:163], v[204:207], v[32:35]
	v_mfma_f32_16x16x32_bf16 v[24:27], v[168:171], v[204:207], v[24:27]
	s_barrier
	s_add_u32 s24, s24, s10
	s_addc_u32 s25, s25, 0
	s_add_i32 s63, s64, s37
	v_lshl_add_u64 v[240:241], s[24:25], 0, v[48:49]
	s_mov_b32 m0, s63
	v_lshl_add_u64 v[242:243], s[24:25], 0, v[130:131]
	global_load_lds_dwordx4 v[240:241], off
	s_add_i32 m0, s63, 0x2000
	s_nop 0
	global_load_lds_dwordx4 v[242:243], off
	s_waitcnt vmcnt(6)
	s_barrier
	v_mfma_f32_16x16x32_bf16 v[36:39], v[208:211], v[176:179], v[36:39]
	v_mfma_f32_16x16x32_bf16 v[28:31], v[216:219], v[176:179], v[28:31]
	v_mfma_f32_16x16x32_bf16 v[20:23], v[208:211], v[184:187], v[20:23]
	v_mfma_f32_16x16x32_bf16 v[16:19], v[216:219], v[184:187], v[16:19]
	v_mfma_f32_16x16x32_bf16 v[12:15], v[208:211], v[192:195], v[12:15]
	v_mfma_f32_16x16x32_bf16 v[8:11], v[216:219], v[192:195], v[8:11]
	v_mfma_f32_16x16x32_bf16 v[4:7], v[208:211], v[200:203], v[4:7]
	v_mfma_f32_16x16x32_bf16 v[0:3], v[216:219], v[200:203], v[0:3]
	v_mfma_f32_16x16x32_bf16 v[36:39], v[212:215], v[180:183], v[36:39]
	v_mfma_f32_16x16x32_bf16 v[28:31], v[234:237], v[180:183], v[28:31]
	v_mfma_f32_16x16x32_bf16 v[20:23], v[212:215], v[188:191], v[20:23]
	v_mfma_f32_16x16x32_bf16 v[16:19], v[234:237], v[188:191], v[16:19]
	v_mfma_f32_16x16x32_bf16 v[12:15], v[212:215], v[196:199], v[12:15]
	v_mfma_f32_16x16x32_bf16 v[8:11], v[234:237], v[196:199], v[8:11]
	v_mfma_f32_16x16x32_bf16 v[4:7], v[212:215], v[204:207], v[4:7]
	v_mfma_f32_16x16x32_bf16 v[0:3], v[234:237], v[204:207], v[0:3]
	s_add_i32 s24, 0, 0x18000
	v_add_u32_e32 v155, s24, v152
	s_barrier
	ds_read_b128 v[156:159], v155
	ds_read_b128 v[160:163], v155 offset:1024
	ds_read_b128 v[164:167], v155 offset:2048
	ds_read_b128 v[168:171], v155 offset:3072
	s_add_u32 s22, s22, s10
	s_addc_u32 s23, s23, 0
	s_mov_b32 m0, s46
	v_lshl_add_u64 v[208:209], s[22:23], 0, v[48:49]
	ds_read_b128 v[176:179], v154 offset:32768
	ds_read_b128 v[180:183], v154 offset:33792
	ds_read_b128 v[184:187], v154 offset:34816
	ds_read_b128 v[188:191], v154 offset:35840
	ds_read_b128 v[192:195], v154 offset:36864
	ds_read_b128 v[196:199], v154 offset:37888
	ds_read_b128 v[200:203], v154 offset:38912
	ds_read_b128 v[204:207], v154 offset:39936
	global_load_lds_dwordx4 v[208:209], off
	v_lshl_add_u64 v[208:209], s[22:23], 0, v[130:131]
	s_mov_b32 m0, s47
	s_nop 0
	global_load_lds_dwordx4 v[208:209], off
	s_waitcnt lgkmcnt(8)
	s_barrier
; #define PG8_STAGE(bufoff, gbase, voff) do { _Pragma("unroll") for (int _i = 0; _i < 2; ++_i) \
;         __builtin_amdgcn_global_load_lds((const unsigned*)((const char*)(gbase) + (voff)[_i]), (PG8_LAS unsigned*)(lds + (bufoff) + ldsw + _i * 8192), 16, 0, 0); } while (0)
; #define PG8_LDA(dst, b, h) do { _Pragma("unroll") for (int m = 0; m < 4; ++m) _Pragma("unroll") for (int k = 0; k < 2; ++k) dst[m][k] = *(const PG8_LAS bf16x8*)(lds + PG8_SA(b, h) + aoff + m * 2048 + k * 1024); } while (0)
; #define PG8_LDB(dst, b, h) do { _Pragma("unroll") for (int n = 0; n < 2; ++n) _Pragma("unroll") for (int k = 0; k < 2; ++k) dst[n][k] = *(const PG8_LAS bf16x8*)(lds + PG8_SB(b, h) + boff + n * 2048 + k * 1024); } while (0)
; #define PG8_MMA(ai, bj, At, Bt) do { __builtin_amdgcn_s_setprio(1); _Pragma("unroll") for (int m = 0; m < 4; ++m) _Pragma("unroll") for (int n = 0; n < 2; ++n) _Pragma("unroll") for (int k = 0; k < 2; ++k) \
;         acc[ai][bj][m][n] = __builtin_amdgcn_mfma_f32_16x16x32_bf16(Bt[n][k], At[m][k], acc[ai][bj][m][n], 0, 0, 0); __builtin_amdgcn_s_setprio(0); } while (0)
; #define PG8_WAIT_V(n) asm volatile("s_waitcnt vmcnt(" #n ")" ::: "memory")
; #define PG8_WAIT_L(n) asm volatile("s_waitcnt lgkmcnt(" #n ")" ::: "memory")
; #define PG8_BAR __builtin_amdgcn_s_barrier()
; #define PG8_SCHED __builtin_amdgcn_sched_barrier(0)
; template <class Epi, class Sched>
; __device__ __forceinline__ void gemm_phase(PG8_LAS unsigned char* lds, const Gemm g, const Sched& S, const Epi& E) {
;     ...
;             PG8_LDB(B0, 1, 0); PG8_SCHED; PG8_LDA(At, 1, 0); PG8_STAGE(PG8_SA(0, 1), a2 + hstep, voffA);
;             PG8_WAIT_L(8); PG8_BAR; PG8_WAIT_L(0); PG8_MMA(0, 0, At, B0); PG8_BAR; PG8_SCHED;
;             PG8_LDB(B1, 1, 1); PG8_STAGE(PG8_SB(1, 0), b3, voffB);
;             PG8_BAR; PG8_WAIT_L(0); PG8_MMA(0, 1, At, B1); PG8_BAR;
;             PG8_LDA(At, 1, 1); PG8_STAGE(PG8_SA(1, 0), a3, voffA);
;             PG8_BAR; PG8_WAIT_L(0); PG8_MMA(1, 0, At, B0); PG8_BAR; PG8_SCHED;
;             PG8_STAGE(PG8_SB(1, 1), b3 + hstep, voffB);
;             PG8_WAIT_V(6); PG8_BAR; PG8_MMA(1, 1, At, B1); PG8_BAR;
	s_waitcnt lgkmcnt(7)
	v_mfma_f32_16x16x32_bf16 v[126:129], v[156:159], v[176:179], v[126:129]
	v_mfma_f32_16x16x32_bf16 v[122:125], v[164:167], v[176:179], v[122:125]
	s_waitcnt lgkmcnt(5)
	v_mfma_f32_16x16x32_bf16 v[118:121], v[156:159], v[184:187], v[118:121]
	v_mfma_f32_16x16x32_bf16 v[114:117], v[164:167], v[184:187], v[114:117]
	s_waitcnt lgkmcnt(3)
	v_mfma_f32_16x16x32_bf16 v[110:113], v[156:159], v[192:195], v[110:113]
	v_mfma_f32_16x16x32_bf16 v[106:109], v[164:167], v[192:195], v[106:109]
	s_waitcnt lgkmcnt(1)
	v_mfma_f32_16x16x32_bf16 v[98:101], v[156:159], v[200:203], v[98:101]
	v_mfma_f32_16x16x32_bf16 v[90:93], v[164:167], v[200:203], v[90:93]
	v_mfma_f32_16x16x32_bf16 v[126:129], v[160:163], v[180:183], v[126:129]
	v_mfma_f32_16x16x32_bf16 v[122:125], v[168:171], v[180:183], v[122:125]
	v_mfma_f32_16x16x32_bf16 v[118:121], v[160:163], v[188:191], v[118:121]
	v_mfma_f32_16x16x32_bf16 v[114:117], v[168:171], v[188:191], v[114:117]
	v_mfma_f32_16x16x32_bf16 v[110:113], v[160:163], v[196:199], v[110:113]
	v_mfma_f32_16x16x32_bf16 v[106:109], v[168:171], v[196:199], v[106:109]
	s_waitcnt lgkmcnt(0)
	v_mfma_f32_16x16x32_bf16 v[98:101], v[160:163], v[204:207], v[98:101]
	v_mfma_f32_16x16x32_bf16 v[90:93], v[168:171], v[204:207], v[90:93]
	s_barrier
	s_add_i32 s22, 0, 0x1c000
	s_add_i32 s23, s24, s37
	v_add_u32_e32 v155, s22, v152
	v_lshl_add_u64 v[172:173], v[172:173], 0, s[0:1]
	s_mov_b32 m0, s23
	ds_read_b128 v[208:211], v155
	ds_read_b128 v[212:215], v155 offset:1024
	ds_read_b128 v[216:219], v155 offset:2048
	ds_read_b128 v[234:237], v155 offset:3072
	global_load_lds_dwordx4 v[172:173], off
	v_lshl_add_u64 v[172:173], v[224:225], 0, s[0:1]
	s_add_i32 m0, s23, 0x2000
	s_nop 0
	global_load_lds_dwordx4 v[172:173], off
	s_barrier
	s_waitcnt lgkmcnt(3)
	v_mfma_f32_16x16x32_bf16 v[102:105], v[208:211], v[176:179], v[102:105]
	s_waitcnt lgkmcnt(1)
	v_mfma_f32_16x16x32_bf16 v[94:97], v[216:219], v[176:179], v[94:97]
	v_mfma_f32_16x16x32_bf16 v[86:89], v[208:211], v[184:187], v[86:89]
	v_mfma_f32_16x16x32_bf16 v[82:85], v[216:219], v[184:187], v[82:85]
	v_mfma_f32_16x16x32_bf16 v[78:81], v[208:211], v[192:195], v[78:81]
	v_mfma_f32_16x16x32_bf16 v[74:77], v[216:219], v[192:195], v[74:77]
	v_mfma_f32_16x16x32_bf16 v[70:73], v[208:211], v[200:203], v[70:73]
	v_mfma_f32_16x16x32_bf16 v[66:69], v[216:219], v[200:203], v[66:69]
	v_mfma_f32_16x16x32_bf16 v[102:105], v[212:215], v[180:183], v[102:105]
	s_waitcnt lgkmcnt(0)
	v_mfma_f32_16x16x32_bf16 v[94:97], v[234:237], v[180:183], v[94:97]
	v_mfma_f32_16x16x32_bf16 v[86:89], v[212:215], v[188:191], v[86:89]
	v_mfma_f32_16x16x32_bf16 v[82:85], v[234:237], v[188:191], v[82:85]
	v_mfma_f32_16x16x32_bf16 v[78:81], v[212:215], v[196:199], v[78:81]
	v_mfma_f32_16x16x32_bf16 v[74:77], v[234:237], v[196:199], v[74:77]
	v_mfma_f32_16x16x32_bf16 v[70:73], v[212:215], v[204:207], v[70:73]
	v_mfma_f32_16x16x32_bf16 v[66:69], v[234:237], v[204:207], v[66:69]
	s_mov_b32 m0, s50
	v_lshl_add_u64 v[172:173], v[228:229], 0, s[0:1]
	s_barrier
	ds_read_b128 v[176:179], v154 offset:49152
	ds_read_b128 v[180:183], v154 offset:50176
	ds_read_b128 v[184:187], v154 offset:51200
	ds_read_b128 v[188:191], v154 offset:52224
	ds_read_b128 v[192:195], v154 offset:53248
	ds_read_b128 v[196:199], v154 offset:54272
	ds_read_b128 v[200:203], v154 offset:55296
	ds_read_b128 v[204:207], v154 offset:56320
	global_load_lds_dwordx4 v[172:173], off
	v_lshl_add_u64 v[172:173], v[238:239], 0, s[0:1]
	s_mov_b32 m0, s51
	s_nop 0
	global_load_lds_dwordx4 v[172:173], off
	s_barrier
	s_waitcnt lgkmcnt(7)
	v_mfma_f32_16x16x32_bf16 v[62:65], v[156:159], v[176:179], v[62:65]
	v_mfma_f32_16x16x32_bf16 v[58:61], v[164:167], v[176:179], v[58:61]
	s_waitcnt lgkmcnt(5)
	v_mfma_f32_16x16x32_bf16 v[54:57], v[156:159], v[184:187], v[54:57]
	v_mfma_f32_16x16x32_bf16 v[50:53], v[164:167], v[184:187], v[50:53]
	s_waitcnt lgkmcnt(3)
	v_mfma_f32_16x16x32_bf16 v[44:47], v[156:159], v[192:195], v[44:47]
	v_mfma_f32_16x16x32_bf16 v[40:43], v[164:167], v[192:195], v[40:43]
	s_waitcnt lgkmcnt(1)
	v_mfma_f32_16x16x32_bf16 v[32:35], v[156:159], v[200:203], v[32:35]
	v_mfma_f32_16x16x32_bf16 v[24:27], v[164:167], v[200:203], v[24:27]
	v_mfma_f32_16x16x32_bf16 v[62:65], v[160:163], v[180:183], v[62:65]
	v_mfma_f32_16x16x32_bf16 v[58:61], v[168:171], v[180:183], v[58:61]
	v_mfma_f32_16x16x32_bf16 v[54:57], v[160:163], v[188:191], v[54:57]
	v_mfma_f32_16x16x32_bf16 v[50:53], v[168:171], v[188:191], v[50:53]
	v_mfma_f32_16x16x32_bf16 v[44:47], v[160:163], v[196:199], v[44:47]
	v_mfma_f32_16x16x32_bf16 v[40:43], v[168:171], v[196:199], v[40:43]
	s_waitcnt lgkmcnt(0)
	v_mfma_f32_16x16x32_bf16 v[32:35], v[160:163], v[204:207], v[32:35]
	v_mfma_f32_16x16x32_bf16 v[24:27], v[168:171], v[204:207], v[24:27]
	s_barrier
	s_add_i32 s22, s22, s37
	v_lshl_add_u64 v[156:157], v[240:241], 0, s[0:1]
	s_mov_b32 m0, s22
	s_nop 0
	global_load_lds_dwordx4 v[156:157], off
	v_lshl_add_u64 v[156:157], v[242:243], 0, s[0:1]
	s_add_i32 m0, s22, 0x2000
	s_nop 0
	global_load_lds_dwordx4 v[156:157], off
	s_waitcnt vmcnt(6)
	s_barrier
	v_mfma_f32_16x16x32_bf16 v[36:39], v[208:211], v[176:179], v[36:39]
	v_mfma_f32_16x16x32_bf16 v[28:31], v[216:219], v[176:179], v[28:31]
	v_mfma_f32_16x16x32_bf16 v[20:23], v[208:211], v[184:187], v[20:23]
	v_mfma_f32_16x16x32_bf16 v[16:19], v[216:219], v[184:187], v[16:19]
	v_mfma_f32_16x16x32_bf16 v[12:15], v[208:211], v[192:195], v[12:15]
	v_mfma_f32_16x16x32_bf16 v[8:11], v[216:219], v[192:195], v[8:11]
	v_mfma_f32_16x16x32_bf16 v[4:7], v[208:211], v[200:203], v[4:7]
	v_mfma_f32_16x16x32_bf16 v[0:3], v[216:219], v[200:203], v[0:3]
	v_mfma_f32_16x16x32_bf16 v[36:39], v[212:215], v[180:183], v[36:39]
	v_mfma_f32_16x16x32_bf16 v[28:31], v[234:237], v[180:183], v[28:31]
	v_mfma_f32_16x16x32_bf16 v[20:23], v[212:215], v[188:191], v[20:23]
	v_mfma_f32_16x16x32_bf16 v[16:19], v[234:237], v[188:191], v[16:19]
	v_mfma_f32_16x16x32_bf16 v[12:15], v[212:215], v[196:199], v[12:15]
	v_mfma_f32_16x16x32_bf16 v[8:11], v[234:237], v[196:199], v[8:11]
	v_mfma_f32_16x16x32_bf16 v[4:7], v[212:215], v[204:207], v[4:7]
	v_mfma_f32_16x16x32_bf16 v[0:3], v[234:237], v[204:207], v[0:3]
	s_add_u32 s20, s20, 0x100
	s_addc_u32 s21, s21, 0
	s_add_u32 s3, s3, 0x100
	s_addc_u32 s40, s40, 0
	s_cmp_ge_u32 s41, s54
	s_mov_b32 s22, s41
	s_barrier
	s_cbranch_scc0 .LBB0_288

; #define PG8_STAGE(bufoff, gbase, voff) do { _Pragma("unroll") for (int _i = 0; _i < 2; ++_i) \
;         __builtin_amdgcn_global_load_lds((const unsigned*)((const char*)(gbase) + (voff)[_i]), (PG8_LAS unsigned*)(lds + (bufoff) + ldsw + _i * 8192), 16, 0, 0); } while (0)
; #define PG8_LDA(dst, b, h) do { _Pragma("unroll") for (int m = 0; m < 4; ++m) _Pragma("unroll") for (int k = 0; k < 2; ++k) dst[m][k] = *(const PG8_LAS bf16x8*)(lds + PG8_SA(b, h) + aoff + m * 2048 + k * 1024); } while (0)
; #define PG8_LDB(dst, b, h) do { _Pragma("unroll") for (int n = 0; n < 2; ++n) _Pragma("unroll") for (int k = 0; k < 2; ++k) dst[n][k] = *(const PG8_LAS bf16x8*)(lds + PG8_SB(b, h) + boff + n * 2048 + k * 1024); } while (0)
; #define PG8_WAIT_L(n) asm volatile("s_waitcnt lgkmcnt(" #n ")" ::: "memory")
; #define PG8_BAR __builtin_amdgcn_s_barrier()
; #define PG8_SCHED __builtin_amdgcn_sched_barrier(0)
; template <class Epi, class Sched>
; __device__ __forceinline__ void gemm_phase(PG8_LAS unsigned char* lds, const Gemm g, const Sched& S, const Epi& E) {
;     ...
;         const bool has_next = S.next(ui + 1, nxt);
;         const char* nA = has_next ? (const char*)g.A + (size_t)nxt.pm * tstepA + (size_t)nxt.kc * cstep : cA; const char* nB = has_next ? (const char*)g.Bt + (size_t)nxt.pn * tstep + (size_t)nxt.kc * cstep : cB;
;         for (int t = 0; t < nt; t += 2) {
;             const bool last = (t == nt - 2);
;             const char* a1 = cA + (size_t)(t + 1) * kstep;
;             const char* a2 = last ? nA : cA + (size_t)(t + 2) * kstep; const char* b2 = last ? nB : cB + (size_t)(t + 2) * kstep;
;             const char* a3 = a2 + kstep; const char* b3 = b2 + kstep;
;             if (last && has_next) S.a_ready(nxt);
;             PG8_LDB(B0, 0, 0); PG8_SCHED; PG8_LDA(At, 0, 0); PG8_STAGE(PG8_SA(1, 1), a1 + hstep, voffA);
;             PG8_WAIT_L(8); PG8_BAR; PG8_WAIT_L(0); PG8_MMA(0, 0, At, B0); PG8_BAR; PG8_SCHED;
;             PG8_LDB(B1, 0, 1); PG8_STAGE(PG8_SB(0, 0), b2, voffB);
;             PG8_BAR; PG8_WAIT_L(0); PG8_MMA(0, 1, At, B1); PG8_BAR;
;             PG8_LDA(At, 0, 1); PG8_STAGE(PG8_SA(0, 0), a2, voffA);
;             PG8_BAR; PG8_WAIT_L(0); PG8_MMA(1, 0, At, B0); PG8_BAR; PG8_SCHED;
.LBB0_319:
	v_mov_b64_e32 v[0:1], s[56:57]
	s_ashr_i32 s25, s24, 31
	v_cmp_lt_i64_e32 vcc, s[26:27], v[0:1]
	s_lshl_b64 s[26:27], s[24:25], 19
	s_add_u32 s26, s8, s26
	s_addc_u32 s27, s9, s27
	s_and_b64 s[28:29], vcc, exec
	s_cselect_b32 s25, s27, s31
	s_cselect_b32 s56, s26, s30
	s_ashr_i32 s23, s22, 31
	s_lshl_b64 s[28:29], s[22:23], 19
	s_add_u32 s28, s6, s28
	s_addc_u32 s29, s7, s29
	s_and_b64 s[36:37], vcc, exec
	s_cselect_b32 s23, s29, s35
	s_cselect_b32 s57, s28, s34
	s_add_u32 s30, s30, 0x40080
	s_addc_u32 s31, s31, 0
	s_add_u32 s59, s34, 0x100
	s_addc_u32 s63, s35, 0
	s_mov_b32 s64, -2
	s_add_u32 s34, s30, 0xfffc0080
	s_addc_u32 s35, s31, -1
	s_add_i32 s65, 0, 0x10000
	v_add_u32_e32 v140, s65, v143
	ds_read_b128 v[146:149], v140
	ds_read_b128 v[150:153], v140 offset:1024
	ds_read_b128 v[154:157], v140 offset:2048
	ds_read_b128 v[158:161], v140 offset:3072
	s_cmp_eq_u32 s64, 12
	s_cselect_b32 s37, s25, s35
	s_cselect_b32 s36, s56, s34
	s_cselect_b32 s35, s23, s63
	s_cselect_b32 s34, s57, s59
	v_lshl_add_u64 v[140:141], s[30:31], 0, v[136:137]
	s_add_i32 m0, s21, 0xc000
	ds_read_b128 v[162:165], v145
	ds_read_b128 v[166:169], v145 offset:1024
	ds_read_b128 v[170:173], v145 offset:2048
	ds_read_b128 v[176:179], v145 offset:3072
	ds_read_b128 v[180:183], v145 offset:4096
	ds_read_b128 v[184:187], v145 offset:5120
	ds_read_b128 v[188:191], v145 offset:6144
	ds_read_b128 v[192:195], v145 offset:7168
	global_load_lds_dwordx4 v[140:141], off
	v_lshl_add_u64 v[140:141], s[30:31], 0, v[138:139]
	s_add_i32 m0, s21, 0xe000
	s_nop 0
	global_load_lds_dwordx4 v[140:141], off
	s_waitcnt lgkmcnt(8)
	s_barrier
	s_waitcnt lgkmcnt(7)
	v_mfma_f32_16x16x32_bf16 v[126:129], v[146:149], v[162:165], 0
	v_mfma_f32_16x16x32_bf16 v[122:125], v[154:157], v[162:165], 0
	s_waitcnt lgkmcnt(5)
	v_mfma_f32_16x16x32_bf16 v[118:121], v[146:149], v[170:173], 0
	v_mfma_f32_16x16x32_bf16 v[110:113], v[154:157], v[170:173], 0
	s_waitcnt lgkmcnt(3)
	v_mfma_f32_16x16x32_bf16 v[102:105], v[146:149], v[180:183], 0
	v_mfma_f32_16x16x32_bf16 v[94:97], v[154:157], v[180:183], 0
	s_waitcnt lgkmcnt(1)
	v_mfma_f32_16x16x32_bf16 v[86:89], v[146:149], v[188:191], 0
	v_mfma_f32_16x16x32_bf16 v[78:81], v[154:157], v[188:191], 0
	v_mfma_f32_16x16x32_bf16 v[126:129], v[150:153], v[166:169], v[126:129]
	v_mfma_f32_16x16x32_bf16 v[122:125], v[158:161], v[166:169], v[122:125]
	v_mfma_f32_16x16x32_bf16 v[118:121], v[150:153], v[176:179], v[118:121]
	v_mfma_f32_16x16x32_bf16 v[110:113], v[158:161], v[176:179], v[110:113]
	v_mfma_f32_16x16x32_bf16 v[102:105], v[150:153], v[184:187], v[102:105]
	v_mfma_f32_16x16x32_bf16 v[94:97], v[158:161], v[184:187], v[94:97]
	s_waitcnt lgkmcnt(0)
	v_mfma_f32_16x16x32_bf16 v[86:89], v[150:153], v[192:195], v[86:89]
	v_mfma_f32_16x16x32_bf16 v[78:81], v[158:161], v[192:195], v[78:81]
	s_barrier
	s_add_i32 s68, 0, 0x14000
	v_add_u32_e32 v140, s68, v143
	s_add_i32 s65, s65, s13
	ds_read_b128 v[196:199], v140
	ds_read_b128 v[200:203], v140 offset:1024
	ds_read_b128 v[204:207], v140 offset:2048
	ds_read_b128 v[208:211], v140 offset:3072
	v_lshl_add_u64 v[140:141], s[34:35], 0, v[48:49]
	s_mov_b32 m0, s65
	v_lshl_add_u64 v[212:213], s[34:35], 0, v[130:131]
	global_load_lds_dwordx4 v[140:141], off
	s_add_i32 m0, s65, 0x2000
	s_nop 0
	global_load_lds_dwordx4 v[212:213], off
	s_barrier
	s_waitcnt lgkmcnt(3)
	v_mfma_f32_16x16x32_bf16 v[114:117], v[196:199], v[162:165], 0
	s_waitcnt lgkmcnt(1)
	v_mfma_f32_16x16x32_bf16 v[106:109], v[204:207], v[162:165], 0
	v_mfma_f32_16x16x32_bf16 v[98:101], v[196:199], v[170:173], 0
	v_mfma_f32_16x16x32_bf16 v[90:93], v[204:207], v[170:173], 0
	v_mfma_f32_16x16x32_bf16 v[82:85], v[196:199], v[180:183], 0
	v_mfma_f32_16x16x32_bf16 v[74:77], v[204:207], v[180:183], 0
	v_mfma_f32_16x16x32_bf16 v[70:73], v[196:199], v[188:191], 0
	v_mfma_f32_16x16x32_bf16 v[66:69], v[204:207], v[188:191], 0
	v_mfma_f32_16x16x32_bf16 v[114:117], v[200:203], v[166:169], v[114:117]
	s_waitcnt lgkmcnt(0)
	v_mfma_f32_16x16x32_bf16 v[106:109], v[208:211], v[166:169], v[106:109]
	v_mfma_f32_16x16x32_bf16 v[98:101], v[200:203], v[176:179], v[98:101]
	v_mfma_f32_16x16x32_bf16 v[90:93], v[208:211], v[176:179], v[90:93]
	v_mfma_f32_16x16x32_bf16 v[82:85], v[200:203], v[184:187], v[82:85]
	v_mfma_f32_16x16x32_bf16 v[74:77], v[208:211], v[184:187], v[74:77]
	v_mfma_f32_16x16x32_bf16 v[70:73], v[200:203], v[192:195], v[70:73]
	v_mfma_f32_16x16x32_bf16 v[66:69], v[208:211], v[192:195], v[66:69]
	s_mov_b32 m0, s21
	v_lshl_add_u64 v[214:215], s[36:37], 0, v[134:135]
	s_barrier
	ds_read_b128 v[162:165], v145 offset:16384
	ds_read_b128 v[166:169], v145 offset:17408
	ds_read_b128 v[170:173], v145 offset:18432
	ds_read_b128 v[176:179], v145 offset:19456
	ds_read_b128 v[180:183], v145 offset:20480
	ds_read_b128 v[184:187], v145 offset:21504
	ds_read_b128 v[188:191], v145 offset:22528
	ds_read_b128 v[192:195], v145 offset:23552
	global_load_lds_dwordx4 v[214:215], off
	v_lshl_add_u64 v[216:217], s[36:37], 0, v[132:133]
	s_mov_b32 m0, s46
	s_nop 0
	global_load_lds_dwordx4 v[216:217], off
	s_barrier
; #define PG8_STAGE(bufoff, gbase, voff) do { _Pragma("unroll") for (int _i = 0; _i < 2; ++_i) \
;         __builtin_amdgcn_global_load_lds((const unsigned*)((const char*)(gbase) + (voff)[_i]), (PG8_LAS unsigned*)(lds + (bufoff) + ldsw + _i * 8192), 16, 0, 0); } while (0)
; #define PG8_LDA(dst, b, h) do { _Pragma("unroll") for (int m = 0; m < 4; ++m) _Pragma("unroll") for (int k = 0; k < 2; ++k) dst[m][k] = *(const PG8_LAS bf16x8*)(lds + PG8_SA(b, h) + aoff + m * 2048 + k * 1024); } while (0)
; #define PG8_LDB(dst, b, h) do { _Pragma("unroll") for (int n = 0; n < 2; ++n) _Pragma("unroll") for (int k = 0; k < 2; ++k) dst[n][k] = *(const PG8_LAS bf16x8*)(lds + PG8_SB(b, h) + boff + n * 2048 + k * 1024); } while (0)
; #define PG8_MMA(ai, bj, At, Bt) do { __builtin_amdgcn_s_setprio(1); _Pragma("unroll") for (int m = 0; m < 4; ++m) _Pragma("unroll") for (int n = 0; n < 2; ++n) _Pragma("unroll") for (int k = 0; k < 2; ++k) \
;         acc[ai][bj][m][n] = __builtin_amdgcn_mfma_f32_16x16x32_bf16(Bt[n][k], At[m][k], acc[ai][bj][m][n], 0, 0, 0); __builtin_amdgcn_s_setprio(0); } while (0)
; #define PG8_WAIT_V(n) asm volatile("s_waitcnt vmcnt(" #n ")" ::: "memory")
; #define PG8_WAIT_L(n) asm volatile("s_waitcnt lgkmcnt(" #n ")" ::: "memory")
; #define PG8_BAR __builtin_amdgcn_s_barrier()
; #define PG8_SCHED __builtin_amdgcn_sched_barrier(0)
; template <class Epi, class Sched>
; __device__ __forceinline__ void gemm_phase(PG8_LAS unsigned char* lds, const Gemm g, const Sched& S, const Epi& E) {
;     ...
;             PG8_BAR; PG8_WAIT_L(0); PG8_MMA(1, 0, At, B0); PG8_BAR; PG8_SCHED;
;             PG8_STAGE(PG8_SB(0, 1), b2 + hstep, voffB);
;             PG8_WAIT_V(6); PG8_BAR; PG8_MMA(1, 1, At, B1); PG8_BAR;
;             PG8_LDB(B0, 1, 0); PG8_SCHED; PG8_LDA(At, 1, 0); PG8_STAGE(PG8_SA(0, 1), a2 + hstep, voffA);
;             PG8_WAIT_L(8); PG8_BAR; PG8_WAIT_L(0); PG8_MMA(0, 0, At, B0); PG8_BAR; PG8_SCHED;
;             PG8_LDB(B1, 1, 1); PG8_STAGE(PG8_SB(1, 0), b3, voffB);
;             PG8_BAR; PG8_WAIT_L(0); PG8_MMA(0, 1, At, B1); PG8_BAR;
	s_waitcnt lgkmcnt(7)
	v_mfma_f32_16x16x32_bf16 v[62:65], v[146:149], v[162:165], 0
	v_mfma_f32_16x16x32_bf16 v[58:61], v[154:157], v[162:165], 0
	s_waitcnt lgkmcnt(5)
	v_mfma_f32_16x16x32_bf16 v[54:57], v[146:149], v[170:173], 0
	v_mfma_f32_16x16x32_bf16 v[44:47], v[154:157], v[170:173], 0
	s_waitcnt lgkmcnt(3)
	v_mfma_f32_16x16x32_bf16 v[36:39], v[146:149], v[180:183], 0
	v_mfma_f32_16x16x32_bf16 v[28:31], v[154:157], v[180:183], 0
	s_waitcnt lgkmcnt(1)
	v_mfma_f32_16x16x32_bf16 v[20:23], v[146:149], v[188:191], 0
	v_mfma_f32_16x16x32_bf16 v[12:15], v[154:157], v[188:191], 0
	v_mfma_f32_16x16x32_bf16 v[62:65], v[150:153], v[166:169], v[62:65]
	v_mfma_f32_16x16x32_bf16 v[58:61], v[158:161], v[166:169], v[58:61]
	v_mfma_f32_16x16x32_bf16 v[54:57], v[150:153], v[176:179], v[54:57]
	v_mfma_f32_16x16x32_bf16 v[44:47], v[158:161], v[176:179], v[44:47]
	v_mfma_f32_16x16x32_bf16 v[36:39], v[150:153], v[184:187], v[36:39]
	v_mfma_f32_16x16x32_bf16 v[28:31], v[158:161], v[184:187], v[28:31]
	s_waitcnt lgkmcnt(0)
	v_mfma_f32_16x16x32_bf16 v[20:23], v[150:153], v[192:195], v[20:23]
	v_mfma_f32_16x16x32_bf16 v[12:15], v[158:161], v[192:195], v[12:15]
	s_barrier
	s_add_u32 s66, s34, 0x40000
	s_addc_u32 s67, s35, 0
	s_add_i32 s65, s68, s13
	v_lshl_add_u64 v[146:147], s[66:67], 0, v[48:49]
	s_mov_b32 m0, s65
	s_nop 0
	global_load_lds_dwordx4 v[146:147], off
	v_lshl_add_u64 v[146:147], s[66:67], 0, v[130:131]
	s_add_i32 m0, s65, 0x2000
	s_nop 0
	global_load_lds_dwordx4 v[146:147], off
	s_waitcnt vmcnt(6)
	s_barrier
	v_mfma_f32_16x16x32_bf16 v[50:53], v[196:199], v[162:165], 0
	v_mfma_f32_16x16x32_bf16 v[40:43], v[204:207], v[162:165], 0
	v_mfma_f32_16x16x32_bf16 v[32:35], v[196:199], v[170:173], 0
	v_mfma_f32_16x16x32_bf16 v[24:27], v[204:207], v[170:173], 0
	v_mfma_f32_16x16x32_bf16 v[16:19], v[196:199], v[180:183], 0
	v_mfma_f32_16x16x32_bf16 v[8:11], v[204:207], v[180:183], 0
	v_mfma_f32_16x16x32_bf16 v[4:7], v[196:199], v[188:191], 0
	v_mfma_f32_16x16x32_bf16 v[0:3], v[204:207], v[188:191], 0
	v_mfma_f32_16x16x32_bf16 v[50:53], v[200:203], v[166:169], v[50:53]
	v_mfma_f32_16x16x32_bf16 v[40:43], v[208:211], v[166:169], v[40:43]
	v_mfma_f32_16x16x32_bf16 v[32:35], v[200:203], v[176:179], v[32:35]
	v_mfma_f32_16x16x32_bf16 v[24:27], v[208:211], v[176:179], v[24:27]
	v_mfma_f32_16x16x32_bf16 v[16:19], v[200:203], v[184:187], v[16:19]
	v_mfma_f32_16x16x32_bf16 v[8:11], v[208:211], v[184:187], v[8:11]
	v_mfma_f32_16x16x32_bf16 v[4:7], v[200:203], v[192:195], v[4:7]
	v_mfma_f32_16x16x32_bf16 v[0:3], v[208:211], v[192:195], v[0:3]
	s_add_i32 s65, 0, 0x18000
	v_add_u32_e32 v158, s65, v143
	s_barrier
	ds_read_b128 v[146:149], v158
	ds_read_b128 v[150:153], v158 offset:1024
	ds_read_b128 v[154:157], v158 offset:2048
	ds_read_b128 v[158:161], v158 offset:3072
	s_add_u32 s36, s36, 0x40000
	s_addc_u32 s37, s37, 0
	s_mov_b32 m0, s47
	v_lshl_add_u64 v[196:197], s[36:37], 0, v[134:135]
	ds_read_b128 v[162:165], v145 offset:32768
	ds_read_b128 v[166:169], v145 offset:33792
	ds_read_b128 v[170:173], v145 offset:34816
	ds_read_b128 v[176:179], v145 offset:35840
	ds_read_b128 v[180:183], v145 offset:36864
	ds_read_b128 v[184:187], v145 offset:37888
	ds_read_b128 v[188:191], v145 offset:38912
	ds_read_b128 v[192:195], v145 offset:39936
	global_load_lds_dwordx4 v[196:197], off
	v_lshl_add_u64 v[196:197], s[36:37], 0, v[132:133]
	s_mov_b32 m0, s48
	s_nop 0
	global_load_lds_dwordx4 v[196:197], off
	s_waitcnt lgkmcnt(8)
	s_barrier
	s_waitcnt lgkmcnt(7)
	v_mfma_f32_16x16x32_bf16 v[126:129], v[146:149], v[162:165], v[126:129]
	v_mfma_f32_16x16x32_bf16 v[122:125], v[154:157], v[162:165], v[122:125]
	s_waitcnt lgkmcnt(5)
	v_mfma_f32_16x16x32_bf16 v[118:121], v[146:149], v[170:173], v[118:121]
	v_mfma_f32_16x16x32_bf16 v[110:113], v[154:157], v[170:173], v[110:113]
	s_waitcnt lgkmcnt(3)
	v_mfma_f32_16x16x32_bf16 v[102:105], v[146:149], v[180:183], v[102:105]
	v_mfma_f32_16x16x32_bf16 v[94:97], v[154:157], v[180:183], v[94:97]
	s_waitcnt lgkmcnt(1)
	v_mfma_f32_16x16x32_bf16 v[86:89], v[146:149], v[188:191], v[86:89]
	v_mfma_f32_16x16x32_bf16 v[78:81], v[154:157], v[188:191], v[78:81]
	v_mfma_f32_16x16x32_bf16 v[126:129], v[150:153], v[166:169], v[126:129]
	v_mfma_f32_16x16x32_bf16 v[122:125], v[158:161], v[166:169], v[122:125]
	v_mfma_f32_16x16x32_bf16 v[118:121], v[150:153], v[176:179], v[118:121]
	v_mfma_f32_16x16x32_bf16 v[110:113], v[158:161], v[176:179], v[110:113]
	v_mfma_f32_16x16x32_bf16 v[102:105], v[150:153], v[184:187], v[102:105]
	v_mfma_f32_16x16x32_bf16 v[94:97], v[158:161], v[184:187], v[94:97]
	s_waitcnt lgkmcnt(0)
	v_mfma_f32_16x16x32_bf16 v[86:89], v[150:153], v[192:195], v[86:89]
	v_mfma_f32_16x16x32_bf16 v[78:81], v[158:161], v[192:195], v[78:81]
	s_barrier
	s_add_i32 s36, 0, 0x1c000
	s_add_i32 s37, s65, s13
	v_add_u32_e32 v175, s36, v143
	v_lshl_add_u64 v[140:141], v[140:141], 0, s[0:1]
	s_mov_b32 m0, s37
	ds_read_b128 v[196:199], v175
	ds_read_b128 v[200:203], v175 offset:1024
	ds_read_b128 v[204:207], v175 offset:2048
	ds_read_b128 v[208:211], v175 offset:3072
	global_load_lds_dwordx4 v[140:141], off
	v_lshl_add_u64 v[140:141], v[212:213], 0, s[0:1]
	s_add_i32 m0, s37, 0x2000
	s_nop 0
	global_load_lds_dwordx4 v[140:141], off
	s_barrier
; #define PG8_STAGE(bufoff, gbase, voff) do { _Pragma("unroll") for (int _i = 0; _i < 2; ++_i) \
;         __builtin_amdgcn_global_load_lds((const unsigned*)((const char*)(gbase) + (voff)[_i]), (PG8_LAS unsigned*)(lds + (bufoff) + ldsw + _i * 8192), 16, 0, 0); } while (0)
; #define PG8_LDA(dst, b, h) do { _Pragma("unroll") for (int m = 0; m < 4; ++m) _Pragma("unroll") for (int k = 0; k < 2; ++k) dst[m][k] = *(const PG8_LAS bf16x8*)(lds + PG8_SA(b, h) + aoff + m * 2048 + k * 1024); } while (0)
; #define PG8_MMA(ai, bj, At, Bt) do { __builtin_amdgcn_s_setprio(1); _Pragma("unroll") for (int m = 0; m < 4; ++m) _Pragma("unroll") for (int n = 0; n < 2; ++n) _Pragma("unroll") for (int k = 0; k < 2; ++k) \
;         acc[ai][bj][m][n] = __builtin_amdgcn_mfma_f32_16x16x32_bf16(Bt[n][k], At[m][k], acc[ai][bj][m][n], 0, 0, 0); __builtin_amdgcn_s_setprio(0); } while (0)
; #define PG8_WAIT_V(n) asm volatile("s_waitcnt vmcnt(" #n ")" ::: "memory")
; #define PG8_WAIT_L(n) asm volatile("s_waitcnt lgkmcnt(" #n ")" ::: "memory")
; #define PG8_BAR __builtin_amdgcn_s_barrier()
; #define PG8_SCHED __builtin_amdgcn_sched_barrier(0)
; template <class Epi, class Sched>
; __device__ __forceinline__ void gemm_phase(PG8_LAS unsigned char* lds, const Gemm g, const Sched& S, const Epi& E) {
;     ...
;             PG8_BAR; PG8_WAIT_L(0); PG8_MMA(0, 1, At, B1); PG8_BAR;
;             PG8_LDA(At, 1, 1); PG8_STAGE(PG8_SA(1, 0), a3, voffA);
;             PG8_BAR; PG8_WAIT_L(0); PG8_MMA(1, 0, At, B0); PG8_BAR; PG8_SCHED;
;             PG8_STAGE(PG8_SB(1, 1), b3 + hstep, voffB);
;             PG8_WAIT_V(6); PG8_BAR; PG8_MMA(1, 1, At, B1); PG8_BAR;
	s_waitcnt lgkmcnt(3)
	v_mfma_f32_16x16x32_bf16 v[114:117], v[196:199], v[162:165], v[114:117]
	s_waitcnt lgkmcnt(1)
	v_mfma_f32_16x16x32_bf16 v[106:109], v[204:207], v[162:165], v[106:109]
	v_mfma_f32_16x16x32_bf16 v[98:101], v[196:199], v[170:173], v[98:101]
	v_mfma_f32_16x16x32_bf16 v[90:93], v[204:207], v[170:173], v[90:93]
	v_mfma_f32_16x16x32_bf16 v[82:85], v[196:199], v[180:183], v[82:85]
	v_mfma_f32_16x16x32_bf16 v[74:77], v[204:207], v[180:183], v[74:77]
	v_mfma_f32_16x16x32_bf16 v[70:73], v[196:199], v[188:191], v[70:73]
	v_mfma_f32_16x16x32_bf16 v[66:69], v[204:207], v[188:191], v[66:69]
	v_mfma_f32_16x16x32_bf16 v[114:117], v[200:203], v[166:169], v[114:117]
	s_waitcnt lgkmcnt(0)
	v_mfma_f32_16x16x32_bf16 v[106:109], v[208:211], v[166:169], v[106:109]
	v_mfma_f32_16x16x32_bf16 v[98:101], v[200:203], v[176:179], v[98:101]
	v_mfma_f32_16x16x32_bf16 v[90:93], v[208:211], v[176:179], v[90:93]
	v_mfma_f32_16x16x32_bf16 v[82:85], v[200:203], v[184:187], v[82:85]
	v_mfma_f32_16x16x32_bf16 v[74:77], v[208:211], v[184:187], v[74:77]
	v_mfma_f32_16x16x32_bf16 v[70:73], v[200:203], v[192:195], v[70:73]
	v_mfma_f32_16x16x32_bf16 v[66:69], v[208:211], v[192:195], v[66:69]
	s_mov_b32 m0, s49
	v_lshl_add_u64 v[140:141], v[214:215], 0, s[0:1]
	s_barrier
	ds_read_b128 v[162:165], v145 offset:49152
	ds_read_b128 v[166:169], v145 offset:50176
	ds_read_b128 v[170:173], v145 offset:51200
	ds_read_b128 v[176:179], v145 offset:52224
	ds_read_b128 v[180:183], v145 offset:53248
	ds_read_b128 v[184:187], v145 offset:54272
	ds_read_b128 v[188:191], v145 offset:55296
	ds_read_b128 v[192:195], v145 offset:56320
	global_load_lds_dwordx4 v[140:141], off
	v_lshl_add_u64 v[140:141], v[216:217], 0, s[0:1]
	s_mov_b32 m0, s50
	s_nop 0
	global_load_lds_dwordx4 v[140:141], off
	s_barrier
	s_waitcnt lgkmcnt(7)
	v_mfma_f32_16x16x32_bf16 v[62:65], v[146:149], v[162:165], v[62:65]
	v_mfma_f32_16x16x32_bf16 v[58:61], v[154:157], v[162:165], v[58:61]
	s_waitcnt lgkmcnt(5)
	v_mfma_f32_16x16x32_bf16 v[54:57], v[146:149], v[170:173], v[54:57]
	v_mfma_f32_16x16x32_bf16 v[44:47], v[154:157], v[170:173], v[44:47]
	s_waitcnt lgkmcnt(3)
	v_mfma_f32_16x16x32_bf16 v[36:39], v[146:149], v[180:183], v[36:39]
	v_mfma_f32_16x16x32_bf16 v[28:31], v[154:157], v[180:183], v[28:31]
	s_waitcnt lgkmcnt(1)
	v_mfma_f32_16x16x32_bf16 v[20:23], v[146:149], v[188:191], v[20:23]
	v_mfma_f32_16x16x32_bf16 v[12:15], v[154:157], v[188:191], v[12:15]
	v_mfma_f32_16x16x32_bf16 v[62:65], v[150:153], v[166:169], v[62:65]
	v_mfma_f32_16x16x32_bf16 v[58:61], v[158:161], v[166:169], v[58:61]
	v_mfma_f32_16x16x32_bf16 v[54:57], v[150:153], v[176:179], v[54:57]
	v_mfma_f32_16x16x32_bf16 v[44:47], v[158:161], v[176:179], v[44:47]
	v_mfma_f32_16x16x32_bf16 v[36:39], v[150:153], v[184:187], v[36:39]
	v_mfma_f32_16x16x32_bf16 v[28:31], v[158:161], v[184:187], v[28:31]
	s_waitcnt lgkmcnt(0)
	v_mfma_f32_16x16x32_bf16 v[20:23], v[150:153], v[192:195], v[20:23]
	v_mfma_f32_16x16x32_bf16 v[12:15], v[158:161], v[192:195], v[12:15]
	s_barrier
	s_add_u32 s34, s34, 0x40080
	s_addc_u32 s35, s35, 0
	s_add_i32 s36, s36, s13
	v_lshl_add_u64 v[140:141], s[34:35], 0, v[48:49]
	s_mov_b32 m0, s36
	s_nop 0
	global_load_lds_dwordx4 v[140:141], off
	v_lshl_add_u64 v[140:141], s[34:35], 0, v[130:131]
	s_add_i32 m0, s36, 0x2000
	s_nop 0
	global_load_lds_dwordx4 v[140:141], off
	s_waitcnt vmcnt(6)
	s_barrier
	v_mfma_f32_16x16x32_bf16 v[50:53], v[196:199], v[162:165], v[50:53]
	v_mfma_f32_16x16x32_bf16 v[40:43], v[204:207], v[162:165], v[40:43]
	v_mfma_f32_16x16x32_bf16 v[32:35], v[196:199], v[170:173], v[32:35]
	v_mfma_f32_16x16x32_bf16 v[24:27], v[204:207], v[170:173], v[24:27]
	v_mfma_f32_16x16x32_bf16 v[16:19], v[196:199], v[180:183], v[16:19]
	v_mfma_f32_16x16x32_bf16 v[8:11], v[204:207], v[180:183], v[8:11]
	v_mfma_f32_16x16x32_bf16 v[4:7], v[196:199], v[188:191], v[4:7]
	v_mfma_f32_16x16x32_bf16 v[0:3], v[204:207], v[188:191], v[0:3]
	v_mfma_f32_16x16x32_bf16 v[50:53], v[200:203], v[166:169], v[50:53]
	v_mfma_f32_16x16x32_bf16 v[40:43], v[208:211], v[166:169], v[40:43]
	v_mfma_f32_16x16x32_bf16 v[32:35], v[200:203], v[176:179], v[32:35]
	v_mfma_f32_16x16x32_bf16 v[24:27], v[208:211], v[176:179], v[24:27]
	v_mfma_f32_16x16x32_bf16 v[16:19], v[200:203], v[184:187], v[16:19]
	v_mfma_f32_16x16x32_bf16 v[8:11], v[208:211], v[184:187], v[8:11]
	v_mfma_f32_16x16x32_bf16 v[4:7], v[200:203], v[192:195], v[4:7]
	v_mfma_f32_16x16x32_bf16 v[0:3], v[208:211], v[192:195], v[0:3]
	s_add_i32 s64, s64, 2
	s_add_u32 s30, s30, 0x100
	s_addc_u32 s31, s31, 0
	s_add_u32 s59, s59, 0x100
	s_addc_u32 s63, s63, 0
	s_cmp_gt_u32 s64, 13
	s_barrier
	s_cbranch_scc1 .Lkpeel_exit_320
; #define PG8_STAGE(bufoff, gbase, voff) do { _Pragma("unroll") for (int _i = 0; _i < 2; ++_i) \
;         __builtin_amdgcn_global_load_lds((const unsigned*)((const char*)(gbase) + (voff)[_i]), (PG8_LAS unsigned*)(lds + (bufoff) + ldsw + _i * 8192), 16, 0, 0); } while (0)
; #define PG8_LDA(dst, b, h) do { _Pragma("unroll") for (int m = 0; m < 4; ++m) _Pragma("unroll") for (int k = 0; k < 2; ++k) dst[m][k] = *(const PG8_LAS bf16x8*)(lds + PG8_SA(b, h) + aoff + m * 2048 + k * 1024); } while (0)
; #define PG8_LDB(dst, b, h) do { _Pragma("unroll") for (int n = 0; n < 2; ++n) _Pragma("unroll") for (int k = 0; k < 2; ++k) dst[n][k] = *(const PG8_LAS bf16x8*)(lds + PG8_SB(b, h) + boff + n * 2048 + k * 1024); } while (0)
; #define PG8_MMA(ai, bj, At, Bt) do { __builtin_amdgcn_s_setprio(1); _Pragma("unroll") for (int m = 0; m < 4; ++m) _Pragma("unroll") for (int n = 0; n < 2; ++n) _Pragma("unroll") for (int k = 0; k < 2; ++k) \
;         acc[ai][bj][m][n] = __builtin_amdgcn_mfma_f32_16x16x32_bf16(Bt[n][k], At[m][k], acc[ai][bj][m][n], 0, 0, 0); __builtin_amdgcn_s_setprio(0); } while (0)
; #define PG8_WAIT_V(n) asm volatile("s_waitcnt vmcnt(" #n ")" ::: "memory")
; #define PG8_WAIT_L(n) asm volatile("s_waitcnt lgkmcnt(" #n ")" ::: "memory")
; #define PG8_BAR __builtin_amdgcn_s_barrier()
; #define PG8_SCHED __builtin_amdgcn_sched_barrier(0)
; template <class Epi, class Sched>
; __device__ __forceinline__ void gemm_phase(PG8_LAS unsigned char* lds, const Gemm g, const Sched& S, const Epi& E) {
;     ...
;             PG8_LDB(B0, 0, 0); PG8_SCHED; PG8_LDA(At, 0, 0); PG8_STAGE(PG8_SA(1, 1), a1 + hstep, voffA);
;             PG8_WAIT_L(8); PG8_BAR; PG8_WAIT_L(0); PG8_MMA(0, 0, At, B0); PG8_BAR; PG8_SCHED;
;             PG8_LDB(B1, 0, 1); PG8_STAGE(PG8_SB(0, 0), b2, voffB);
;             PG8_BAR; PG8_WAIT_L(0); PG8_MMA(0, 1, At, B1); PG8_BAR;
;             PG8_LDA(At, 0, 1); PG8_STAGE(PG8_SA(0, 0), a2, voffA);
;             PG8_BAR; PG8_WAIT_L(0); PG8_MMA(1, 0, At, B0); PG8_BAR; PG8_SCHED;
;             PG8_STAGE(PG8_SB(0, 1), b2 + hstep, voffB);
;             PG8_WAIT_V(6); PG8_BAR; PG8_MMA(1, 1, At, B1); PG8_BAR;
;             PG8_LDB(B0, 1, 0); PG8_SCHED; PG8_LDA(At, 1, 0); PG8_STAGE(PG8_SA(0, 1), a2 + hstep, voffA);
;             PG8_WAIT_L(8); PG8_BAR; PG8_WAIT_L(0); PG8_MMA(0, 0, At, B0); PG8_BAR; PG8_SCHED;
.LBB0_320:
	s_add_u32 s34, s30, 0xfffc0080
	s_addc_u32 s35, s31, -1
	s_add_i32 s65, 0, 0x10000
	v_add_u32_e32 v140, s65, v143
	ds_read_b128 v[146:149], v140
	ds_read_b128 v[150:153], v140 offset:1024
	ds_read_b128 v[154:157], v140 offset:2048
	ds_read_b128 v[158:161], v140 offset:3072
	s_cmp_eq_u32 s64, 12
	s_cselect_b32 s37, s25, s35
	s_cselect_b32 s36, s56, s34
	s_cselect_b32 s35, s23, s63
	s_cselect_b32 s34, s57, s59
	v_lshl_add_u64 v[140:141], s[30:31], 0, v[136:137]
	s_add_i32 m0, s21, 0xc000
	ds_read_b128 v[162:165], v145
	ds_read_b128 v[166:169], v145 offset:1024
	ds_read_b128 v[170:173], v145 offset:2048
	ds_read_b128 v[176:179], v145 offset:3072
	ds_read_b128 v[180:183], v145 offset:4096
	ds_read_b128 v[184:187], v145 offset:5120
	ds_read_b128 v[188:191], v145 offset:6144
	ds_read_b128 v[192:195], v145 offset:7168
	global_load_lds_dwordx4 v[140:141], off
	v_lshl_add_u64 v[140:141], s[30:31], 0, v[138:139]
	s_add_i32 m0, s21, 0xe000
	s_nop 0
	global_load_lds_dwordx4 v[140:141], off
	s_waitcnt lgkmcnt(8)
	s_barrier
	s_waitcnt lgkmcnt(7)
	v_mfma_f32_16x16x32_bf16 v[126:129], v[146:149], v[162:165], v[126:129]
	v_mfma_f32_16x16x32_bf16 v[122:125], v[154:157], v[162:165], v[122:125]
	s_waitcnt lgkmcnt(5)
	v_mfma_f32_16x16x32_bf16 v[118:121], v[146:149], v[170:173], v[118:121]
	v_mfma_f32_16x16x32_bf16 v[110:113], v[154:157], v[170:173], v[110:113]
	s_waitcnt lgkmcnt(3)
	v_mfma_f32_16x16x32_bf16 v[102:105], v[146:149], v[180:183], v[102:105]
	v_mfma_f32_16x16x32_bf16 v[94:97], v[154:157], v[180:183], v[94:97]
	s_waitcnt lgkmcnt(1)
	v_mfma_f32_16x16x32_bf16 v[86:89], v[146:149], v[188:191], v[86:89]
	v_mfma_f32_16x16x32_bf16 v[78:81], v[154:157], v[188:191], v[78:81]
	v_mfma_f32_16x16x32_bf16 v[126:129], v[150:153], v[166:169], v[126:129]
	v_mfma_f32_16x16x32_bf16 v[122:125], v[158:161], v[166:169], v[122:125]
	v_mfma_f32_16x16x32_bf16 v[118:121], v[150:153], v[176:179], v[118:121]
	v_mfma_f32_16x16x32_bf16 v[110:113], v[158:161], v[176:179], v[110:113]
	v_mfma_f32_16x16x32_bf16 v[102:105], v[150:153], v[184:187], v[102:105]
	v_mfma_f32_16x16x32_bf16 v[94:97], v[158:161], v[184:187], v[94:97]
	s_waitcnt lgkmcnt(0)
	v_mfma_f32_16x16x32_bf16 v[86:89], v[150:153], v[192:195], v[86:89]
	v_mfma_f32_16x16x32_bf16 v[78:81], v[158:161], v[192:195], v[78:81]
	s_barrier
	s_add_i32 s68, 0, 0x14000
	v_add_u32_e32 v140, s68, v143
	s_add_i32 s65, s65, s13
	ds_read_b128 v[196:199], v140
	ds_read_b128 v[200:203], v140 offset:1024
	ds_read_b128 v[204:207], v140 offset:2048
	ds_read_b128 v[208:211], v140 offset:3072
	v_lshl_add_u64 v[140:141], s[34:35], 0, v[48:49]
	s_mov_b32 m0, s65
	v_lshl_add_u64 v[212:213], s[34:35], 0, v[130:131]
	global_load_lds_dwordx4 v[140:141], off
	s_add_i32 m0, s65, 0x2000
	s_nop 0
	global_load_lds_dwordx4 v[212:213], off
	s_barrier
	s_waitcnt lgkmcnt(3)
	v_mfma_f32_16x16x32_bf16 v[114:117], v[196:199], v[162:165], v[114:117]
	s_waitcnt lgkmcnt(1)
	v_mfma_f32_16x16x32_bf16 v[106:109], v[204:207], v[162:165], v[106:109]
	v_mfma_f32_16x16x32_bf16 v[98:101], v[196:199], v[170:173], v[98:101]
	v_mfma_f32_16x16x32_bf16 v[90:93], v[204:207], v[170:173], v[90:93]
	v_mfma_f32_16x16x32_bf16 v[82:85], v[196:199], v[180:183], v[82:85]
	v_mfma_f32_16x16x32_bf16 v[74:77], v[204:207], v[180:183], v[74:77]
	v_mfma_f32_16x16x32_bf16 v[70:73], v[196:199], v[188:191], v[70:73]
	v_mfma_f32_16x16x32_bf16 v[66:69], v[204:207], v[188:191], v[66:69]
	v_mfma_f32_16x16x32_bf16 v[114:117], v[200:203], v[166:169], v[114:117]
	s_waitcnt lgkmcnt(0)
	v_mfma_f32_16x16x32_bf16 v[106:109], v[208:211], v[166:169], v[106:109]
	v_mfma_f32_16x16x32_bf16 v[98:101], v[200:203], v[176:179], v[98:101]
	v_mfma_f32_16x16x32_bf16 v[90:93], v[208:211], v[176:179], v[90:93]
	v_mfma_f32_16x16x32_bf16 v[82:85], v[200:203], v[184:187], v[82:85]
	v_mfma_f32_16x16x32_bf16 v[74:77], v[208:211], v[184:187], v[74:77]
	v_mfma_f32_16x16x32_bf16 v[70:73], v[200:203], v[192:195], v[70:73]
	v_mfma_f32_16x16x32_bf16 v[66:69], v[208:211], v[192:195], v[66:69]
	s_mov_b32 m0, s21
	v_lshl_add_u64 v[214:215], s[36:37], 0, v[134:135]
	s_barrier
	ds_read_b128 v[162:165], v145 offset:16384
	ds_read_b128 v[166:169], v145 offset:17408
	ds_read_b128 v[170:173], v145 offset:18432
	ds_read_b128 v[176:179], v145 offset:19456
	ds_read_b128 v[180:183], v145 offset:20480
	ds_read_b128 v[184:187], v145 offset:21504
	ds_read_b128 v[188:191], v145 offset:22528
	ds_read_b128 v[192:195], v145 offset:23552
	global_load_lds_dwordx4 v[214:215], off
	v_lshl_add_u64 v[216:217], s[36:37], 0, v[132:133]
	s_mov_b32 m0, s46
	s_nop 0
	global_load_lds_dwordx4 v[216:217], off
	s_barrier
	s_waitcnt lgkmcnt(7)
	v_mfma_f32_16x16x32_bf16 v[62:65], v[146:149], v[162:165], v[62:65]
	v_mfma_f32_16x16x32_bf16 v[58:61], v[154:157], v[162:165], v[58:61]
	s_waitcnt lgkmcnt(5)
	v_mfma_f32_16x16x32_bf16 v[54:57], v[146:149], v[170:173], v[54:57]
	v_mfma_f32_16x16x32_bf16 v[44:47], v[154:157], v[170:173], v[44:47]
	s_waitcnt lgkmcnt(3)
	v_mfma_f32_16x16x32_bf16 v[36:39], v[146:149], v[180:183], v[36:39]
	v_mfma_f32_16x16x32_bf16 v[28:31], v[154:157], v[180:183], v[28:31]
	s_waitcnt lgkmcnt(1)
	v_mfma_f32_16x16x32_bf16 v[20:23], v[146:149], v[188:191], v[20:23]
	v_mfma_f32_16x16x32_bf16 v[12:15], v[154:157], v[188:191], v[12:15]
	v_mfma_f32_16x16x32_bf16 v[62:65], v[150:153], v[166:169], v[62:65]
	v_mfma_f32_16x16x32_bf16 v[58:61], v[158:161], v[166:169], v[58:61]
	v_mfma_f32_16x16x32_bf16 v[54:57], v[150:153], v[176:179], v[54:57]
	v_mfma_f32_16x16x32_bf16 v[44:47], v[158:161], v[176:179], v[44:47]
	v_mfma_f32_16x16x32_bf16 v[36:39], v[150:153], v[184:187], v[36:39]
	v_mfma_f32_16x16x32_bf16 v[28:31], v[158:161], v[184:187], v[28:31]
	s_waitcnt lgkmcnt(0)
	v_mfma_f32_16x16x32_bf16 v[20:23], v[150:153], v[192:195], v[20:23]
	v_mfma_f32_16x16x32_bf16 v[12:15], v[158:161], v[192:195], v[12:15]
	s_barrier
; #define PG8_STAGE(bufoff, gbase, voff) do { _Pragma("unroll") for (int _i = 0; _i < 2; ++_i) \
;         __builtin_amdgcn_global_load_lds((const unsigned*)((const char*)(gbase) + (voff)[_i]), (PG8_LAS unsigned*)(lds + (bufoff) + ldsw + _i * 8192), 16, 0, 0); } while (0)
; #define PG8_LDA(dst, b, h) do { _Pragma("unroll") for (int m = 0; m < 4; ++m) _Pragma("unroll") for (int k = 0; k < 2; ++k) dst[m][k] = *(const PG8_LAS bf16x8*)(lds + PG8_SA(b, h) + aoff + m * 2048 + k * 1024); } while (0)
; #define PG8_LDB(dst, b, h) do { _Pragma("unroll") for (int n = 0; n < 2; ++n) _Pragma("unroll") for (int k = 0; k < 2; ++k) dst[n][k] = *(const PG8_LAS bf16x8*)(lds + PG8_SB(b, h) + boff + n * 2048 + k * 1024); } while (0)
; #define PG8_MMA(ai, bj, At, Bt) do { __builtin_amdgcn_s_setprio(1); _Pragma("unroll") for (int m = 0; m < 4; ++m) _Pragma("unroll") for (int n = 0; n < 2; ++n) _Pragma("unroll") for (int k = 0; k < 2; ++k) \
;         acc[ai][bj][m][n] = __builtin_amdgcn_mfma_f32_16x16x32_bf16(Bt[n][k], At[m][k], acc[ai][bj][m][n], 0, 0, 0); __builtin_amdgcn_s_setprio(0); } while (0)
; #define PG8_WAIT_V(n) asm volatile("s_waitcnt vmcnt(" #n ")" ::: "memory")
; #define PG8_WAIT_L(n) asm volatile("s_waitcnt lgkmcnt(" #n ")" ::: "memory")
; #define PG8_BAR __builtin_amdgcn_s_barrier()
; #define PG8_SCHED __builtin_amdgcn_sched_barrier(0)
; template <class Epi, class Sched>
; __device__ __forceinline__ void gemm_phase(PG8_LAS unsigned char* lds, const Gemm g, const Sched& S, const Epi& E) {
;     ...
;             PG8_STAGE(PG8_SB(0, 1), b2 + hstep, voffB);
;             PG8_WAIT_V(6); PG8_BAR; PG8_MMA(1, 1, At, B1); PG8_BAR;
;             PG8_LDB(B0, 1, 0); PG8_SCHED; PG8_LDA(At, 1, 0); PG8_STAGE(PG8_SA(0, 1), a2 + hstep, voffA);
;             PG8_WAIT_L(8); PG8_BAR; PG8_WAIT_L(0); PG8_MMA(0, 0, At, B0); PG8_BAR; PG8_SCHED;
;             PG8_LDB(B1, 1, 1); PG8_STAGE(PG8_SB(1, 0), b3, voffB);
	s_add_u32 s66, s34, 0x40000
	s_addc_u32 s67, s35, 0
	s_add_i32 s65, s68, s13
	v_lshl_add_u64 v[146:147], s[66:67], 0, v[48:49]
	s_mov_b32 m0, s65
	s_nop 0
	global_load_lds_dwordx4 v[146:147], off
	v_lshl_add_u64 v[146:147], s[66:67], 0, v[130:131]
	s_add_i32 m0, s65, 0x2000
	s_nop 0
	global_load_lds_dwordx4 v[146:147], off
	s_waitcnt vmcnt(6)
	s_barrier
	v_mfma_f32_16x16x32_bf16 v[50:53], v[196:199], v[162:165], v[50:53]
	v_mfma_f32_16x16x32_bf16 v[40:43], v[204:207], v[162:165], v[40:43]
	v_mfma_f32_16x16x32_bf16 v[32:35], v[196:199], v[170:173], v[32:35]
	v_mfma_f32_16x16x32_bf16 v[24:27], v[204:207], v[170:173], v[24:27]
	v_mfma_f32_16x16x32_bf16 v[16:19], v[196:199], v[180:183], v[16:19]
	v_mfma_f32_16x16x32_bf16 v[8:11], v[204:207], v[180:183], v[8:11]
	v_mfma_f32_16x16x32_bf16 v[4:7], v[196:199], v[188:191], v[4:7]
	v_mfma_f32_16x16x32_bf16 v[0:3], v[204:207], v[188:191], v[0:3]
	v_mfma_f32_16x16x32_bf16 v[50:53], v[200:203], v[166:169], v[50:53]
	v_mfma_f32_16x16x32_bf16 v[40:43], v[208:211], v[166:169], v[40:43]
	v_mfma_f32_16x16x32_bf16 v[32:35], v[200:203], v[176:179], v[32:35]
	v_mfma_f32_16x16x32_bf16 v[24:27], v[208:211], v[176:179], v[24:27]
	v_mfma_f32_16x16x32_bf16 v[16:19], v[200:203], v[184:187], v[16:19]
	v_mfma_f32_16x16x32_bf16 v[8:11], v[208:211], v[184:187], v[8:11]
	v_mfma_f32_16x16x32_bf16 v[4:7], v[200:203], v[192:195], v[4:7]
	v_mfma_f32_16x16x32_bf16 v[0:3], v[208:211], v[192:195], v[0:3]
	s_add_i32 s65, 0, 0x18000
	v_add_u32_e32 v158, s65, v143
	s_barrier
	ds_read_b128 v[146:149], v158
	ds_read_b128 v[150:153], v158 offset:1024
	ds_read_b128 v[154:157], v158 offset:2048
	ds_read_b128 v[158:161], v158 offset:3072
	s_add_u32 s36, s36, 0x40000
	s_addc_u32 s37, s37, 0
	s_mov_b32 m0, s47
	v_lshl_add_u64 v[196:197], s[36:37], 0, v[134:135]
	ds_read_b128 v[162:165], v145 offset:32768
	ds_read_b128 v[166:169], v145 offset:33792
	ds_read_b128 v[170:173], v145 offset:34816
	ds_read_b128 v[176:179], v145 offset:35840
	ds_read_b128 v[180:183], v145 offset:36864
	ds_read_b128 v[184:187], v145 offset:37888
	ds_read_b128 v[188:191], v145 offset:38912
	ds_read_b128 v[192:195], v145 offset:39936
	global_load_lds_dwordx4 v[196:197], off
	v_lshl_add_u64 v[196:197], s[36:37], 0, v[132:133]
	s_mov_b32 m0, s48
	s_nop 0
	global_load_lds_dwordx4 v[196:197], off
	s_waitcnt lgkmcnt(8)
	s_barrier
	s_waitcnt lgkmcnt(7)
	v_mfma_f32_16x16x32_bf16 v[126:129], v[146:149], v[162:165], v[126:129]
	v_mfma_f32_16x16x32_bf16 v[122:125], v[154:157], v[162:165], v[122:125]
	s_waitcnt lgkmcnt(5)
	v_mfma_f32_16x16x32_bf16 v[118:121], v[146:149], v[170:173], v[118:121]
	v_mfma_f32_16x16x32_bf16 v[110:113], v[154:157], v[170:173], v[110:113]
	s_waitcnt lgkmcnt(3)
	v_mfma_f32_16x16x32_bf16 v[102:105], v[146:149], v[180:183], v[102:105]
	v_mfma_f32_16x16x32_bf16 v[94:97], v[154:157], v[180:183], v[94:97]
	s_waitcnt lgkmcnt(1)
	v_mfma_f32_16x16x32_bf16 v[86:89], v[146:149], v[188:191], v[86:89]
	v_mfma_f32_16x16x32_bf16 v[78:81], v[154:157], v[188:191], v[78:81]
	v_mfma_f32_16x16x32_bf16 v[126:129], v[150:153], v[166:169], v[126:129]
	v_mfma_f32_16x16x32_bf16 v[122:125], v[158:161], v[166:169], v[122:125]
	v_mfma_f32_16x16x32_bf16 v[118:121], v[150:153], v[176:179], v[118:121]
	v_mfma_f32_16x16x32_bf16 v[110:113], v[158:161], v[176:179], v[110:113]
	v_mfma_f32_16x16x32_bf16 v[102:105], v[150:153], v[184:187], v[102:105]
	v_mfma_f32_16x16x32_bf16 v[94:97], v[158:161], v[184:187], v[94:97]
	s_waitcnt lgkmcnt(0)
	v_mfma_f32_16x16x32_bf16 v[86:89], v[150:153], v[192:195], v[86:89]
	v_mfma_f32_16x16x32_bf16 v[78:81], v[158:161], v[192:195], v[78:81]
	s_barrier
	s_add_i32 s36, 0, 0x1c000
	s_add_i32 s37, s65, s13
	v_add_u32_e32 v175, s36, v143
	v_lshl_add_u64 v[140:141], v[140:141], 0, s[0:1]
	s_mov_b32 m0, s37
	ds_read_b128 v[196:199], v175
	ds_read_b128 v[200:203], v175 offset:1024
	ds_read_b128 v[204:207], v175 offset:2048
	ds_read_b128 v[208:211], v175 offset:3072
	global_load_lds_dwordx4 v[140:141], off
	v_lshl_add_u64 v[140:141], v[212:213], 0, s[0:1]
	s_add_i32 m0, s37, 0x2000
	s_nop 0
	global_load_lds_dwordx4 v[140:141], off
	s_barrier
; #define PG8_STAGE(bufoff, gbase, voff) do { _Pragma("unroll") for (int _i = 0; _i < 2; ++_i) \
;         __builtin_amdgcn_global_load_lds((const unsigned*)((const char*)(gbase) + (voff)[_i]), (PG8_LAS unsigned*)(lds + (bufoff) + ldsw + _i * 8192), 16, 0, 0); } while (0)
; #define PG8_LDA(dst, b, h) do { _Pragma("unroll") for (int m = 0; m < 4; ++m) _Pragma("unroll") for (int k = 0; k < 2; ++k) dst[m][k] = *(const PG8_LAS bf16x8*)(lds + PG8_SA(b, h) + aoff + m * 2048 + k * 1024); } while (0)
; #define PG8_MMA(ai, bj, At, Bt) do { __builtin_amdgcn_s_setprio(1); _Pragma("unroll") for (int m = 0; m < 4; ++m) _Pragma("unroll") for (int n = 0; n < 2; ++n) _Pragma("unroll") for (int k = 0; k < 2; ++k) \
;         acc[ai][bj][m][n] = __builtin_amdgcn_mfma_f32_16x16x32_bf16(Bt[n][k], At[m][k], acc[ai][bj][m][n], 0, 0, 0); __builtin_amdgcn_s_setprio(0); } while (0)
; #define PG8_WAIT_V(n) asm volatile("s_waitcnt vmcnt(" #n ")" ::: "memory")
; #define PG8_WAIT_L(n) asm volatile("s_waitcnt lgkmcnt(" #n ")" ::: "memory")
; #define PG8_BAR __builtin_amdgcn_s_barrier()
; #define PG8_SCHED __builtin_amdgcn_sched_barrier(0)
; template <class Epi, class Sched>
; __device__ __forceinline__ void gemm_phase(PG8_LAS unsigned char* lds, const Gemm g, const Sched& S, const Epi& E) {
;     ...
;             PG8_BAR; PG8_WAIT_L(0); PG8_MMA(0, 1, At, B1); PG8_BAR;
;             PG8_LDA(At, 1, 1); PG8_STAGE(PG8_SA(1, 0), a3, voffA);
;             PG8_BAR; PG8_WAIT_L(0); PG8_MMA(1, 0, At, B0); PG8_BAR; PG8_SCHED;
;             PG8_STAGE(PG8_SB(1, 1), b3 + hstep, voffB);
;             PG8_WAIT_V(6); PG8_BAR; PG8_MMA(1, 1, At, B1); PG8_BAR;
	s_waitcnt lgkmcnt(3)
	v_mfma_f32_16x16x32_bf16 v[114:117], v[196:199], v[162:165], v[114:117]
	s_waitcnt lgkmcnt(1)
	v_mfma_f32_16x16x32_bf16 v[106:109], v[204:207], v[162:165], v[106:109]
	v_mfma_f32_16x16x32_bf16 v[98:101], v[196:199], v[170:173], v[98:101]
	v_mfma_f32_16x16x32_bf16 v[90:93], v[204:207], v[170:173], v[90:93]
	v_mfma_f32_16x16x32_bf16 v[82:85], v[196:199], v[180:183], v[82:85]
	v_mfma_f32_16x16x32_bf16 v[74:77], v[204:207], v[180:183], v[74:77]
	v_mfma_f32_16x16x32_bf16 v[70:73], v[196:199], v[188:191], v[70:73]
	v_mfma_f32_16x16x32_bf16 v[66:69], v[204:207], v[188:191], v[66:69]
	v_mfma_f32_16x16x32_bf16 v[114:117], v[200:203], v[166:169], v[114:117]
	s_waitcnt lgkmcnt(0)
	v_mfma_f32_16x16x32_bf16 v[106:109], v[208:211], v[166:169], v[106:109]
	v_mfma_f32_16x16x32_bf16 v[98:101], v[200:203], v[176:179], v[98:101]
	v_mfma_f32_16x16x32_bf16 v[90:93], v[208:211], v[176:179], v[90:93]
	v_mfma_f32_16x16x32_bf16 v[82:85], v[200:203], v[184:187], v[82:85]
	v_mfma_f32_16x16x32_bf16 v[74:77], v[208:211], v[184:187], v[74:77]
	v_mfma_f32_16x16x32_bf16 v[70:73], v[200:203], v[192:195], v[70:73]
	v_mfma_f32_16x16x32_bf16 v[66:69], v[208:211], v[192:195], v[66:69]
	s_mov_b32 m0, s49
	v_lshl_add_u64 v[140:141], v[214:215], 0, s[0:1]
	s_barrier
	ds_read_b128 v[162:165], v145 offset:49152
	ds_read_b128 v[166:169], v145 offset:50176
	ds_read_b128 v[170:173], v145 offset:51200
	ds_read_b128 v[176:179], v145 offset:52224
	ds_read_b128 v[180:183], v145 offset:53248
	ds_read_b128 v[184:187], v145 offset:54272
	ds_read_b128 v[188:191], v145 offset:55296
	ds_read_b128 v[192:195], v145 offset:56320
	global_load_lds_dwordx4 v[140:141], off
	v_lshl_add_u64 v[140:141], v[216:217], 0, s[0:1]
	s_mov_b32 m0, s50
	s_nop 0
	global_load_lds_dwordx4 v[140:141], off
	s_barrier
	s_waitcnt lgkmcnt(7)
	v_mfma_f32_16x16x32_bf16 v[62:65], v[146:149], v[162:165], v[62:65]
	v_mfma_f32_16x16x32_bf16 v[58:61], v[154:157], v[162:165], v[58:61]
	s_waitcnt lgkmcnt(5)
	v_mfma_f32_16x16x32_bf16 v[54:57], v[146:149], v[170:173], v[54:57]
	v_mfma_f32_16x16x32_bf16 v[44:47], v[154:157], v[170:173], v[44:47]
	s_waitcnt lgkmcnt(3)
	v_mfma_f32_16x16x32_bf16 v[36:39], v[146:149], v[180:183], v[36:39]
	v_mfma_f32_16x16x32_bf16 v[28:31], v[154:157], v[180:183], v[28:31]
	s_waitcnt lgkmcnt(1)
	v_mfma_f32_16x16x32_bf16 v[20:23], v[146:149], v[188:191], v[20:23]
	v_mfma_f32_16x16x32_bf16 v[12:15], v[154:157], v[188:191], v[12:15]
	v_mfma_f32_16x16x32_bf16 v[62:65], v[150:153], v[166:169], v[62:65]
	v_mfma_f32_16x16x32_bf16 v[58:61], v[158:161], v[166:169], v[58:61]
	v_mfma_f32_16x16x32_bf16 v[54:57], v[150:153], v[176:179], v[54:57]
	v_mfma_f32_16x16x32_bf16 v[44:47], v[158:161], v[176:179], v[44:47]
	v_mfma_f32_16x16x32_bf16 v[36:39], v[150:153], v[184:187], v[36:39]
	v_mfma_f32_16x16x32_bf16 v[28:31], v[158:161], v[184:187], v[28:31]
	s_waitcnt lgkmcnt(0)
	v_mfma_f32_16x16x32_bf16 v[20:23], v[150:153], v[192:195], v[20:23]
	v_mfma_f32_16x16x32_bf16 v[12:15], v[158:161], v[192:195], v[12:15]
	s_barrier
	s_add_u32 s34, s34, 0x40080
	s_addc_u32 s35, s35, 0
	s_add_i32 s36, s36, s13
	v_lshl_add_u64 v[140:141], s[34:35], 0, v[48:49]
	s_mov_b32 m0, s36
	s_nop 0
	global_load_lds_dwordx4 v[140:141], off
	v_lshl_add_u64 v[140:141], s[34:35], 0, v[130:131]
	s_add_i32 m0, s36, 0x2000
	s_nop 0
	global_load_lds_dwordx4 v[140:141], off
	s_waitcnt vmcnt(6)
	s_barrier
	v_mfma_f32_16x16x32_bf16 v[50:53], v[196:199], v[162:165], v[50:53]
	v_mfma_f32_16x16x32_bf16 v[40:43], v[204:207], v[162:165], v[40:43]
	v_mfma_f32_16x16x32_bf16 v[32:35], v[196:199], v[170:173], v[32:35]
	v_mfma_f32_16x16x32_bf16 v[24:27], v[204:207], v[170:173], v[24:27]
	v_mfma_f32_16x16x32_bf16 v[16:19], v[196:199], v[180:183], v[16:19]
	v_mfma_f32_16x16x32_bf16 v[8:11], v[204:207], v[180:183], v[8:11]
	v_mfma_f32_16x16x32_bf16 v[4:7], v[196:199], v[188:191], v[4:7]
	v_mfma_f32_16x16x32_bf16 v[0:3], v[204:207], v[188:191], v[0:3]
	v_mfma_f32_16x16x32_bf16 v[50:53], v[200:203], v[166:169], v[50:53]
	v_mfma_f32_16x16x32_bf16 v[40:43], v[208:211], v[166:169], v[40:43]
	v_mfma_f32_16x16x32_bf16 v[32:35], v[200:203], v[176:179], v[32:35]
	v_mfma_f32_16x16x32_bf16 v[24:27], v[208:211], v[176:179], v[24:27]
	v_mfma_f32_16x16x32_bf16 v[16:19], v[200:203], v[184:187], v[16:19]
	v_mfma_f32_16x16x32_bf16 v[8:11], v[208:211], v[184:187], v[8:11]
	v_mfma_f32_16x16x32_bf16 v[4:7], v[200:203], v[192:195], v[4:7]
	v_mfma_f32_16x16x32_bf16 v[0:3], v[208:211], v[192:195], v[0:3]
	s_add_i32 s64, s64, 2
	s_add_u32 s30, s30, 0x100
	s_addc_u32 s31, s31, 0
	s_add_u32 s59, s59, 0x100
	s_addc_u32 s63, s63, 0
	s_cmp_gt_u32 s64, 13
	s_barrier
	s_cbranch_scc0 .LBB0_320

; #define PG8_STAGE(bufoff, gbase, voff) do { _Pragma("unroll") for (int _i = 0; _i < 2; ++_i) \
;         __builtin_amdgcn_global_load_lds((const unsigned*)((const char*)(gbase) + (voff)[_i]), (PG8_LAS unsigned*)(lds + (bufoff) + ldsw + _i * 8192), 16, 0, 0); } while (0)
; #define PG8_LDA(dst, b, h) do { _Pragma("unroll") for (int m = 0; m < 4; ++m) _Pragma("unroll") for (int k = 0; k < 2; ++k) dst[m][k] = *(const PG8_LAS bf16x8*)(lds + PG8_SA(b, h) + aoff + m * 2048 + k * 1024); } while (0)
; #define PG8_LDB(dst, b, h) do { _Pragma("unroll") for (int n = 0; n < 2; ++n) _Pragma("unroll") for (int k = 0; k < 2; ++k) dst[n][k] = *(const PG8_LAS bf16x8*)(lds + PG8_SB(b, h) + boff + n * 2048 + k * 1024); } while (0)
; #define PG8_WAIT_L(n) asm volatile("s_waitcnt lgkmcnt(" #n ")" ::: "memory")
; #define PG8_BAR __builtin_amdgcn_s_barrier()
; #define PG8_SCHED __builtin_amdgcn_sched_barrier(0)
; template <class Epi, class Sched>
; __device__ __forceinline__ void gemm_phase(PG8_LAS unsigned char* lds, const Gemm g, const Sched& S, const Epi& E) {
;     ...
;         const bool has_next = S.next(ui + 1, nxt);
;         const char* nA = has_next ? (const char*)g.A + (size_t)nxt.pm * tstepA + (size_t)nxt.kc * cstep : cA; const char* nB = has_next ? (const char*)g.Bt + (size_t)nxt.pn * tstep + (size_t)nxt.kc * cstep : cB;
;         for (int t = 0; t < nt; t += 2) {
;             const bool last = (t == nt - 2);
;             const char* a1 = cA + (size_t)(t + 1) * kstep;
;             const char* a2 = last ? nA : cA + (size_t)(t + 2) * kstep; const char* b2 = last ? nB : cB + (size_t)(t + 2) * kstep;
;             const char* a3 = a2 + kstep; const char* b3 = b2 + kstep;
;             if (last && has_next) S.a_ready(nxt);
;             PG8_LDB(B0, 0, 0); PG8_SCHED; PG8_LDA(At, 0, 0); PG8_STAGE(PG8_SA(1, 1), a1 + hstep, voffA);
;             PG8_WAIT_L(8); PG8_BAR; PG8_WAIT_L(0); PG8_MMA(0, 0, At, B0); PG8_BAR; PG8_SCHED;
;             PG8_LDB(B1, 0, 1); PG8_STAGE(PG8_SB(0, 0), b2, voffB);
;             PG8_BAR; PG8_WAIT_L(0); PG8_MMA(0, 1, At, B1); PG8_BAR;
;             PG8_LDA(At, 0, 1); PG8_STAGE(PG8_SA(0, 0), a2, voffA);
;             PG8_BAR; PG8_WAIT_L(0); PG8_MMA(1, 0, At, B0); PG8_BAR; PG8_SCHED;
.LBB0_334:
	v_mov_b64_e32 v[0:1], 0x440
	s_ashr_i32 s23, s22, 31
	v_cmp_lt_i64_e32 vcc, s[16:17], v[0:1]
	s_lshl_b64 s[16:17], s[22:23], 19
	s_add_u32 s24, s28, s16
	s_addc_u32 s25, s29, s17
	s_and_b64 s[16:17], vcc, exec
	s_cselect_b32 s23, s25, s7
	s_cselect_b32 s50, s24, s6
	s_ashr_i32 s21, s20, 31
	s_lshl_b64 s[16:17], s[20:21], 19
	s_add_u32 s26, s30, s16
	s_addc_u32 s27, s31, s17
	s_and_b64 s[16:17], vcc, exec
	s_cselect_b32 s21, s27, s13
	s_cselect_b32 s51, s26, s12
	s_add_u32 s6, s6, 0x40080
	s_addc_u32 s7, s7, 0
	s_add_u32 s54, s12, 0x100
	s_addc_u32 s55, s13, 0
	s_mov_b32 s56, -2
	s_add_u32 s12, s6, 0xfffc0080
	s_addc_u32 s13, s7, -1
	s_add_i32 s57, 0, 0x10000
	v_add_u32_e32 v48, s57, v166
	ds_read_b128 v[144:147], v48
	ds_read_b128 v[148:151], v48 offset:1024
	ds_read_b128 v[152:155], v48 offset:2048
	ds_read_b128 v[156:159], v48 offset:3072
	s_cmp_eq_u32 s56, 12
	s_cselect_b32 s17, s23, s13
	s_cselect_b32 s16, s50, s12
	s_cselect_b32 s13, s21, s55
	s_cselect_b32 s12, s51, s54
	v_lshl_add_u64 v[164:165], s[6:7], 0, v[140:141]
	s_add_i32 m0, s3, 0xc000
	ds_read_b128 v[160:163], v167
	ds_read_b128 v[168:171], v167 offset:1024
	ds_read_b128 v[176:179], v167 offset:2048
	ds_read_b128 v[180:183], v167 offset:3072
	ds_read_b128 v[184:187], v167 offset:4096
	ds_read_b128 v[188:191], v167 offset:5120
	ds_read_b128 v[192:195], v167 offset:6144
	ds_read_b128 v[196:199], v167 offset:7168
	global_load_lds_dwordx4 v[164:165], off
	v_lshl_add_u64 v[164:165], s[6:7], 0, v[142:143]
	s_add_i32 m0, s3, 0xe000
	s_nop 0
	global_load_lds_dwordx4 v[164:165], off
	s_waitcnt lgkmcnt(8)
	s_barrier
	s_waitcnt lgkmcnt(7)
	v_mfma_f32_16x16x32_bf16 v[126:129], v[144:147], v[160:163], 0
	v_mfma_f32_16x16x32_bf16 v[122:125], v[152:155], v[160:163], 0
	s_waitcnt lgkmcnt(5)
	v_mfma_f32_16x16x32_bf16 v[110:113], v[144:147], v[176:179], 0
	v_mfma_f32_16x16x32_bf16 v[106:109], v[152:155], v[176:179], 0
	s_waitcnt lgkmcnt(3)
	v_mfma_f32_16x16x32_bf16 v[94:97], v[144:147], v[184:187], 0
	v_mfma_f32_16x16x32_bf16 v[90:93], v[152:155], v[184:187], 0
	s_waitcnt lgkmcnt(1)
	v_mfma_f32_16x16x32_bf16 v[78:81], v[144:147], v[192:195], 0
	v_mfma_f32_16x16x32_bf16 v[74:77], v[152:155], v[192:195], 0
	v_mfma_f32_16x16x32_bf16 v[126:129], v[148:151], v[168:171], v[126:129]
	v_mfma_f32_16x16x32_bf16 v[122:125], v[156:159], v[168:171], v[122:125]
	v_mfma_f32_16x16x32_bf16 v[110:113], v[148:151], v[180:183], v[110:113]
	v_mfma_f32_16x16x32_bf16 v[106:109], v[156:159], v[180:183], v[106:109]
	v_mfma_f32_16x16x32_bf16 v[94:97], v[148:151], v[188:191], v[94:97]
	v_mfma_f32_16x16x32_bf16 v[90:93], v[156:159], v[188:191], v[90:93]
	s_waitcnt lgkmcnt(0)
	v_mfma_f32_16x16x32_bf16 v[78:81], v[148:151], v[196:199], v[78:81]
	v_mfma_f32_16x16x32_bf16 v[74:77], v[156:159], v[196:199], v[74:77]
	s_barrier
	s_add_i32 s59, 0, 0x14000
	s_add_i32 s57, s57, s34
	v_add_u32_e32 v48, s59, v166
	v_lshl_add_u64 v[164:165], s[12:13], 0, v[134:135]
	s_mov_b32 m0, s57
	ds_read_b128 v[200:203], v48
	ds_read_b128 v[204:207], v48 offset:1024
	ds_read_b128 v[208:211], v48 offset:2048
	ds_read_b128 v[212:215], v48 offset:3072
	global_load_lds_dwordx4 v[164:165], off
	v_lshl_add_u64 v[172:173], s[12:13], 0, v[130:131]
	s_add_i32 m0, s57, 0x2000
	s_nop 0
	global_load_lds_dwordx4 v[172:173], off
	s_barrier
	s_waitcnt lgkmcnt(3)
	v_mfma_f32_16x16x32_bf16 v[118:121], v[200:203], v[160:163], 0
	s_waitcnt lgkmcnt(1)
	v_mfma_f32_16x16x32_bf16 v[114:117], v[208:211], v[160:163], 0
	v_mfma_f32_16x16x32_bf16 v[102:105], v[200:203], v[176:179], 0
	v_mfma_f32_16x16x32_bf16 v[98:101], v[208:211], v[176:179], 0
	v_mfma_f32_16x16x32_bf16 v[86:89], v[200:203], v[184:187], 0
	v_mfma_f32_16x16x32_bf16 v[82:85], v[208:211], v[184:187], 0
	v_mfma_f32_16x16x32_bf16 v[70:73], v[200:203], v[192:195], 0
	v_mfma_f32_16x16x32_bf16 v[66:69], v[208:211], v[192:195], 0
	v_mfma_f32_16x16x32_bf16 v[118:121], v[204:207], v[168:171], v[118:121]
	s_waitcnt lgkmcnt(0)
	v_mfma_f32_16x16x32_bf16 v[114:117], v[212:215], v[168:171], v[114:117]
	v_mfma_f32_16x16x32_bf16 v[102:105], v[204:207], v[180:183], v[102:105]
	v_mfma_f32_16x16x32_bf16 v[98:101], v[212:215], v[180:183], v[98:101]
	v_mfma_f32_16x16x32_bf16 v[86:89], v[204:207], v[188:191], v[86:89]
	v_mfma_f32_16x16x32_bf16 v[82:85], v[212:215], v[188:191], v[82:85]
	v_mfma_f32_16x16x32_bf16 v[70:73], v[204:207], v[196:199], v[70:73]
	v_mfma_f32_16x16x32_bf16 v[66:69], v[212:215], v[196:199], v[66:69]
	s_mov_b32 m0, s3
	v_lshl_add_u64 v[216:217], s[16:17], 0, v[136:137]
	s_barrier
	ds_read_b128 v[160:163], v167 offset:16384
	ds_read_b128 v[168:171], v167 offset:17408
	ds_read_b128 v[176:179], v167 offset:18432
	ds_read_b128 v[180:183], v167 offset:19456
	ds_read_b128 v[184:187], v167 offset:20480
	ds_read_b128 v[188:191], v167 offset:21504
	ds_read_b128 v[192:195], v167 offset:22528
	ds_read_b128 v[196:199], v167 offset:23552
	global_load_lds_dwordx4 v[216:217], off
	v_lshl_add_u64 v[218:219], s[16:17], 0, v[132:133]
	s_mov_b32 m0, s36
	s_nop 0
	global_load_lds_dwordx4 v[218:219], off
	s_barrier
	s_waitcnt lgkmcnt(7)
	v_mfma_f32_16x16x32_bf16 v[62:65], v[144:147], v[160:163], 0
	v_mfma_f32_16x16x32_bf16 v[58:61], v[152:155], v[160:163], 0
	s_waitcnt lgkmcnt(5)
	v_mfma_f32_16x16x32_bf16 v[44:47], v[144:147], v[176:179], 0
	v_mfma_f32_16x16x32_bf16 v[40:43], v[152:155], v[176:179], 0
	s_waitcnt lgkmcnt(3)
	v_mfma_f32_16x16x32_bf16 v[28:31], v[144:147], v[184:187], 0
	v_mfma_f32_16x16x32_bf16 v[24:27], v[152:155], v[184:187], 0
	s_waitcnt lgkmcnt(1)
	v_mfma_f32_16x16x32_bf16 v[12:15], v[144:147], v[192:195], 0
	v_mfma_f32_16x16x32_bf16 v[8:11], v[152:155], v[192:195], 0
	v_mfma_f32_16x16x32_bf16 v[62:65], v[148:151], v[168:171], v[62:65]
	v_mfma_f32_16x16x32_bf16 v[58:61], v[156:159], v[168:171], v[58:61]
	v_mfma_f32_16x16x32_bf16 v[44:47], v[148:151], v[180:183], v[44:47]
	v_mfma_f32_16x16x32_bf16 v[40:43], v[156:159], v[180:183], v[40:43]
	v_mfma_f32_16x16x32_bf16 v[28:31], v[148:151], v[188:191], v[28:31]
	v_mfma_f32_16x16x32_bf16 v[24:27], v[156:159], v[188:191], v[24:27]
	s_waitcnt lgkmcnt(0)
	v_mfma_f32_16x16x32_bf16 v[12:15], v[148:151], v[196:199], v[12:15]
	v_mfma_f32_16x16x32_bf16 v[8:11], v[156:159], v[196:199], v[8:11]
	s_barrier
; #define PG8_STAGE(bufoff, gbase, voff) do { _Pragma("unroll") for (int _i = 0; _i < 2; ++_i) \
;         __builtin_amdgcn_global_load_lds((const unsigned*)((const char*)(gbase) + (voff)[_i]), (PG8_LAS unsigned*)(lds + (bufoff) + ldsw + _i * 8192), 16, 0, 0); } while (0)
; #define PG8_LDA(dst, b, h) do { _Pragma("unroll") for (int m = 0; m < 4; ++m) _Pragma("unroll") for (int k = 0; k < 2; ++k) dst[m][k] = *(const PG8_LAS bf16x8*)(lds + PG8_SA(b, h) + aoff + m * 2048 + k * 1024); } while (0)
; #define PG8_LDB(dst, b, h) do { _Pragma("unroll") for (int n = 0; n < 2; ++n) _Pragma("unroll") for (int k = 0; k < 2; ++k) dst[n][k] = *(const PG8_LAS bf16x8*)(lds + PG8_SB(b, h) + boff + n * 2048 + k * 1024); } while (0)
; #define PG8_MMA(ai, bj, At, Bt) do { __builtin_amdgcn_s_setprio(1); _Pragma("unroll") for (int m = 0; m < 4; ++m) _Pragma("unroll") for (int n = 0; n < 2; ++n) _Pragma("unroll") for (int k = 0; k < 2; ++k) \
;         acc[ai][bj][m][n] = __builtin_amdgcn_mfma_f32_16x16x32_bf16(Bt[n][k], At[m][k], acc[ai][bj][m][n], 0, 0, 0); __builtin_amdgcn_s_setprio(0); } while (0)
; #define PG8_WAIT_V(n) asm volatile("s_waitcnt vmcnt(" #n ")" ::: "memory")
; #define PG8_WAIT_L(n) asm volatile("s_waitcnt lgkmcnt(" #n ")" ::: "memory")
; #define PG8_BAR __builtin_amdgcn_s_barrier()
; #define PG8_SCHED __builtin_amdgcn_sched_barrier(0)
; template <class Epi, class Sched>
; __device__ __forceinline__ void gemm_phase(PG8_LAS unsigned char* lds, const Gemm g, const Sched& S, const Epi& E) {
;     ...
;             PG8_STAGE(PG8_SB(0, 1), b2 + hstep, voffB);
;             PG8_WAIT_V(6); PG8_BAR; PG8_MMA(1, 1, At, B1); PG8_BAR;
;             PG8_LDB(B0, 1, 0); PG8_SCHED; PG8_LDA(At, 1, 0); PG8_STAGE(PG8_SA(0, 1), a2 + hstep, voffA);
;             PG8_WAIT_L(8); PG8_BAR; PG8_WAIT_L(0); PG8_MMA(0, 0, At, B0); PG8_BAR; PG8_SCHED;
;             PG8_LDB(B1, 1, 1); PG8_STAGE(PG8_SB(1, 0), b3, voffB);
;             PG8_BAR; PG8_WAIT_L(0); PG8_MMA(0, 1, At, B1); PG8_BAR;
;             PG8_LDA(At, 1, 1); PG8_STAGE(PG8_SA(1, 0), a3, voffA);
	s_add_u32 s64, s12, 0x40000
	s_addc_u32 s65, s13, 0
	s_add_i32 s57, s59, s34
	v_lshl_add_u64 v[144:145], s[64:65], 0, v[134:135]
	s_mov_b32 m0, s57
	s_nop 0
	global_load_lds_dwordx4 v[144:145], off
	v_lshl_add_u64 v[144:145], s[64:65], 0, v[130:131]
	s_add_i32 m0, s57, 0x2000
	s_nop 0
	global_load_lds_dwordx4 v[144:145], off
	s_waitcnt vmcnt(6)
	s_barrier
	v_mfma_f32_16x16x32_bf16 v[54:57], v[200:203], v[160:163], 0
	v_mfma_f32_16x16x32_bf16 v[50:53], v[208:211], v[160:163], 0
	v_mfma_f32_16x16x32_bf16 v[36:39], v[200:203], v[176:179], 0
	v_mfma_f32_16x16x32_bf16 v[32:35], v[208:211], v[176:179], 0
	v_mfma_f32_16x16x32_bf16 v[20:23], v[200:203], v[184:187], 0
	v_mfma_f32_16x16x32_bf16 v[16:19], v[208:211], v[184:187], 0
	v_mfma_f32_16x16x32_bf16 v[4:7], v[200:203], v[192:195], 0
	v_mfma_f32_16x16x32_bf16 v[0:3], v[208:211], v[192:195], 0
	v_mfma_f32_16x16x32_bf16 v[54:57], v[204:207], v[168:171], v[54:57]
	v_mfma_f32_16x16x32_bf16 v[50:53], v[212:215], v[168:171], v[50:53]
	v_mfma_f32_16x16x32_bf16 v[36:39], v[204:207], v[180:183], v[36:39]
	v_mfma_f32_16x16x32_bf16 v[32:35], v[212:215], v[180:183], v[32:35]
	v_mfma_f32_16x16x32_bf16 v[20:23], v[204:207], v[188:191], v[20:23]
	v_mfma_f32_16x16x32_bf16 v[16:19], v[212:215], v[188:191], v[16:19]
	v_mfma_f32_16x16x32_bf16 v[4:7], v[204:207], v[196:199], v[4:7]
	v_mfma_f32_16x16x32_bf16 v[0:3], v[212:215], v[196:199], v[0:3]
	s_add_i32 s57, 0, 0x18000
	v_add_u32_e32 v48, s57, v166
	s_barrier
	ds_read_b128 v[144:147], v48
	ds_read_b128 v[148:151], v48 offset:1024
	ds_read_b128 v[152:155], v48 offset:2048
	ds_read_b128 v[156:159], v48 offset:3072
	s_add_u32 s16, s16, 0x40000
	s_addc_u32 s17, s17, 0
	s_mov_b32 m0, s37
	v_lshl_add_u64 v[200:201], s[16:17], 0, v[136:137]
	ds_read_b128 v[160:163], v167 offset:32768
	ds_read_b128 v[168:171], v167 offset:33792
	ds_read_b128 v[176:179], v167 offset:34816
	ds_read_b128 v[180:183], v167 offset:35840
	ds_read_b128 v[184:187], v167 offset:36864
	ds_read_b128 v[188:191], v167 offset:37888
	ds_read_b128 v[192:195], v167 offset:38912
	ds_read_b128 v[196:199], v167 offset:39936
	global_load_lds_dwordx4 v[200:201], off
	v_lshl_add_u64 v[200:201], s[16:17], 0, v[132:133]
	s_mov_b32 m0, s38
	s_nop 0
	global_load_lds_dwordx4 v[200:201], off
	s_waitcnt lgkmcnt(8)
	s_barrier
	s_waitcnt lgkmcnt(7)
	v_mfma_f32_16x16x32_bf16 v[126:129], v[144:147], v[160:163], v[126:129]
	v_mfma_f32_16x16x32_bf16 v[122:125], v[152:155], v[160:163], v[122:125]
	s_waitcnt lgkmcnt(5)
	v_mfma_f32_16x16x32_bf16 v[110:113], v[144:147], v[176:179], v[110:113]
	v_mfma_f32_16x16x32_bf16 v[106:109], v[152:155], v[176:179], v[106:109]
	s_waitcnt lgkmcnt(3)
	v_mfma_f32_16x16x32_bf16 v[94:97], v[144:147], v[184:187], v[94:97]
	v_mfma_f32_16x16x32_bf16 v[90:93], v[152:155], v[184:187], v[90:93]
	s_waitcnt lgkmcnt(1)
	v_mfma_f32_16x16x32_bf16 v[78:81], v[144:147], v[192:195], v[78:81]
	v_mfma_f32_16x16x32_bf16 v[74:77], v[152:155], v[192:195], v[74:77]
	v_mfma_f32_16x16x32_bf16 v[126:129], v[148:151], v[168:171], v[126:129]
	v_mfma_f32_16x16x32_bf16 v[122:125], v[156:159], v[168:171], v[122:125]
	v_mfma_f32_16x16x32_bf16 v[110:113], v[148:151], v[180:183], v[110:113]
	v_mfma_f32_16x16x32_bf16 v[106:109], v[156:159], v[180:183], v[106:109]
	v_mfma_f32_16x16x32_bf16 v[94:97], v[148:151], v[188:191], v[94:97]
	v_mfma_f32_16x16x32_bf16 v[90:93], v[156:159], v[188:191], v[90:93]
	s_waitcnt lgkmcnt(0)
	v_mfma_f32_16x16x32_bf16 v[78:81], v[148:151], v[196:199], v[78:81]
	v_mfma_f32_16x16x32_bf16 v[74:77], v[156:159], v[196:199], v[74:77]
	s_barrier
	s_add_i32 s16, 0, 0x1c000
	s_add_i32 s17, s57, s34
	v_add_u32_e32 v48, s16, v166
	v_lshl_add_u64 v[164:165], v[164:165], 0, s[0:1]
	s_mov_b32 m0, s17
	ds_read_b128 v[200:203], v48
	ds_read_b128 v[204:207], v48 offset:1024
	ds_read_b128 v[208:211], v48 offset:2048
	ds_read_b128 v[212:215], v48 offset:3072
	global_load_lds_dwordx4 v[164:165], off
	v_lshl_add_u64 v[164:165], v[172:173], 0, s[0:1]
	s_add_i32 m0, s17, 0x2000
	s_nop 0
	global_load_lds_dwordx4 v[164:165], off
	s_barrier
	s_waitcnt lgkmcnt(3)
	v_mfma_f32_16x16x32_bf16 v[118:121], v[200:203], v[160:163], v[118:121]
	s_waitcnt lgkmcnt(1)
	v_mfma_f32_16x16x32_bf16 v[114:117], v[208:211], v[160:163], v[114:117]
	v_mfma_f32_16x16x32_bf16 v[102:105], v[200:203], v[176:179], v[102:105]
	v_mfma_f32_16x16x32_bf16 v[98:101], v[208:211], v[176:179], v[98:101]
	v_mfma_f32_16x16x32_bf16 v[86:89], v[200:203], v[184:187], v[86:89]
	v_mfma_f32_16x16x32_bf16 v[82:85], v[208:211], v[184:187], v[82:85]
	v_mfma_f32_16x16x32_bf16 v[70:73], v[200:203], v[192:195], v[70:73]
	v_mfma_f32_16x16x32_bf16 v[66:69], v[208:211], v[192:195], v[66:69]
	v_mfma_f32_16x16x32_bf16 v[118:121], v[204:207], v[168:171], v[118:121]
	s_waitcnt lgkmcnt(0)
	v_mfma_f32_16x16x32_bf16 v[114:117], v[212:215], v[168:171], v[114:117]
	v_mfma_f32_16x16x32_bf16 v[102:105], v[204:207], v[180:183], v[102:105]
	v_mfma_f32_16x16x32_bf16 v[98:101], v[212:215], v[180:183], v[98:101]
	v_mfma_f32_16x16x32_bf16 v[86:89], v[204:207], v[188:191], v[86:89]
	v_mfma_f32_16x16x32_bf16 v[82:85], v[212:215], v[188:191], v[82:85]
	v_mfma_f32_16x16x32_bf16 v[70:73], v[204:207], v[196:199], v[70:73]
	v_mfma_f32_16x16x32_bf16 v[66:69], v[212:215], v[196:199], v[66:69]
	s_mov_b32 m0, s39
	v_lshl_add_u64 v[164:165], v[216:217], 0, s[0:1]
	s_barrier
	ds_read_b128 v[160:163], v167 offset:49152
	ds_read_b128 v[168:171], v167 offset:50176
	ds_read_b128 v[176:179], v167 offset:51200
	ds_read_b128 v[180:183], v167 offset:52224
	ds_read_b128 v[184:187], v167 offset:53248
	ds_read_b128 v[188:191], v167 offset:54272
	ds_read_b128 v[192:195], v167 offset:55296
	ds_read_b128 v[196:199], v167 offset:56320
	global_load_lds_dwordx4 v[164:165], off
	v_lshl_add_u64 v[164:165], v[218:219], 0, s[0:1]
	s_mov_b32 m0, s42
	s_nop 0
	global_load_lds_dwordx4 v[164:165], off
	s_barrier
; #define PG8_STAGE(bufoff, gbase, voff) do { _Pragma("unroll") for (int _i = 0; _i < 2; ++_i) \
;         __builtin_amdgcn_global_load_lds((const unsigned*)((const char*)(gbase) + (voff)[_i]), (PG8_LAS unsigned*)(lds + (bufoff) + ldsw + _i * 8192), 16, 0, 0); } while (0)
; #define PG8_LDA(dst, b, h) do { _Pragma("unroll") for (int m = 0; m < 4; ++m) _Pragma("unroll") for (int k = 0; k < 2; ++k) dst[m][k] = *(const PG8_LAS bf16x8*)(lds + PG8_SA(b, h) + aoff + m * 2048 + k * 1024); } while (0)
; #define PG8_LDB(dst, b, h) do { _Pragma("unroll") for (int n = 0; n < 2; ++n) _Pragma("unroll") for (int k = 0; k < 2; ++k) dst[n][k] = *(const PG8_LAS bf16x8*)(lds + PG8_SB(b, h) + boff + n * 2048 + k * 1024); } while (0)
; #define PG8_MMA(ai, bj, At, Bt) do { __builtin_amdgcn_s_setprio(1); _Pragma("unroll") for (int m = 0; m < 4; ++m) _Pragma("unroll") for (int n = 0; n < 2; ++n) _Pragma("unroll") for (int k = 0; k < 2; ++k) \
;         acc[ai][bj][m][n] = __builtin_amdgcn_mfma_f32_16x16x32_bf16(Bt[n][k], At[m][k], acc[ai][bj][m][n], 0, 0, 0); __builtin_amdgcn_s_setprio(0); } while (0)
; #define PG8_WAIT_V(n) asm volatile("s_waitcnt vmcnt(" #n ")" ::: "memory")
; #define PG8_WAIT_L(n) asm volatile("s_waitcnt lgkmcnt(" #n ")" ::: "memory")
; #define PG8_BAR __builtin_amdgcn_s_barrier()
; #define PG8_SCHED __builtin_amdgcn_sched_barrier(0)
; template <class Epi, class Sched>
; __device__ __forceinline__ void gemm_phase(PG8_LAS unsigned char* lds, const Gemm g, const Sched& S, const Epi& E) {
;     ...
;             PG8_LDB(B0, 0, 0); PG8_SCHED; PG8_LDA(At, 0, 0); PG8_STAGE(PG8_SA(1, 1), a1 + hstep, voffA);
;             PG8_WAIT_L(8); PG8_BAR; PG8_WAIT_L(0); PG8_MMA(0, 0, At, B0); PG8_BAR; PG8_SCHED;
;             PG8_LDB(B1, 0, 1); PG8_STAGE(PG8_SB(0, 0), b2, voffB);
;     ...
;             PG8_BAR; PG8_WAIT_L(0); PG8_MMA(1, 0, At, B0); PG8_BAR; PG8_SCHED;
;             PG8_STAGE(PG8_SB(1, 1), b3 + hstep, voffB);
;             PG8_WAIT_V(6); PG8_BAR; PG8_MMA(1, 1, At, B1); PG8_BAR;
	s_waitcnt lgkmcnt(7)
	v_mfma_f32_16x16x32_bf16 v[62:65], v[144:147], v[160:163], v[62:65]
	v_mfma_f32_16x16x32_bf16 v[58:61], v[152:155], v[160:163], v[58:61]
	s_waitcnt lgkmcnt(5)
	v_mfma_f32_16x16x32_bf16 v[44:47], v[144:147], v[176:179], v[44:47]
	v_mfma_f32_16x16x32_bf16 v[40:43], v[152:155], v[176:179], v[40:43]
	s_waitcnt lgkmcnt(3)
	v_mfma_f32_16x16x32_bf16 v[28:31], v[144:147], v[184:187], v[28:31]
	v_mfma_f32_16x16x32_bf16 v[24:27], v[152:155], v[184:187], v[24:27]
	s_waitcnt lgkmcnt(1)
	v_mfma_f32_16x16x32_bf16 v[12:15], v[144:147], v[192:195], v[12:15]
	v_mfma_f32_16x16x32_bf16 v[8:11], v[152:155], v[192:195], v[8:11]
	v_mfma_f32_16x16x32_bf16 v[62:65], v[148:151], v[168:171], v[62:65]
	v_mfma_f32_16x16x32_bf16 v[58:61], v[156:159], v[168:171], v[58:61]
	v_mfma_f32_16x16x32_bf16 v[44:47], v[148:151], v[180:183], v[44:47]
	v_mfma_f32_16x16x32_bf16 v[40:43], v[156:159], v[180:183], v[40:43]
	v_mfma_f32_16x16x32_bf16 v[28:31], v[148:151], v[188:191], v[28:31]
	v_mfma_f32_16x16x32_bf16 v[24:27], v[156:159], v[188:191], v[24:27]
	s_waitcnt lgkmcnt(0)
	v_mfma_f32_16x16x32_bf16 v[12:15], v[148:151], v[196:199], v[12:15]
	v_mfma_f32_16x16x32_bf16 v[8:11], v[156:159], v[196:199], v[8:11]
	s_barrier
	s_add_u32 s12, s12, 0x40080
	s_addc_u32 s13, s13, 0
	s_add_i32 s16, s16, s34
	v_lshl_add_u64 v[144:145], s[12:13], 0, v[134:135]
	s_mov_b32 m0, s16
	s_nop 0
	global_load_lds_dwordx4 v[144:145], off
	v_lshl_add_u64 v[144:145], s[12:13], 0, v[130:131]
	s_add_i32 m0, s16, 0x2000
	s_nop 0
	global_load_lds_dwordx4 v[144:145], off
	s_waitcnt vmcnt(6)
	s_barrier
	v_mfma_f32_16x16x32_bf16 v[54:57], v[200:203], v[160:163], v[54:57]
	v_mfma_f32_16x16x32_bf16 v[50:53], v[208:211], v[160:163], v[50:53]
	v_mfma_f32_16x16x32_bf16 v[36:39], v[200:203], v[176:179], v[36:39]
	v_mfma_f32_16x16x32_bf16 v[32:35], v[208:211], v[176:179], v[32:35]
	v_mfma_f32_16x16x32_bf16 v[20:23], v[200:203], v[184:187], v[20:23]
	v_mfma_f32_16x16x32_bf16 v[16:19], v[208:211], v[184:187], v[16:19]
	v_mfma_f32_16x16x32_bf16 v[4:7], v[200:203], v[192:195], v[4:7]
	v_mfma_f32_16x16x32_bf16 v[0:3], v[208:211], v[192:195], v[0:3]
	v_mfma_f32_16x16x32_bf16 v[54:57], v[204:207], v[168:171], v[54:57]
	v_mfma_f32_16x16x32_bf16 v[50:53], v[212:215], v[168:171], v[50:53]
	v_mfma_f32_16x16x32_bf16 v[36:39], v[204:207], v[180:183], v[36:39]
	v_mfma_f32_16x16x32_bf16 v[32:35], v[212:215], v[180:183], v[32:35]
	v_mfma_f32_16x16x32_bf16 v[20:23], v[204:207], v[188:191], v[20:23]
	v_mfma_f32_16x16x32_bf16 v[16:19], v[212:215], v[188:191], v[16:19]
	v_mfma_f32_16x16x32_bf16 v[4:7], v[204:207], v[196:199], v[4:7]
	v_mfma_f32_16x16x32_bf16 v[0:3], v[212:215], v[196:199], v[0:3]
	s_add_i32 s56, s56, 2
	s_add_u32 s6, s6, 0x100
	s_addc_u32 s7, s7, 0
	s_add_u32 s54, s54, 0x100
	s_addc_u32 s55, s55, 0
	s_cmp_gt_u32 s56, 13
	s_barrier
	s_cbranch_scc1 .Lkpeel_exit_335
.LBB0_335:
	s_add_u32 s12, s6, 0xfffc0080
	s_addc_u32 s13, s7, -1
	s_add_i32 s57, 0, 0x10000
	v_add_u32_e32 v48, s57, v166
	ds_read_b128 v[144:147], v48
	ds_read_b128 v[148:151], v48 offset:1024
	ds_read_b128 v[152:155], v48 offset:2048
	ds_read_b128 v[156:159], v48 offset:3072
	s_cmp_eq_u32 s56, 12
	s_cselect_b32 s17, s23, s13
	s_cselect_b32 s16, s50, s12
	s_cselect_b32 s13, s21, s55
	s_cselect_b32 s12, s51, s54
	v_lshl_add_u64 v[164:165], s[6:7], 0, v[140:141]
	s_add_i32 m0, s3, 0xc000
	ds_read_b128 v[160:163], v167
	ds_read_b128 v[168:171], v167 offset:1024
	ds_read_b128 v[176:179], v167 offset:2048
	ds_read_b128 v[180:183], v167 offset:3072
	ds_read_b128 v[184:187], v167 offset:4096
	ds_read_b128 v[188:191], v167 offset:5120
	ds_read_b128 v[192:195], v167 offset:6144
	ds_read_b128 v[196:199], v167 offset:7168
	global_load_lds_dwordx4 v[164:165], off
	v_lshl_add_u64 v[164:165], s[6:7], 0, v[142:143]
	s_add_i32 m0, s3, 0xe000
	s_nop 0
	global_load_lds_dwordx4 v[164:165], off
	s_waitcnt lgkmcnt(8)
	s_barrier
	s_waitcnt lgkmcnt(7)
	v_mfma_f32_16x16x32_bf16 v[126:129], v[144:147], v[160:163], v[126:129]
	v_mfma_f32_16x16x32_bf16 v[122:125], v[152:155], v[160:163], v[122:125]
	s_waitcnt lgkmcnt(5)
	v_mfma_f32_16x16x32_bf16 v[110:113], v[144:147], v[176:179], v[110:113]
	v_mfma_f32_16x16x32_bf16 v[106:109], v[152:155], v[176:179], v[106:109]
	s_waitcnt lgkmcnt(3)
	v_mfma_f32_16x16x32_bf16 v[94:97], v[144:147], v[184:187], v[94:97]
	v_mfma_f32_16x16x32_bf16 v[90:93], v[152:155], v[184:187], v[90:93]
	s_waitcnt lgkmcnt(1)
	v_mfma_f32_16x16x32_bf16 v[78:81], v[144:147], v[192:195], v[78:81]
	v_mfma_f32_16x16x32_bf16 v[74:77], v[152:155], v[192:195], v[74:77]
	v_mfma_f32_16x16x32_bf16 v[126:129], v[148:151], v[168:171], v[126:129]
	v_mfma_f32_16x16x32_bf16 v[122:125], v[156:159], v[168:171], v[122:125]
	v_mfma_f32_16x16x32_bf16 v[110:113], v[148:151], v[180:183], v[110:113]
	v_mfma_f32_16x16x32_bf16 v[106:109], v[156:159], v[180:183], v[106:109]
	v_mfma_f32_16x16x32_bf16 v[94:97], v[148:151], v[188:191], v[94:97]
	v_mfma_f32_16x16x32_bf16 v[90:93], v[156:159], v[188:191], v[90:93]
	s_waitcnt lgkmcnt(0)
	v_mfma_f32_16x16x32_bf16 v[78:81], v[148:151], v[196:199], v[78:81]
	v_mfma_f32_16x16x32_bf16 v[74:77], v[156:159], v[196:199], v[74:77]
	s_barrier
	s_add_i32 s59, 0, 0x14000
	s_add_i32 s57, s57, s34
	v_add_u32_e32 v48, s59, v166
	v_lshl_add_u64 v[164:165], s[12:13], 0, v[134:135]
	s_mov_b32 m0, s57
	ds_read_b128 v[200:203], v48
	ds_read_b128 v[204:207], v48 offset:1024
	ds_read_b128 v[208:211], v48 offset:2048
	ds_read_b128 v[212:215], v48 offset:3072
	global_load_lds_dwordx4 v[164:165], off
	v_lshl_add_u64 v[172:173], s[12:13], 0, v[130:131]
	s_add_i32 m0, s57, 0x2000
	s_nop 0
	global_load_lds_dwordx4 v[172:173], off
	s_barrier
; #define PG8_STAGE(bufoff, gbase, voff) do { _Pragma("unroll") for (int _i = 0; _i < 2; ++_i) \
;         __builtin_amdgcn_global_load_lds((const unsigned*)((const char*)(gbase) + (voff)[_i]), (PG8_LAS unsigned*)(lds + (bufoff) + ldsw + _i * 8192), 16, 0, 0); } while (0)
; #define PG8_LDA(dst, b, h) do { _Pragma("unroll") for (int m = 0; m < 4; ++m) _Pragma("unroll") for (int k = 0; k < 2; ++k) dst[m][k] = *(const PG8_LAS bf16x8*)(lds + PG8_SA(b, h) + aoff + m * 2048 + k * 1024); } while (0)
; #define PG8_LDB(dst, b, h) do { _Pragma("unroll") for (int n = 0; n < 2; ++n) _Pragma("unroll") for (int k = 0; k < 2; ++k) dst[n][k] = *(const PG8_LAS bf16x8*)(lds + PG8_SB(b, h) + boff + n * 2048 + k * 1024); } while (0)
; #define PG8_MMA(ai, bj, At, Bt) do { __builtin_amdgcn_s_setprio(1); _Pragma("unroll") for (int m = 0; m < 4; ++m) _Pragma("unroll") for (int n = 0; n < 2; ++n) _Pragma("unroll") for (int k = 0; k < 2; ++k) \
;         acc[ai][bj][m][n] = __builtin_amdgcn_mfma_f32_16x16x32_bf16(Bt[n][k], At[m][k], acc[ai][bj][m][n], 0, 0, 0); __builtin_amdgcn_s_setprio(0); } while (0)
; #define PG8_WAIT_V(n) asm volatile("s_waitcnt vmcnt(" #n ")" ::: "memory")
; #define PG8_WAIT_L(n) asm volatile("s_waitcnt lgkmcnt(" #n ")" ::: "memory")
; #define PG8_BAR __builtin_amdgcn_s_barrier()
; #define PG8_SCHED __builtin_amdgcn_sched_barrier(0)
; template <class Epi, class Sched>
; __device__ __forceinline__ void gemm_phase(PG8_LAS unsigned char* lds, const Gemm g, const Sched& S, const Epi& E) {
;     ...
;             PG8_BAR; PG8_WAIT_L(0); PG8_MMA(0, 1, At, B1); PG8_BAR;
;             PG8_LDA(At, 0, 1); PG8_STAGE(PG8_SA(0, 0), a2, voffA);
;             PG8_BAR; PG8_WAIT_L(0); PG8_MMA(1, 0, At, B0); PG8_BAR; PG8_SCHED;
;             PG8_STAGE(PG8_SB(0, 1), b2 + hstep, voffB);
;             PG8_WAIT_V(6); PG8_BAR; PG8_MMA(1, 1, At, B1); PG8_BAR;
;             PG8_LDB(B0, 1, 0); PG8_SCHED; PG8_LDA(At, 1, 0); PG8_STAGE(PG8_SA(0, 1), a2 + hstep, voffA);
;             PG8_WAIT_L(8); PG8_BAR; PG8_WAIT_L(0); PG8_MMA(0, 0, At, B0); PG8_BAR; PG8_SCHED;
	s_waitcnt lgkmcnt(3)
	v_mfma_f32_16x16x32_bf16 v[118:121], v[200:203], v[160:163], v[118:121]
	s_waitcnt lgkmcnt(1)
	v_mfma_f32_16x16x32_bf16 v[114:117], v[208:211], v[160:163], v[114:117]
	v_mfma_f32_16x16x32_bf16 v[102:105], v[200:203], v[176:179], v[102:105]
	v_mfma_f32_16x16x32_bf16 v[98:101], v[208:211], v[176:179], v[98:101]
	v_mfma_f32_16x16x32_bf16 v[86:89], v[200:203], v[184:187], v[86:89]
	v_mfma_f32_16x16x32_bf16 v[82:85], v[208:211], v[184:187], v[82:85]
	v_mfma_f32_16x16x32_bf16 v[70:73], v[200:203], v[192:195], v[70:73]
	v_mfma_f32_16x16x32_bf16 v[66:69], v[208:211], v[192:195], v[66:69]
	v_mfma_f32_16x16x32_bf16 v[118:121], v[204:207], v[168:171], v[118:121]
	s_waitcnt lgkmcnt(0)
	v_mfma_f32_16x16x32_bf16 v[114:117], v[212:215], v[168:171], v[114:117]
	v_mfma_f32_16x16x32_bf16 v[102:105], v[204:207], v[180:183], v[102:105]
	v_mfma_f32_16x16x32_bf16 v[98:101], v[212:215], v[180:183], v[98:101]
	v_mfma_f32_16x16x32_bf16 v[86:89], v[204:207], v[188:191], v[86:89]
	v_mfma_f32_16x16x32_bf16 v[82:85], v[212:215], v[188:191], v[82:85]
	v_mfma_f32_16x16x32_bf16 v[70:73], v[204:207], v[196:199], v[70:73]
	v_mfma_f32_16x16x32_bf16 v[66:69], v[212:215], v[196:199], v[66:69]
	s_mov_b32 m0, s3
	v_lshl_add_u64 v[216:217], s[16:17], 0, v[136:137]
	s_barrier
	ds_read_b128 v[160:163], v167 offset:16384
	ds_read_b128 v[168:171], v167 offset:17408
	ds_read_b128 v[176:179], v167 offset:18432
	ds_read_b128 v[180:183], v167 offset:19456
	ds_read_b128 v[184:187], v167 offset:20480
	ds_read_b128 v[188:191], v167 offset:21504
	ds_read_b128 v[192:195], v167 offset:22528
	ds_read_b128 v[196:199], v167 offset:23552
	global_load_lds_dwordx4 v[216:217], off
	v_lshl_add_u64 v[218:219], s[16:17], 0, v[132:133]
	s_mov_b32 m0, s36
	s_nop 0
	global_load_lds_dwordx4 v[218:219], off
	s_barrier
	s_waitcnt lgkmcnt(7)
	v_mfma_f32_16x16x32_bf16 v[62:65], v[144:147], v[160:163], v[62:65]
	v_mfma_f32_16x16x32_bf16 v[58:61], v[152:155], v[160:163], v[58:61]
	s_waitcnt lgkmcnt(5)
	v_mfma_f32_16x16x32_bf16 v[44:47], v[144:147], v[176:179], v[44:47]
	v_mfma_f32_16x16x32_bf16 v[40:43], v[152:155], v[176:179], v[40:43]
	s_waitcnt lgkmcnt(3)
	v_mfma_f32_16x16x32_bf16 v[28:31], v[144:147], v[184:187], v[28:31]
	v_mfma_f32_16x16x32_bf16 v[24:27], v[152:155], v[184:187], v[24:27]
	s_waitcnt lgkmcnt(1)
	v_mfma_f32_16x16x32_bf16 v[12:15], v[144:147], v[192:195], v[12:15]
	v_mfma_f32_16x16x32_bf16 v[8:11], v[152:155], v[192:195], v[8:11]
	v_mfma_f32_16x16x32_bf16 v[62:65], v[148:151], v[168:171], v[62:65]
	v_mfma_f32_16x16x32_bf16 v[58:61], v[156:159], v[168:171], v[58:61]
	v_mfma_f32_16x16x32_bf16 v[44:47], v[148:151], v[180:183], v[44:47]
	v_mfma_f32_16x16x32_bf16 v[40:43], v[156:159], v[180:183], v[40:43]
	v_mfma_f32_16x16x32_bf16 v[28:31], v[148:151], v[188:191], v[28:31]
	v_mfma_f32_16x16x32_bf16 v[24:27], v[156:159], v[188:191], v[24:27]
	s_waitcnt lgkmcnt(0)
	v_mfma_f32_16x16x32_bf16 v[12:15], v[148:151], v[196:199], v[12:15]
	v_mfma_f32_16x16x32_bf16 v[8:11], v[156:159], v[196:199], v[8:11]
	s_barrier
	s_add_u32 s64, s12, 0x40000
	s_addc_u32 s65, s13, 0
	s_add_i32 s57, s59, s34
	v_lshl_add_u64 v[144:145], s[64:65], 0, v[134:135]
	s_mov_b32 m0, s57
	s_nop 0
	global_load_lds_dwordx4 v[144:145], off
	v_lshl_add_u64 v[144:145], s[64:65], 0, v[130:131]
	s_add_i32 m0, s57, 0x2000
	s_nop 0
	global_load_lds_dwordx4 v[144:145], off
	s_waitcnt vmcnt(6)
	s_barrier
	v_mfma_f32_16x16x32_bf16 v[54:57], v[200:203], v[160:163], v[54:57]
	v_mfma_f32_16x16x32_bf16 v[50:53], v[208:211], v[160:163], v[50:53]
	v_mfma_f32_16x16x32_bf16 v[36:39], v[200:203], v[176:179], v[36:39]
	v_mfma_f32_16x16x32_bf16 v[32:35], v[208:211], v[176:179], v[32:35]
	v_mfma_f32_16x16x32_bf16 v[20:23], v[200:203], v[184:187], v[20:23]
	v_mfma_f32_16x16x32_bf16 v[16:19], v[208:211], v[184:187], v[16:19]
	v_mfma_f32_16x16x32_bf16 v[4:7], v[200:203], v[192:195], v[4:7]
	v_mfma_f32_16x16x32_bf16 v[0:3], v[208:211], v[192:195], v[0:3]
	v_mfma_f32_16x16x32_bf16 v[54:57], v[204:207], v[168:171], v[54:57]
	v_mfma_f32_16x16x32_bf16 v[50:53], v[212:215], v[168:171], v[50:53]
	v_mfma_f32_16x16x32_bf16 v[36:39], v[204:207], v[180:183], v[36:39]
	v_mfma_f32_16x16x32_bf16 v[32:35], v[212:215], v[180:183], v[32:35]
	v_mfma_f32_16x16x32_bf16 v[20:23], v[204:207], v[188:191], v[20:23]
	v_mfma_f32_16x16x32_bf16 v[16:19], v[212:215], v[188:191], v[16:19]
	v_mfma_f32_16x16x32_bf16 v[4:7], v[204:207], v[196:199], v[4:7]
	v_mfma_f32_16x16x32_bf16 v[0:3], v[212:215], v[196:199], v[0:3]
	s_add_i32 s57, 0, 0x18000
	v_add_u32_e32 v48, s57, v166
	s_barrier
	ds_read_b128 v[144:147], v48
	ds_read_b128 v[148:151], v48 offset:1024
	ds_read_b128 v[152:155], v48 offset:2048
	ds_read_b128 v[156:159], v48 offset:3072
	s_add_u32 s16, s16, 0x40000
	s_addc_u32 s17, s17, 0
	s_mov_b32 m0, s37
	v_lshl_add_u64 v[200:201], s[16:17], 0, v[136:137]
	ds_read_b128 v[160:163], v167 offset:32768
	ds_read_b128 v[168:171], v167 offset:33792
	ds_read_b128 v[176:179], v167 offset:34816
	ds_read_b128 v[180:183], v167 offset:35840
	ds_read_b128 v[184:187], v167 offset:36864
	ds_read_b128 v[188:191], v167 offset:37888
	ds_read_b128 v[192:195], v167 offset:38912
	ds_read_b128 v[196:199], v167 offset:39936
	global_load_lds_dwordx4 v[200:201], off
	v_lshl_add_u64 v[200:201], s[16:17], 0, v[132:133]
	s_mov_b32 m0, s38
	s_nop 0
	global_load_lds_dwordx4 v[200:201], off
	s_waitcnt lgkmcnt(8)
	s_barrier
; #define PG8_STAGE(bufoff, gbase, voff) do { _Pragma("unroll") for (int _i = 0; _i < 2; ++_i) \
;         __builtin_amdgcn_global_load_lds((const unsigned*)((const char*)(gbase) + (voff)[_i]), (PG8_LAS unsigned*)(lds + (bufoff) + ldsw + _i * 8192), 16, 0, 0); } while (0)
; #define PG8_LDA(dst, b, h) do { _Pragma("unroll") for (int m = 0; m < 4; ++m) _Pragma("unroll") for (int k = 0; k < 2; ++k) dst[m][k] = *(const PG8_LAS bf16x8*)(lds + PG8_SA(b, h) + aoff + m * 2048 + k * 1024); } while (0)
; #define PG8_LDB(dst, b, h) do { _Pragma("unroll") for (int n = 0; n < 2; ++n) _Pragma("unroll") for (int k = 0; k < 2; ++k) dst[n][k] = *(const PG8_LAS bf16x8*)(lds + PG8_SB(b, h) + boff + n * 2048 + k * 1024); } while (0)
; #define PG8_MMA(ai, bj, At, Bt) do { __builtin_amdgcn_s_setprio(1); _Pragma("unroll") for (int m = 0; m < 4; ++m) _Pragma("unroll") for (int n = 0; n < 2; ++n) _Pragma("unroll") for (int k = 0; k < 2; ++k) \
;         acc[ai][bj][m][n] = __builtin_amdgcn_mfma_f32_16x16x32_bf16(Bt[n][k], At[m][k], acc[ai][bj][m][n], 0, 0, 0); __builtin_amdgcn_s_setprio(0); } while (0)
; #define PG8_WAIT_V(n) asm volatile("s_waitcnt vmcnt(" #n ")" ::: "memory")
; #define PG8_WAIT_L(n) asm volatile("s_waitcnt lgkmcnt(" #n ")" ::: "memory")
; #define PG8_BAR __builtin_amdgcn_s_barrier()
; #define PG8_SCHED __builtin_amdgcn_sched_barrier(0)
; template <class Epi, class Sched>
; __device__ __forceinline__ void gemm_phase(PG8_LAS unsigned char* lds, const Gemm g, const Sched& S, const Epi& E) {
;     ...
;             PG8_WAIT_L(8); PG8_BAR; PG8_WAIT_L(0); PG8_MMA(0, 0, At, B0); PG8_BAR; PG8_SCHED;
;             PG8_LDB(B1, 1, 1); PG8_STAGE(PG8_SB(1, 0), b3, voffB);
;             PG8_BAR; PG8_WAIT_L(0); PG8_MMA(0, 1, At, B1); PG8_BAR;
;             PG8_LDA(At, 1, 1); PG8_STAGE(PG8_SA(1, 0), a3, voffA);
;             PG8_BAR; PG8_WAIT_L(0); PG8_MMA(1, 0, At, B0); PG8_BAR; PG8_SCHED;
;             PG8_STAGE(PG8_SB(1, 1), b3 + hstep, voffB);
;             PG8_WAIT_V(6); PG8_BAR; PG8_MMA(1, 1, At, B1); PG8_BAR;
	s_waitcnt lgkmcnt(7)
	v_mfma_f32_16x16x32_bf16 v[126:129], v[144:147], v[160:163], v[126:129]
	v_mfma_f32_16x16x32_bf16 v[122:125], v[152:155], v[160:163], v[122:125]
	s_waitcnt lgkmcnt(5)
	v_mfma_f32_16x16x32_bf16 v[110:113], v[144:147], v[176:179], v[110:113]
	v_mfma_f32_16x16x32_bf16 v[106:109], v[152:155], v[176:179], v[106:109]
	s_waitcnt lgkmcnt(3)
	v_mfma_f32_16x16x32_bf16 v[94:97], v[144:147], v[184:187], v[94:97]
	v_mfma_f32_16x16x32_bf16 v[90:93], v[152:155], v[184:187], v[90:93]
	s_waitcnt lgkmcnt(1)
	v_mfma_f32_16x16x32_bf16 v[78:81], v[144:147], v[192:195], v[78:81]
	v_mfma_f32_16x16x32_bf16 v[74:77], v[152:155], v[192:195], v[74:77]
	v_mfma_f32_16x16x32_bf16 v[126:129], v[148:151], v[168:171], v[126:129]
	v_mfma_f32_16x16x32_bf16 v[122:125], v[156:159], v[168:171], v[122:125]
	v_mfma_f32_16x16x32_bf16 v[110:113], v[148:151], v[180:183], v[110:113]
	v_mfma_f32_16x16x32_bf16 v[106:109], v[156:159], v[180:183], v[106:109]
	v_mfma_f32_16x16x32_bf16 v[94:97], v[148:151], v[188:191], v[94:97]
	v_mfma_f32_16x16x32_bf16 v[90:93], v[156:159], v[188:191], v[90:93]
	s_waitcnt lgkmcnt(0)
	v_mfma_f32_16x16x32_bf16 v[78:81], v[148:151], v[196:199], v[78:81]
	v_mfma_f32_16x16x32_bf16 v[74:77], v[156:159], v[196:199], v[74:77]
	s_barrier
	s_add_i32 s16, 0, 0x1c000
	s_add_i32 s17, s57, s34
	v_add_u32_e32 v48, s16, v166
	v_lshl_add_u64 v[164:165], v[164:165], 0, s[0:1]
	s_mov_b32 m0, s17
	ds_read_b128 v[200:203], v48
	ds_read_b128 v[204:207], v48 offset:1024
	ds_read_b128 v[208:211], v48 offset:2048
	ds_read_b128 v[212:215], v48 offset:3072
	global_load_lds_dwordx4 v[164:165], off
	v_lshl_add_u64 v[164:165], v[172:173], 0, s[0:1]
	s_add_i32 m0, s17, 0x2000
	s_nop 0
	global_load_lds_dwordx4 v[164:165], off
	s_barrier
	s_waitcnt lgkmcnt(3)
	v_mfma_f32_16x16x32_bf16 v[118:121], v[200:203], v[160:163], v[118:121]
	s_waitcnt lgkmcnt(1)
	v_mfma_f32_16x16x32_bf16 v[114:117], v[208:211], v[160:163], v[114:117]
	v_mfma_f32_16x16x32_bf16 v[102:105], v[200:203], v[176:179], v[102:105]
	v_mfma_f32_16x16x32_bf16 v[98:101], v[208:211], v[176:179], v[98:101]
	v_mfma_f32_16x16x32_bf16 v[86:89], v[200:203], v[184:187], v[86:89]
	v_mfma_f32_16x16x32_bf16 v[82:85], v[208:211], v[184:187], v[82:85]
	v_mfma_f32_16x16x32_bf16 v[70:73], v[200:203], v[192:195], v[70:73]
	v_mfma_f32_16x16x32_bf16 v[66:69], v[208:211], v[192:195], v[66:69]
	v_mfma_f32_16x16x32_bf16 v[118:121], v[204:207], v[168:171], v[118:121]
	s_waitcnt lgkmcnt(0)
	v_mfma_f32_16x16x32_bf16 v[114:117], v[212:215], v[168:171], v[114:117]
	v_mfma_f32_16x16x32_bf16 v[102:105], v[204:207], v[180:183], v[102:105]
	v_mfma_f32_16x16x32_bf16 v[98:101], v[212:215], v[180:183], v[98:101]
	v_mfma_f32_16x16x32_bf16 v[86:89], v[204:207], v[188:191], v[86:89]
	v_mfma_f32_16x16x32_bf16 v[82:85], v[212:215], v[188:191], v[82:85]
	v_mfma_f32_16x16x32_bf16 v[70:73], v[204:207], v[196:199], v[70:73]
	v_mfma_f32_16x16x32_bf16 v[66:69], v[212:215], v[196:199], v[66:69]
	s_mov_b32 m0, s39
	v_lshl_add_u64 v[164:165], v[216:217], 0, s[0:1]
	s_barrier
	ds_read_b128 v[160:163], v167 offset:49152
	ds_read_b128 v[168:171], v167 offset:50176
	ds_read_b128 v[176:179], v167 offset:51200
	ds_read_b128 v[180:183], v167 offset:52224
	ds_read_b128 v[184:187], v167 offset:53248
	ds_read_b128 v[188:191], v167 offset:54272
	ds_read_b128 v[192:195], v167 offset:55296
	ds_read_b128 v[196:199], v167 offset:56320
	global_load_lds_dwordx4 v[164:165], off
	v_lshl_add_u64 v[164:165], v[218:219], 0, s[0:1]
	s_mov_b32 m0, s42
	s_nop 0
	global_load_lds_dwordx4 v[164:165], off
	s_barrier
	s_waitcnt lgkmcnt(7)
	v_mfma_f32_16x16x32_bf16 v[62:65], v[144:147], v[160:163], v[62:65]
	v_mfma_f32_16x16x32_bf16 v[58:61], v[152:155], v[160:163], v[58:61]
	s_waitcnt lgkmcnt(5)
	v_mfma_f32_16x16x32_bf16 v[44:47], v[144:147], v[176:179], v[44:47]
	v_mfma_f32_16x16x32_bf16 v[40:43], v[152:155], v[176:179], v[40:43]
	s_waitcnt lgkmcnt(3)
	v_mfma_f32_16x16x32_bf16 v[28:31], v[144:147], v[184:187], v[28:31]
	v_mfma_f32_16x16x32_bf16 v[24:27], v[152:155], v[184:187], v[24:27]
	s_waitcnt lgkmcnt(1)
	v_mfma_f32_16x16x32_bf16 v[12:15], v[144:147], v[192:195], v[12:15]
	v_mfma_f32_16x16x32_bf16 v[8:11], v[152:155], v[192:195], v[8:11]
	v_mfma_f32_16x16x32_bf16 v[62:65], v[148:151], v[168:171], v[62:65]
	v_mfma_f32_16x16x32_bf16 v[58:61], v[156:159], v[168:171], v[58:61]
	v_mfma_f32_16x16x32_bf16 v[44:47], v[148:151], v[180:183], v[44:47]
	v_mfma_f32_16x16x32_bf16 v[40:43], v[156:159], v[180:183], v[40:43]
	v_mfma_f32_16x16x32_bf16 v[28:31], v[148:151], v[188:191], v[28:31]
	v_mfma_f32_16x16x32_bf16 v[24:27], v[156:159], v[188:191], v[24:27]
	s_waitcnt lgkmcnt(0)
	v_mfma_f32_16x16x32_bf16 v[12:15], v[148:151], v[196:199], v[12:15]
	v_mfma_f32_16x16x32_bf16 v[8:11], v[156:159], v[196:199], v[8:11]
	s_barrier
	s_add_u32 s12, s12, 0x40080
	s_addc_u32 s13, s13, 0
	s_add_i32 s16, s16, s34
	v_lshl_add_u64 v[144:145], s[12:13], 0, v[134:135]
	s_mov_b32 m0, s16
	s_nop 0
	global_load_lds_dwordx4 v[144:145], off
	v_lshl_add_u64 v[144:145], s[12:13], 0, v[130:131]
	s_add_i32 m0, s16, 0x2000
	s_nop 0
	global_load_lds_dwordx4 v[144:145], off
	s_waitcnt vmcnt(6)
	s_barrier
	v_mfma_f32_16x16x32_bf16 v[54:57], v[200:203], v[160:163], v[54:57]
	v_mfma_f32_16x16x32_bf16 v[50:53], v[208:211], v[160:163], v[50:53]
	v_mfma_f32_16x16x32_bf16 v[36:39], v[200:203], v[176:179], v[36:39]
	v_mfma_f32_16x16x32_bf16 v[32:35], v[208:211], v[176:179], v[32:35]
	v_mfma_f32_16x16x32_bf16 v[20:23], v[200:203], v[184:187], v[20:23]
	v_mfma_f32_16x16x32_bf16 v[16:19], v[208:211], v[184:187], v[16:19]
	v_mfma_f32_16x16x32_bf16 v[4:7], v[200:203], v[192:195], v[4:7]
	v_mfma_f32_16x16x32_bf16 v[0:3], v[208:211], v[192:195], v[0:3]
	v_mfma_f32_16x16x32_bf16 v[54:57], v[204:207], v[168:171], v[54:57]
	v_mfma_f32_16x16x32_bf16 v[50:53], v[212:215], v[168:171], v[50:53]
	v_mfma_f32_16x16x32_bf16 v[36:39], v[204:207], v[180:183], v[36:39]
	v_mfma_f32_16x16x32_bf16 v[32:35], v[212:215], v[180:183], v[32:35]
	v_mfma_f32_16x16x32_bf16 v[20:23], v[204:207], v[188:191], v[20:23]
	v_mfma_f32_16x16x32_bf16 v[16:19], v[212:215], v[188:191], v[16:19]
	v_mfma_f32_16x16x32_bf16 v[4:7], v[204:207], v[196:199], v[4:7]
	v_mfma_f32_16x16x32_bf16 v[0:3], v[212:215], v[196:199], v[0:3]
	s_add_i32 s56, s56, 2
	s_add_u32 s6, s6, 0x100
	s_addc_u32 s7, s7, 0
	s_add_u32 s54, s54, 0x100
	s_addc_u32 s55, s55, 0
	s_cmp_gt_u32 s56, 13
	s_barrier
	s_cbranch_scc0 .LBB0_335

; #define PG8_STAGE(bufoff, gbase, voff) do { _Pragma("unroll") for (int _i = 0; _i < 2; ++_i) \
;         __builtin_amdgcn_global_load_lds((const unsigned*)((const char*)(gbase) + (voff)[_i]), (PG8_LAS unsigned*)(lds + (bufoff) + ldsw + _i * 8192), 16, 0, 0); } while (0)
; #define PG8_LDA(dst, b, h) do { _Pragma("unroll") for (int m = 0; m < 4; ++m) _Pragma("unroll") for (int k = 0; k < 2; ++k) dst[m][k] = *(const PG8_LAS bf16x8*)(lds + PG8_SA(b, h) + aoff + m * 2048 + k * 1024); } while (0)
; #define PG8_LDB(dst, b, h) do { _Pragma("unroll") for (int n = 0; n < 2; ++n) _Pragma("unroll") for (int k = 0; k < 2; ++k) dst[n][k] = *(const PG8_LAS bf16x8*)(lds + PG8_SB(b, h) + boff + n * 2048 + k * 1024); } while (0)
; #define PG8_WAIT_L(n) asm volatile("s_waitcnt lgkmcnt(" #n ")" ::: "memory")
; #define PG8_BAR __builtin_amdgcn_s_barrier()
; #define PG8_SCHED __builtin_amdgcn_sched_barrier(0)
; template <class Epi, class Sched>
; __device__ __forceinline__ void gemm_phase(PG8_LAS unsigned char* lds, const Gemm g, const Sched& S, const Epi& E) {
;     ...
;         const bool has_next = S.next(ui + 1, nxt);
;         const char* nA = has_next ? (const char*)g.A + (size_t)nxt.pm * tstepA + (size_t)nxt.kc * cstep : cA; const char* nB = has_next ? (const char*)g.Bt + (size_t)nxt.pn * tstep + (size_t)nxt.kc * cstep : cB;
;         for (int t = 0; t < nt; t += 2) {
;             const bool last = (t == nt - 2);
;             const char* a1 = cA + (size_t)(t + 1) * kstep;
;             const char* a2 = last ? nA : cA + (size_t)(t + 2) * kstep; const char* b2 = last ? nB : cB + (size_t)(t + 2) * kstep;
;             const char* a3 = a2 + kstep; const char* b3 = b2 + kstep;
;             if (last && has_next) S.a_ready(nxt);
;             PG8_LDB(B0, 0, 0); PG8_SCHED; PG8_LDA(At, 0, 0); PG8_STAGE(PG8_SA(1, 1), a1 + hstep, voffA);
;             PG8_WAIT_L(8); PG8_BAR; PG8_WAIT_L(0); PG8_MMA(0, 0, At, B0); PG8_BAR; PG8_SCHED;
;             PG8_LDB(B1, 0, 1); PG8_STAGE(PG8_SB(0, 0), b2, voffB);
;             PG8_BAR; PG8_WAIT_L(0); PG8_MMA(0, 1, At, B1); PG8_BAR;
;             PG8_LDA(At, 0, 1); PG8_STAGE(PG8_SA(0, 0), a2, voffA);
;             PG8_BAR; PG8_WAIT_L(0); PG8_MMA(1, 0, At, B0); PG8_BAR; PG8_SCHED;
.LBB0_387:
	s_ashr_i32 s39, s38, 31
	s_lshl_b64 s[16:17], s[38:39], 19
	v_readlane_b32 s3, v254, 53
	s_add_u32 s94, s3, s16
	v_readlane_b32 s3, v254, 54
	s_addc_u32 s95, s3, s17
	s_and_b64 s[16:17], s[62:63], exec
	s_cselect_b32 s3, s95, s13
	s_cselect_b32 s26, s94, s12
	s_add_u32 s6, s6, 0x40080
	s_addc_u32 s7, s7, 0
	s_add_u32 s27, s12, 0x100
	s_addc_u32 s29, s13, 0
	s_mov_b32 s30, -2
	s_add_u32 s12, s6, 0xfffc0080
	s_addc_u32 s13, s7, -1
	s_add_i32 s22, 0, 0x10000
	v_add_u32_e32 v48, s22, v250
	ds_read_b128 v[130:133], v48
	ds_read_b128 v[134:137], v48 offset:1024
	ds_read_b128 v[138:141], v48 offset:2048
	ds_read_b128 v[142:145], v48 offset:3072
	s_cmp_eq_u32 s30, 12
	s_cselect_b32 s17, s9, s13
	s_cselect_b32 s16, s8, s12
	s_cselect_b32 s13, s3, s29
	s_cselect_b32 s12, s26, s27
	v_lshl_add_u64 v[192:193], s[6:7], 0, v[184:185]
	s_add_i32 m0, s37, 0xc000
	ds_read_b128 v[146:149], v242
	ds_read_b128 v[150:153], v242 offset:1024
	ds_read_b128 v[154:157], v242 offset:2048
	ds_read_b128 v[158:161], v242 offset:3072
	ds_read_b128 v[162:165], v242 offset:4096
	ds_read_b128 v[166:169], v242 offset:5120
	ds_read_b128 v[170:173], v242 offset:6144
	ds_read_b128 v[188:191], v242 offset:7168
	global_load_lds_dwordx4 v[192:193], off
	v_lshl_add_u64 v[192:193], s[6:7], 0, v[186:187]
	s_add_i32 m0, s37, 0xe000
	s_nop 0
	global_load_lds_dwordx4 v[192:193], off
	s_waitcnt lgkmcnt(8)
	s_barrier
	s_waitcnt lgkmcnt(7)
	v_mfma_f32_16x16x32_bf16 v[126:129], v[130:133], v[146:149], 0
	v_mfma_f32_16x16x32_bf16 v[62:65], v[138:141], v[146:149], 0
	s_waitcnt lgkmcnt(5)
	v_mfma_f32_16x16x32_bf16 v[118:121], v[130:133], v[154:157], 0
	v_mfma_f32_16x16x32_bf16 v[54:57], v[138:141], v[154:157], 0
	s_waitcnt lgkmcnt(3)
	v_mfma_f32_16x16x32_bf16 v[110:113], v[130:133], v[162:165], 0
	v_mfma_f32_16x16x32_bf16 v[44:47], v[138:141], v[162:165], 0
	s_waitcnt lgkmcnt(1)
	v_mfma_f32_16x16x32_bf16 v[102:105], v[130:133], v[170:173], 0
	v_mfma_f32_16x16x32_bf16 v[36:39], v[138:141], v[170:173], 0
	v_mfma_f32_16x16x32_bf16 v[126:129], v[134:137], v[150:153], v[126:129]
	v_mfma_f32_16x16x32_bf16 v[62:65], v[142:145], v[150:153], v[62:65]
	v_mfma_f32_16x16x32_bf16 v[118:121], v[134:137], v[158:161], v[118:121]
	v_mfma_f32_16x16x32_bf16 v[54:57], v[142:145], v[158:161], v[54:57]
	v_mfma_f32_16x16x32_bf16 v[110:113], v[134:137], v[166:169], v[110:113]
	v_mfma_f32_16x16x32_bf16 v[44:47], v[142:145], v[166:169], v[44:47]
	s_waitcnt lgkmcnt(0)
	v_mfma_f32_16x16x32_bf16 v[102:105], v[134:137], v[188:191], v[102:105]
	v_mfma_f32_16x16x32_bf16 v[36:39], v[142:145], v[188:191], v[36:39]
	s_barrier
	s_add_i32 s31, 0, 0x14000
	s_add_i32 s22, s22, s36
	v_add_u32_e32 v48, s31, v250
	v_lshl_add_u64 v[208:209], s[12:13], 0, v[178:179]
	s_mov_b32 m0, s22
	ds_read_b128 v[192:195], v48
	ds_read_b128 v[196:199], v48 offset:1024
	ds_read_b128 v[200:203], v48 offset:2048
	ds_read_b128 v[204:207], v48 offset:3072
	global_load_lds_dwordx4 v[208:209], off
	v_lshl_add_u64 v[210:211], s[12:13], 0, v[182:183]
	s_add_i32 m0, s22, 0x2000
	s_nop 0
	global_load_lds_dwordx4 v[210:211], off
	s_barrier
	s_waitcnt lgkmcnt(3)
	v_mfma_f32_16x16x32_bf16 v[122:125], v[192:195], v[146:149], 0
	s_waitcnt lgkmcnt(1)
	v_mfma_f32_16x16x32_bf16 v[58:61], v[200:203], v[146:149], 0
	v_mfma_f32_16x16x32_bf16 v[114:117], v[192:195], v[154:157], 0
	v_mfma_f32_16x16x32_bf16 v[50:53], v[200:203], v[154:157], 0
	v_mfma_f32_16x16x32_bf16 v[106:109], v[192:195], v[162:165], 0
	v_mfma_f32_16x16x32_bf16 v[40:43], v[200:203], v[162:165], 0
	v_mfma_f32_16x16x32_bf16 v[98:101], v[192:195], v[170:173], 0
	v_mfma_f32_16x16x32_bf16 v[32:35], v[200:203], v[170:173], 0
	v_mfma_f32_16x16x32_bf16 v[122:125], v[196:199], v[150:153], v[122:125]
	s_waitcnt lgkmcnt(0)
	v_mfma_f32_16x16x32_bf16 v[58:61], v[204:207], v[150:153], v[58:61]
	v_mfma_f32_16x16x32_bf16 v[114:117], v[196:199], v[158:161], v[114:117]
	v_mfma_f32_16x16x32_bf16 v[50:53], v[204:207], v[158:161], v[50:53]
	v_mfma_f32_16x16x32_bf16 v[106:109], v[196:199], v[166:169], v[106:109]
	v_mfma_f32_16x16x32_bf16 v[40:43], v[204:207], v[166:169], v[40:43]
	v_mfma_f32_16x16x32_bf16 v[98:101], v[196:199], v[188:191], v[98:101]
	v_mfma_f32_16x16x32_bf16 v[32:35], v[204:207], v[188:191], v[32:35]
	s_mov_b32 m0, s37
	v_lshl_add_u64 v[212:213], s[16:17], 0, v[176:177]
	s_barrier
	ds_read_b128 v[146:149], v242 offset:16384
	ds_read_b128 v[150:153], v242 offset:17408
	ds_read_b128 v[154:157], v242 offset:18432
	ds_read_b128 v[158:161], v242 offset:19456
	ds_read_b128 v[162:165], v242 offset:20480
	ds_read_b128 v[166:169], v242 offset:21504
	ds_read_b128 v[170:173], v242 offset:22528
	ds_read_b128 v[188:191], v242 offset:23552
	global_load_lds_dwordx4 v[212:213], off
	v_lshl_add_u64 v[214:215], s[16:17], 0, v[180:181]
	s_mov_b32 m0, s10
	s_nop 0
	global_load_lds_dwordx4 v[214:215], off
	s_barrier
	s_waitcnt lgkmcnt(7)
	v_mfma_f32_16x16x32_bf16 v[94:97], v[130:133], v[146:149], 0
	v_mfma_f32_16x16x32_bf16 v[28:31], v[138:141], v[146:149], 0
	s_waitcnt lgkmcnt(5)
	v_mfma_f32_16x16x32_bf16 v[86:89], v[130:133], v[154:157], 0
	v_mfma_f32_16x16x32_bf16 v[20:23], v[138:141], v[154:157], 0
	s_waitcnt lgkmcnt(3)
	v_mfma_f32_16x16x32_bf16 v[78:81], v[130:133], v[162:165], 0
	v_mfma_f32_16x16x32_bf16 v[12:15], v[138:141], v[162:165], 0
	s_waitcnt lgkmcnt(1)
	v_mfma_f32_16x16x32_bf16 v[70:73], v[130:133], v[170:173], 0
	v_mfma_f32_16x16x32_bf16 v[4:7], v[138:141], v[170:173], 0
	v_mfma_f32_16x16x32_bf16 v[94:97], v[134:137], v[150:153], v[94:97]
	v_mfma_f32_16x16x32_bf16 v[28:31], v[142:145], v[150:153], v[28:31]
	v_mfma_f32_16x16x32_bf16 v[86:89], v[134:137], v[158:161], v[86:89]
	v_mfma_f32_16x16x32_bf16 v[20:23], v[142:145], v[158:161], v[20:23]
	v_mfma_f32_16x16x32_bf16 v[78:81], v[134:137], v[166:169], v[78:81]
	v_mfma_f32_16x16x32_bf16 v[12:15], v[142:145], v[166:169], v[12:15]
	s_waitcnt lgkmcnt(0)
	v_mfma_f32_16x16x32_bf16 v[70:73], v[134:137], v[188:191], v[70:73]
	v_mfma_f32_16x16x32_bf16 v[4:7], v[142:145], v[188:191], v[4:7]
	s_barrier
; #define PG8_STAGE(bufoff, gbase, voff) do { _Pragma("unroll") for (int _i = 0; _i < 2; ++_i) \
;         __builtin_amdgcn_global_load_lds((const unsigned*)((const char*)(gbase) + (voff)[_i]), (PG8_LAS unsigned*)(lds + (bufoff) + ldsw + _i * 8192), 16, 0, 0); } while (0)
; #define PG8_LDA(dst, b, h) do { _Pragma("unroll") for (int m = 0; m < 4; ++m) _Pragma("unroll") for (int k = 0; k < 2; ++k) dst[m][k] = *(const PG8_LAS bf16x8*)(lds + PG8_SA(b, h) + aoff + m * 2048 + k * 1024); } while (0)
; #define PG8_LDB(dst, b, h) do { _Pragma("unroll") for (int n = 0; n < 2; ++n) _Pragma("unroll") for (int k = 0; k < 2; ++k) dst[n][k] = *(const PG8_LAS bf16x8*)(lds + PG8_SB(b, h) + boff + n * 2048 + k * 1024); } while (0)
; #define PG8_MMA(ai, bj, At, Bt) do { __builtin_amdgcn_s_setprio(1); _Pragma("unroll") for (int m = 0; m < 4; ++m) _Pragma("unroll") for (int n = 0; n < 2; ++n) _Pragma("unroll") for (int k = 0; k < 2; ++k) \
;         acc[ai][bj][m][n] = __builtin_amdgcn_mfma_f32_16x16x32_bf16(Bt[n][k], At[m][k], acc[ai][bj][m][n], 0, 0, 0); __builtin_amdgcn_s_setprio(0); } while (0)
; #define PG8_WAIT_V(n) asm volatile("s_waitcnt vmcnt(" #n ")" ::: "memory")
; #define PG8_WAIT_L(n) asm volatile("s_waitcnt lgkmcnt(" #n ")" ::: "memory")
; #define PG8_BAR __builtin_amdgcn_s_barrier()
; #define PG8_SCHED __builtin_amdgcn_sched_barrier(0)
; template <class Epi, class Sched>
; __device__ __forceinline__ void gemm_phase(PG8_LAS unsigned char* lds, const Gemm g, const Sched& S, const Epi& E) {
;     ...
;             PG8_STAGE(PG8_SB(0, 1), b2 + hstep, voffB);
;             PG8_WAIT_V(6); PG8_BAR; PG8_MMA(1, 1, At, B1); PG8_BAR;
;             PG8_LDB(B0, 1, 0); PG8_SCHED; PG8_LDA(At, 1, 0); PG8_STAGE(PG8_SA(0, 1), a2 + hstep, voffA);
;             PG8_WAIT_L(8); PG8_BAR; PG8_WAIT_L(0); PG8_MMA(0, 0, At, B0); PG8_BAR; PG8_SCHED;
;             PG8_LDB(B1, 1, 1); PG8_STAGE(PG8_SB(1, 0), b3, voffB);
;             PG8_BAR; PG8_WAIT_L(0); PG8_MMA(0, 1, At, B1); PG8_BAR;
;             PG8_LDA(At, 1, 1); PG8_STAGE(PG8_SA(1, 0), a3, voffA);
	s_add_u32 s22, s12, 0x40000
	s_addc_u32 s23, s13, 0
	s_add_i32 s31, s31, s36
	v_lshl_add_u64 v[130:131], s[22:23], 0, v[178:179]
	s_mov_b32 m0, s31
	s_nop 0
	global_load_lds_dwordx4 v[130:131], off
	v_lshl_add_u64 v[130:131], s[22:23], 0, v[182:183]
	s_add_i32 m0, s31, 0x2000
	s_nop 0
	global_load_lds_dwordx4 v[130:131], off
	s_waitcnt vmcnt(6)
	s_barrier
	v_mfma_f32_16x16x32_bf16 v[90:93], v[192:195], v[146:149], 0
	v_mfma_f32_16x16x32_bf16 v[24:27], v[200:203], v[146:149], 0
	v_mfma_f32_16x16x32_bf16 v[82:85], v[192:195], v[154:157], 0
	v_mfma_f32_16x16x32_bf16 v[16:19], v[200:203], v[154:157], 0
	v_mfma_f32_16x16x32_bf16 v[74:77], v[192:195], v[162:165], 0
	v_mfma_f32_16x16x32_bf16 v[8:11], v[200:203], v[162:165], 0
	v_mfma_f32_16x16x32_bf16 v[66:69], v[192:195], v[170:173], 0
	v_mfma_f32_16x16x32_bf16 v[0:3], v[200:203], v[170:173], 0
	v_mfma_f32_16x16x32_bf16 v[90:93], v[196:199], v[150:153], v[90:93]
	v_mfma_f32_16x16x32_bf16 v[24:27], v[204:207], v[150:153], v[24:27]
	v_mfma_f32_16x16x32_bf16 v[82:85], v[196:199], v[158:161], v[82:85]
	v_mfma_f32_16x16x32_bf16 v[16:19], v[204:207], v[158:161], v[16:19]
	v_mfma_f32_16x16x32_bf16 v[74:77], v[196:199], v[166:169], v[74:77]
	v_mfma_f32_16x16x32_bf16 v[8:11], v[204:207], v[166:169], v[8:11]
	v_mfma_f32_16x16x32_bf16 v[66:69], v[196:199], v[188:191], v[66:69]
	v_mfma_f32_16x16x32_bf16 v[0:3], v[204:207], v[188:191], v[0:3]
	s_add_i32 s22, 0, 0x18000
	v_add_u32_e32 v48, s22, v250
	s_barrier
	ds_read_b128 v[130:133], v48
	ds_read_b128 v[134:137], v48 offset:1024
	ds_read_b128 v[138:141], v48 offset:2048
	ds_read_b128 v[142:145], v48 offset:3072
	s_add_u32 s16, s16, 0x40000
	s_addc_u32 s17, s17, 0
	s_mov_b32 m0, s11
	v_lshl_add_u64 v[192:193], s[16:17], 0, v[176:177]
	ds_read_b128 v[146:149], v242 offset:32768
	ds_read_b128 v[150:153], v242 offset:33792
	ds_read_b128 v[154:157], v242 offset:34816
	ds_read_b128 v[158:161], v242 offset:35840
	ds_read_b128 v[162:165], v242 offset:36864
	ds_read_b128 v[166:169], v242 offset:37888
	ds_read_b128 v[170:173], v242 offset:38912
	ds_read_b128 v[188:191], v242 offset:39936
	global_load_lds_dwordx4 v[192:193], off
	v_lshl_add_u64 v[192:193], s[16:17], 0, v[180:181]
	s_mov_b32 m0, s24
	s_nop 0
	global_load_lds_dwordx4 v[192:193], off
	s_waitcnt lgkmcnt(8)
	s_barrier
	s_waitcnt lgkmcnt(7)
	v_mfma_f32_16x16x32_bf16 v[126:129], v[130:133], v[146:149], v[126:129]
	v_mfma_f32_16x16x32_bf16 v[62:65], v[138:141], v[146:149], v[62:65]
	s_waitcnt lgkmcnt(5)
	v_mfma_f32_16x16x32_bf16 v[118:121], v[130:133], v[154:157], v[118:121]
	v_mfma_f32_16x16x32_bf16 v[54:57], v[138:141], v[154:157], v[54:57]
	s_waitcnt lgkmcnt(3)
	v_mfma_f32_16x16x32_bf16 v[110:113], v[130:133], v[162:165], v[110:113]
	v_mfma_f32_16x16x32_bf16 v[44:47], v[138:141], v[162:165], v[44:47]
	s_waitcnt lgkmcnt(1)
	v_mfma_f32_16x16x32_bf16 v[102:105], v[130:133], v[170:173], v[102:105]
	v_mfma_f32_16x16x32_bf16 v[36:39], v[138:141], v[170:173], v[36:39]
	v_mfma_f32_16x16x32_bf16 v[126:129], v[134:137], v[150:153], v[126:129]
	v_mfma_f32_16x16x32_bf16 v[62:65], v[142:145], v[150:153], v[62:65]
	v_mfma_f32_16x16x32_bf16 v[118:121], v[134:137], v[158:161], v[118:121]
	v_mfma_f32_16x16x32_bf16 v[54:57], v[142:145], v[158:161], v[54:57]
	v_mfma_f32_16x16x32_bf16 v[110:113], v[134:137], v[166:169], v[110:113]
	v_mfma_f32_16x16x32_bf16 v[44:47], v[142:145], v[166:169], v[44:47]
	s_waitcnt lgkmcnt(0)
	v_mfma_f32_16x16x32_bf16 v[102:105], v[134:137], v[188:191], v[102:105]
	v_mfma_f32_16x16x32_bf16 v[36:39], v[142:145], v[188:191], v[36:39]
	s_barrier
	s_add_i32 s16, 0, 0x1c000
	s_add_i32 s17, s22, s36
	v_add_u32_e32 v48, s16, v250
	v_lshl_add_u64 v[208:209], v[208:209], 0, s[0:1]
	s_mov_b32 m0, s17
	ds_read_b128 v[192:195], v48
	ds_read_b128 v[196:199], v48 offset:1024
	ds_read_b128 v[200:203], v48 offset:2048
	ds_read_b128 v[204:207], v48 offset:3072
	global_load_lds_dwordx4 v[208:209], off
	v_lshl_add_u64 v[208:209], v[210:211], 0, s[0:1]
	s_add_i32 m0, s17, 0x2000
	s_nop 0
	global_load_lds_dwordx4 v[208:209], off
	s_barrier
	s_waitcnt lgkmcnt(3)
	v_mfma_f32_16x16x32_bf16 v[122:125], v[192:195], v[146:149], v[122:125]
	s_waitcnt lgkmcnt(1)
	v_mfma_f32_16x16x32_bf16 v[58:61], v[200:203], v[146:149], v[58:61]
	v_mfma_f32_16x16x32_bf16 v[114:117], v[192:195], v[154:157], v[114:117]
	v_mfma_f32_16x16x32_bf16 v[50:53], v[200:203], v[154:157], v[50:53]
	v_mfma_f32_16x16x32_bf16 v[106:109], v[192:195], v[162:165], v[106:109]
	v_mfma_f32_16x16x32_bf16 v[40:43], v[200:203], v[162:165], v[40:43]
	v_mfma_f32_16x16x32_bf16 v[98:101], v[192:195], v[170:173], v[98:101]
	v_mfma_f32_16x16x32_bf16 v[32:35], v[200:203], v[170:173], v[32:35]
	v_mfma_f32_16x16x32_bf16 v[122:125], v[196:199], v[150:153], v[122:125]
	s_waitcnt lgkmcnt(0)
	v_mfma_f32_16x16x32_bf16 v[58:61], v[204:207], v[150:153], v[58:61]
	v_mfma_f32_16x16x32_bf16 v[114:117], v[196:199], v[158:161], v[114:117]
	v_mfma_f32_16x16x32_bf16 v[50:53], v[204:207], v[158:161], v[50:53]
	v_mfma_f32_16x16x32_bf16 v[106:109], v[196:199], v[166:169], v[106:109]
	v_mfma_f32_16x16x32_bf16 v[40:43], v[204:207], v[166:169], v[40:43]
	v_mfma_f32_16x16x32_bf16 v[98:101], v[196:199], v[188:191], v[98:101]
	v_mfma_f32_16x16x32_bf16 v[32:35], v[204:207], v[188:191], v[32:35]
	s_mov_b32 m0, s25
	v_lshl_add_u64 v[208:209], v[212:213], 0, s[0:1]
	s_barrier
	ds_read_b128 v[146:149], v242 offset:49152
	ds_read_b128 v[150:153], v242 offset:50176
	ds_read_b128 v[154:157], v242 offset:51200
	ds_read_b128 v[158:161], v242 offset:52224
	ds_read_b128 v[162:165], v242 offset:53248
	ds_read_b128 v[166:169], v242 offset:54272
	ds_read_b128 v[170:173], v242 offset:55296
	ds_read_b128 v[188:191], v242 offset:56320
	global_load_lds_dwordx4 v[208:209], off
	v_lshl_add_u64 v[208:209], v[214:215], 0, s[0:1]
	s_mov_b32 m0, s18
	s_nop 0
	global_load_lds_dwordx4 v[208:209], off
	s_barrier
; #define PG8_STAGE(bufoff, gbase, voff) do { _Pragma("unroll") for (int _i = 0; _i < 2; ++_i) \
;         __builtin_amdgcn_global_load_lds((const unsigned*)((const char*)(gbase) + (voff)[_i]), (PG8_LAS unsigned*)(lds + (bufoff) + ldsw + _i * 8192), 16, 0, 0); } while (0)
; #define PG8_LDA(dst, b, h) do { _Pragma("unroll") for (int m = 0; m < 4; ++m) _Pragma("unroll") for (int k = 0; k < 2; ++k) dst[m][k] = *(const PG8_LAS bf16x8*)(lds + PG8_SA(b, h) + aoff + m * 2048 + k * 1024); } while (0)
; #define PG8_LDB(dst, b, h) do { _Pragma("unroll") for (int n = 0; n < 2; ++n) _Pragma("unroll") for (int k = 0; k < 2; ++k) dst[n][k] = *(const PG8_LAS bf16x8*)(lds + PG8_SB(b, h) + boff + n * 2048 + k * 1024); } while (0)
; #define PG8_MMA(ai, bj, At, Bt) do { __builtin_amdgcn_s_setprio(1); _Pragma("unroll") for (int m = 0; m < 4; ++m) _Pragma("unroll") for (int n = 0; n < 2; ++n) _Pragma("unroll") for (int k = 0; k < 2; ++k) \
;         acc[ai][bj][m][n] = __builtin_amdgcn_mfma_f32_16x16x32_bf16(Bt[n][k], At[m][k], acc[ai][bj][m][n], 0, 0, 0); __builtin_amdgcn_s_setprio(0); } while (0)
; #define PG8_WAIT_V(n) asm volatile("s_waitcnt vmcnt(" #n ")" ::: "memory")
; #define PG8_WAIT_L(n) asm volatile("s_waitcnt lgkmcnt(" #n ")" ::: "memory")
; #define PG8_BAR __builtin_amdgcn_s_barrier()
; #define PG8_SCHED __builtin_amdgcn_sched_barrier(0)
; template <class Epi, class Sched>
; __device__ __forceinline__ void gemm_phase(PG8_LAS unsigned char* lds, const Gemm g, const Sched& S, const Epi& E) {
;     ...
;             PG8_LDB(B0, 0, 0); PG8_SCHED; PG8_LDA(At, 0, 0); PG8_STAGE(PG8_SA(1, 1), a1 + hstep, voffA);
;             PG8_WAIT_L(8); PG8_BAR; PG8_WAIT_L(0); PG8_MMA(0, 0, At, B0); PG8_BAR; PG8_SCHED;
;             PG8_LDB(B1, 0, 1); PG8_STAGE(PG8_SB(0, 0), b2, voffB);
;     ...
;             PG8_BAR; PG8_WAIT_L(0); PG8_MMA(1, 0, At, B0); PG8_BAR; PG8_SCHED;
;             PG8_STAGE(PG8_SB(1, 1), b3 + hstep, voffB);
;             PG8_WAIT_V(6); PG8_BAR; PG8_MMA(1, 1, At, B1); PG8_BAR;
	s_waitcnt lgkmcnt(7)
	v_mfma_f32_16x16x32_bf16 v[94:97], v[130:133], v[146:149], v[94:97]
	v_mfma_f32_16x16x32_bf16 v[28:31], v[138:141], v[146:149], v[28:31]
	s_waitcnt lgkmcnt(5)
	v_mfma_f32_16x16x32_bf16 v[86:89], v[130:133], v[154:157], v[86:89]
	v_mfma_f32_16x16x32_bf16 v[20:23], v[138:141], v[154:157], v[20:23]
	s_waitcnt lgkmcnt(3)
	v_mfma_f32_16x16x32_bf16 v[78:81], v[130:133], v[162:165], v[78:81]
	v_mfma_f32_16x16x32_bf16 v[12:15], v[138:141], v[162:165], v[12:15]
	s_waitcnt lgkmcnt(1)
	v_mfma_f32_16x16x32_bf16 v[70:73], v[130:133], v[170:173], v[70:73]
	v_mfma_f32_16x16x32_bf16 v[4:7], v[138:141], v[170:173], v[4:7]
	v_mfma_f32_16x16x32_bf16 v[94:97], v[134:137], v[150:153], v[94:97]
	v_mfma_f32_16x16x32_bf16 v[28:31], v[142:145], v[150:153], v[28:31]
	v_mfma_f32_16x16x32_bf16 v[86:89], v[134:137], v[158:161], v[86:89]
	v_mfma_f32_16x16x32_bf16 v[20:23], v[142:145], v[158:161], v[20:23]
	v_mfma_f32_16x16x32_bf16 v[78:81], v[134:137], v[166:169], v[78:81]
	v_mfma_f32_16x16x32_bf16 v[12:15], v[142:145], v[166:169], v[12:15]
	s_waitcnt lgkmcnt(0)
	v_mfma_f32_16x16x32_bf16 v[70:73], v[134:137], v[188:191], v[70:73]
	v_mfma_f32_16x16x32_bf16 v[4:7], v[142:145], v[188:191], v[4:7]
	s_barrier
	s_add_u32 s12, s12, 0x40080
	s_addc_u32 s13, s13, 0
	s_add_i32 s16, s16, s36
	v_lshl_add_u64 v[130:131], s[12:13], 0, v[178:179]
	s_mov_b32 m0, s16
	s_nop 0
	global_load_lds_dwordx4 v[130:131], off
	v_lshl_add_u64 v[130:131], s[12:13], 0, v[182:183]
	s_add_i32 m0, s16, 0x2000
	s_nop 0
	global_load_lds_dwordx4 v[130:131], off
	s_waitcnt vmcnt(6)
	s_barrier
	v_mfma_f32_16x16x32_bf16 v[90:93], v[192:195], v[146:149], v[90:93]
	v_mfma_f32_16x16x32_bf16 v[24:27], v[200:203], v[146:149], v[24:27]
	v_mfma_f32_16x16x32_bf16 v[82:85], v[192:195], v[154:157], v[82:85]
	v_mfma_f32_16x16x32_bf16 v[16:19], v[200:203], v[154:157], v[16:19]
	v_mfma_f32_16x16x32_bf16 v[74:77], v[192:195], v[162:165], v[74:77]
	v_mfma_f32_16x16x32_bf16 v[8:11], v[200:203], v[162:165], v[8:11]
	v_mfma_f32_16x16x32_bf16 v[66:69], v[192:195], v[170:173], v[66:69]
	v_mfma_f32_16x16x32_bf16 v[0:3], v[200:203], v[170:173], v[0:3]
	v_mfma_f32_16x16x32_bf16 v[90:93], v[196:199], v[150:153], v[90:93]
	v_mfma_f32_16x16x32_bf16 v[24:27], v[204:207], v[150:153], v[24:27]
	v_mfma_f32_16x16x32_bf16 v[82:85], v[196:199], v[158:161], v[82:85]
	v_mfma_f32_16x16x32_bf16 v[16:19], v[204:207], v[158:161], v[16:19]
	v_mfma_f32_16x16x32_bf16 v[74:77], v[196:199], v[166:169], v[74:77]
	v_mfma_f32_16x16x32_bf16 v[8:11], v[204:207], v[166:169], v[8:11]
	v_mfma_f32_16x16x32_bf16 v[66:69], v[196:199], v[188:191], v[66:69]
	v_mfma_f32_16x16x32_bf16 v[0:3], v[204:207], v[188:191], v[0:3]
	s_add_i32 s30, s30, 2
	s_add_u32 s6, s6, 0x100
	s_addc_u32 s7, s7, 0
	s_add_u32 s27, s27, 0x100
	s_addc_u32 s29, s29, 0
	s_cmp_gt_u32 s30, 13
	s_barrier
	s_cbranch_scc1 .Lkpeel_exit_388
.LBB0_388:
	s_add_u32 s12, s6, 0xfffc0080
	s_addc_u32 s13, s7, -1
	s_add_i32 s22, 0, 0x10000
	v_add_u32_e32 v48, s22, v250
	ds_read_b128 v[130:133], v48
	ds_read_b128 v[134:137], v48 offset:1024
	ds_read_b128 v[138:141], v48 offset:2048
	ds_read_b128 v[142:145], v48 offset:3072
	s_cmp_eq_u32 s30, 12
	s_cselect_b32 s17, s9, s13
	s_cselect_b32 s16, s8, s12
	s_cselect_b32 s13, s3, s29
	s_cselect_b32 s12, s26, s27
	v_lshl_add_u64 v[192:193], s[6:7], 0, v[184:185]
	s_add_i32 m0, s37, 0xc000
	ds_read_b128 v[146:149], v242
	ds_read_b128 v[150:153], v242 offset:1024
	ds_read_b128 v[154:157], v242 offset:2048
	ds_read_b128 v[158:161], v242 offset:3072
	ds_read_b128 v[162:165], v242 offset:4096
	ds_read_b128 v[166:169], v242 offset:5120
	ds_read_b128 v[170:173], v242 offset:6144
	ds_read_b128 v[188:191], v242 offset:7168
	global_load_lds_dwordx4 v[192:193], off
	v_lshl_add_u64 v[192:193], s[6:7], 0, v[186:187]
	s_add_i32 m0, s37, 0xe000
	s_nop 0
	global_load_lds_dwordx4 v[192:193], off
	s_waitcnt lgkmcnt(8)
	s_barrier
	s_waitcnt lgkmcnt(7)
	v_mfma_f32_16x16x32_bf16 v[126:129], v[130:133], v[146:149], v[126:129]
	v_mfma_f32_16x16x32_bf16 v[62:65], v[138:141], v[146:149], v[62:65]
	s_waitcnt lgkmcnt(5)
	v_mfma_f32_16x16x32_bf16 v[118:121], v[130:133], v[154:157], v[118:121]
	v_mfma_f32_16x16x32_bf16 v[54:57], v[138:141], v[154:157], v[54:57]
	s_waitcnt lgkmcnt(3)
	v_mfma_f32_16x16x32_bf16 v[110:113], v[130:133], v[162:165], v[110:113]
	v_mfma_f32_16x16x32_bf16 v[44:47], v[138:141], v[162:165], v[44:47]
	s_waitcnt lgkmcnt(1)
	v_mfma_f32_16x16x32_bf16 v[102:105], v[130:133], v[170:173], v[102:105]
	v_mfma_f32_16x16x32_bf16 v[36:39], v[138:141], v[170:173], v[36:39]
	v_mfma_f32_16x16x32_bf16 v[126:129], v[134:137], v[150:153], v[126:129]
	v_mfma_f32_16x16x32_bf16 v[62:65], v[142:145], v[150:153], v[62:65]
	v_mfma_f32_16x16x32_bf16 v[118:121], v[134:137], v[158:161], v[118:121]
	v_mfma_f32_16x16x32_bf16 v[54:57], v[142:145], v[158:161], v[54:57]
	v_mfma_f32_16x16x32_bf16 v[110:113], v[134:137], v[166:169], v[110:113]
	v_mfma_f32_16x16x32_bf16 v[44:47], v[142:145], v[166:169], v[44:47]
	s_waitcnt lgkmcnt(0)
	v_mfma_f32_16x16x32_bf16 v[102:105], v[134:137], v[188:191], v[102:105]
	v_mfma_f32_16x16x32_bf16 v[36:39], v[142:145], v[188:191], v[36:39]
	s_barrier
	s_add_i32 s31, 0, 0x14000
	s_add_i32 s22, s22, s36
	v_add_u32_e32 v48, s31, v250
	v_lshl_add_u64 v[208:209], s[12:13], 0, v[178:179]
	s_mov_b32 m0, s22
	ds_read_b128 v[192:195], v48
	ds_read_b128 v[196:199], v48 offset:1024
	ds_read_b128 v[200:203], v48 offset:2048
	ds_read_b128 v[204:207], v48 offset:3072
	global_load_lds_dwordx4 v[208:209], off
	v_lshl_add_u64 v[210:211], s[12:13], 0, v[182:183]
	s_add_i32 m0, s22, 0x2000
	s_nop 0
	global_load_lds_dwordx4 v[210:211], off
	s_barrier
; #define PG8_STAGE(bufoff, gbase, voff) do { _Pragma("unroll") for (int _i = 0; _i < 2; ++_i) \
;         __builtin_amdgcn_global_load_lds((const unsigned*)((const char*)(gbase) + (voff)[_i]), (PG8_LAS unsigned*)(lds + (bufoff) + ldsw + _i * 8192), 16, 0, 0); } while (0)
; #define PG8_LDA(dst, b, h) do { _Pragma("unroll") for (int m = 0; m < 4; ++m) _Pragma("unroll") for (int k = 0; k < 2; ++k) dst[m][k] = *(const PG8_LAS bf16x8*)(lds + PG8_SA(b, h) + aoff + m * 2048 + k * 1024); } while (0)
; #define PG8_LDB(dst, b, h) do { _Pragma("unroll") for (int n = 0; n < 2; ++n) _Pragma("unroll") for (int k = 0; k < 2; ++k) dst[n][k] = *(const PG8_LAS bf16x8*)(lds + PG8_SB(b, h) + boff + n * 2048 + k * 1024); } while (0)
; #define PG8_MMA(ai, bj, At, Bt) do { __builtin_amdgcn_s_setprio(1); _Pragma("unroll") for (int m = 0; m < 4; ++m) _Pragma("unroll") for (int n = 0; n < 2; ++n) _Pragma("unroll") for (int k = 0; k < 2; ++k) \
;         acc[ai][bj][m][n] = __builtin_amdgcn_mfma_f32_16x16x32_bf16(Bt[n][k], At[m][k], acc[ai][bj][m][n], 0, 0, 0); __builtin_amdgcn_s_setprio(0); } while (0)
; #define PG8_WAIT_V(n) asm volatile("s_waitcnt vmcnt(" #n ")" ::: "memory")
; #define PG8_WAIT_L(n) asm volatile("s_waitcnt lgkmcnt(" #n ")" ::: "memory")
; #define PG8_BAR __builtin_amdgcn_s_barrier()
; #define PG8_SCHED __builtin_amdgcn_sched_barrier(0)
; template <class Epi, class Sched>
; __device__ __forceinline__ void gemm_phase(PG8_LAS unsigned char* lds, const Gemm g, const Sched& S, const Epi& E) {
;     ...
;             PG8_BAR; PG8_WAIT_L(0); PG8_MMA(0, 1, At, B1); PG8_BAR;
;             PG8_LDA(At, 0, 1); PG8_STAGE(PG8_SA(0, 0), a2, voffA);
;             PG8_BAR; PG8_WAIT_L(0); PG8_MMA(1, 0, At, B0); PG8_BAR; PG8_SCHED;
;             PG8_STAGE(PG8_SB(0, 1), b2 + hstep, voffB);
;             PG8_WAIT_V(6); PG8_BAR; PG8_MMA(1, 1, At, B1); PG8_BAR;
;             PG8_LDB(B0, 1, 0); PG8_SCHED; PG8_LDA(At, 1, 0); PG8_STAGE(PG8_SA(0, 1), a2 + hstep, voffA);
;             PG8_WAIT_L(8); PG8_BAR; PG8_WAIT_L(0); PG8_MMA(0, 0, At, B0); PG8_BAR; PG8_SCHED;
	s_waitcnt lgkmcnt(3)
	v_mfma_f32_16x16x32_bf16 v[122:125], v[192:195], v[146:149], v[122:125]
	s_waitcnt lgkmcnt(1)
	v_mfma_f32_16x16x32_bf16 v[58:61], v[200:203], v[146:149], v[58:61]
	v_mfma_f32_16x16x32_bf16 v[114:117], v[192:195], v[154:157], v[114:117]
	v_mfma_f32_16x16x32_bf16 v[50:53], v[200:203], v[154:157], v[50:53]
	v_mfma_f32_16x16x32_bf16 v[106:109], v[192:195], v[162:165], v[106:109]
	v_mfma_f32_16x16x32_bf16 v[40:43], v[200:203], v[162:165], v[40:43]
	v_mfma_f32_16x16x32_bf16 v[98:101], v[192:195], v[170:173], v[98:101]
	v_mfma_f32_16x16x32_bf16 v[32:35], v[200:203], v[170:173], v[32:35]
	v_mfma_f32_16x16x32_bf16 v[122:125], v[196:199], v[150:153], v[122:125]
	s_waitcnt lgkmcnt(0)
	v_mfma_f32_16x16x32_bf16 v[58:61], v[204:207], v[150:153], v[58:61]
	v_mfma_f32_16x16x32_bf16 v[114:117], v[196:199], v[158:161], v[114:117]
	v_mfma_f32_16x16x32_bf16 v[50:53], v[204:207], v[158:161], v[50:53]
	v_mfma_f32_16x16x32_bf16 v[106:109], v[196:199], v[166:169], v[106:109]
	v_mfma_f32_16x16x32_bf16 v[40:43], v[204:207], v[166:169], v[40:43]
	v_mfma_f32_16x16x32_bf16 v[98:101], v[196:199], v[188:191], v[98:101]
	v_mfma_f32_16x16x32_bf16 v[32:35], v[204:207], v[188:191], v[32:35]
	s_mov_b32 m0, s37
	v_lshl_add_u64 v[212:213], s[16:17], 0, v[176:177]
	s_barrier
	ds_read_b128 v[146:149], v242 offset:16384
	ds_read_b128 v[150:153], v242 offset:17408
	ds_read_b128 v[154:157], v242 offset:18432
	ds_read_b128 v[158:161], v242 offset:19456
	ds_read_b128 v[162:165], v242 offset:20480
	ds_read_b128 v[166:169], v242 offset:21504
	ds_read_b128 v[170:173], v242 offset:22528
	ds_read_b128 v[188:191], v242 offset:23552
	global_load_lds_dwordx4 v[212:213], off
	v_lshl_add_u64 v[214:215], s[16:17], 0, v[180:181]
	s_mov_b32 m0, s10
	s_nop 0
	global_load_lds_dwordx4 v[214:215], off
	s_barrier
	s_waitcnt lgkmcnt(7)
	v_mfma_f32_16x16x32_bf16 v[94:97], v[130:133], v[146:149], v[94:97]
	v_mfma_f32_16x16x32_bf16 v[28:31], v[138:141], v[146:149], v[28:31]
	s_waitcnt lgkmcnt(5)
	v_mfma_f32_16x16x32_bf16 v[86:89], v[130:133], v[154:157], v[86:89]
	v_mfma_f32_16x16x32_bf16 v[20:23], v[138:141], v[154:157], v[20:23]
	s_waitcnt lgkmcnt(3)
	v_mfma_f32_16x16x32_bf16 v[78:81], v[130:133], v[162:165], v[78:81]
	v_mfma_f32_16x16x32_bf16 v[12:15], v[138:141], v[162:165], v[12:15]
	s_waitcnt lgkmcnt(1)
	v_mfma_f32_16x16x32_bf16 v[70:73], v[130:133], v[170:173], v[70:73]
	v_mfma_f32_16x16x32_bf16 v[4:7], v[138:141], v[170:173], v[4:7]
	v_mfma_f32_16x16x32_bf16 v[94:97], v[134:137], v[150:153], v[94:97]
	v_mfma_f32_16x16x32_bf16 v[28:31], v[142:145], v[150:153], v[28:31]
	v_mfma_f32_16x16x32_bf16 v[86:89], v[134:137], v[158:161], v[86:89]
	v_mfma_f32_16x16x32_bf16 v[20:23], v[142:145], v[158:161], v[20:23]
	v_mfma_f32_16x16x32_bf16 v[78:81], v[134:137], v[166:169], v[78:81]
	v_mfma_f32_16x16x32_bf16 v[12:15], v[142:145], v[166:169], v[12:15]
	s_waitcnt lgkmcnt(0)
	v_mfma_f32_16x16x32_bf16 v[70:73], v[134:137], v[188:191], v[70:73]
	v_mfma_f32_16x16x32_bf16 v[4:7], v[142:145], v[188:191], v[4:7]
	s_barrier
	s_add_u32 s22, s12, 0x40000
	s_addc_u32 s23, s13, 0
	s_add_i32 s31, s31, s36
	v_lshl_add_u64 v[130:131], s[22:23], 0, v[178:179]
	s_mov_b32 m0, s31
	s_nop 0
	global_load_lds_dwordx4 v[130:131], off
	v_lshl_add_u64 v[130:131], s[22:23], 0, v[182:183]
	s_add_i32 m0, s31, 0x2000
	s_nop 0
	global_load_lds_dwordx4 v[130:131], off
	s_waitcnt vmcnt(6)
	s_barrier
	v_mfma_f32_16x16x32_bf16 v[90:93], v[192:195], v[146:149], v[90:93]
	v_mfma_f32_16x16x32_bf16 v[24:27], v[200:203], v[146:149], v[24:27]
	v_mfma_f32_16x16x32_bf16 v[82:85], v[192:195], v[154:157], v[82:85]
	v_mfma_f32_16x16x32_bf16 v[16:19], v[200:203], v[154:157], v[16:19]
	v_mfma_f32_16x16x32_bf16 v[74:77], v[192:195], v[162:165], v[74:77]
	v_mfma_f32_16x16x32_bf16 v[8:11], v[200:203], v[162:165], v[8:11]
	v_mfma_f32_16x16x32_bf16 v[66:69], v[192:195], v[170:173], v[66:69]
	v_mfma_f32_16x16x32_bf16 v[0:3], v[200:203], v[170:173], v[0:3]
	v_mfma_f32_16x16x32_bf16 v[90:93], v[196:199], v[150:153], v[90:93]
	v_mfma_f32_16x16x32_bf16 v[24:27], v[204:207], v[150:153], v[24:27]
	v_mfma_f32_16x16x32_bf16 v[82:85], v[196:199], v[158:161], v[82:85]
	v_mfma_f32_16x16x32_bf16 v[16:19], v[204:207], v[158:161], v[16:19]
	v_mfma_f32_16x16x32_bf16 v[74:77], v[196:199], v[166:169], v[74:77]
	v_mfma_f32_16x16x32_bf16 v[8:11], v[204:207], v[166:169], v[8:11]
	v_mfma_f32_16x16x32_bf16 v[66:69], v[196:199], v[188:191], v[66:69]
	v_mfma_f32_16x16x32_bf16 v[0:3], v[204:207], v[188:191], v[0:3]
	s_add_i32 s22, 0, 0x18000
	v_add_u32_e32 v48, s22, v250
	s_barrier
	ds_read_b128 v[130:133], v48
	ds_read_b128 v[134:137], v48 offset:1024
	ds_read_b128 v[138:141], v48 offset:2048
	ds_read_b128 v[142:145], v48 offset:3072
	s_add_u32 s16, s16, 0x40000
	s_addc_u32 s17, s17, 0
	s_mov_b32 m0, s11
	v_lshl_add_u64 v[192:193], s[16:17], 0, v[176:177]
	ds_read_b128 v[146:149], v242 offset:32768
	ds_read_b128 v[150:153], v242 offset:33792
	ds_read_b128 v[154:157], v242 offset:34816
	ds_read_b128 v[158:161], v242 offset:35840
	ds_read_b128 v[162:165], v242 offset:36864
	ds_read_b128 v[166:169], v242 offset:37888
	ds_read_b128 v[170:173], v242 offset:38912
	ds_read_b128 v[188:191], v242 offset:39936
	global_load_lds_dwordx4 v[192:193], off
	v_lshl_add_u64 v[192:193], s[16:17], 0, v[180:181]
	s_mov_b32 m0, s24
	s_nop 0
	global_load_lds_dwordx4 v[192:193], off
	s_waitcnt lgkmcnt(8)
	s_barrier
; #define PG8_STAGE(bufoff, gbase, voff) do { _Pragma("unroll") for (int _i = 0; _i < 2; ++_i) \
;         __builtin_amdgcn_global_load_lds((const unsigned*)((const char*)(gbase) + (voff)[_i]), (PG8_LAS unsigned*)(lds + (bufoff) + ldsw + _i * 8192), 16, 0, 0); } while (0)
; #define PG8_LDA(dst, b, h) do { _Pragma("unroll") for (int m = 0; m < 4; ++m) _Pragma("unroll") for (int k = 0; k < 2; ++k) dst[m][k] = *(const PG8_LAS bf16x8*)(lds + PG8_SA(b, h) + aoff + m * 2048 + k * 1024); } while (0)
; #define PG8_LDB(dst, b, h) do { _Pragma("unroll") for (int n = 0; n < 2; ++n) _Pragma("unroll") for (int k = 0; k < 2; ++k) dst[n][k] = *(const PG8_LAS bf16x8*)(lds + PG8_SB(b, h) + boff + n * 2048 + k * 1024); } while (0)
; #define PG8_MMA(ai, bj, At, Bt) do { __builtin_amdgcn_s_setprio(1); _Pragma("unroll") for (int m = 0; m < 4; ++m) _Pragma("unroll") for (int n = 0; n < 2; ++n) _Pragma("unroll") for (int k = 0; k < 2; ++k) \
;         acc[ai][bj][m][n] = __builtin_amdgcn_mfma_f32_16x16x32_bf16(Bt[n][k], At[m][k], acc[ai][bj][m][n], 0, 0, 0); __builtin_amdgcn_s_setprio(0); } while (0)
; #define PG8_WAIT_V(n) asm volatile("s_waitcnt vmcnt(" #n ")" ::: "memory")
; #define PG8_WAIT_L(n) asm volatile("s_waitcnt lgkmcnt(" #n ")" ::: "memory")
; #define PG8_BAR __builtin_amdgcn_s_barrier()
; #define PG8_SCHED __builtin_amdgcn_sched_barrier(0)
; template <class Epi, class Sched>
; __device__ __forceinline__ void gemm_phase(PG8_LAS unsigned char* lds, const Gemm g, const Sched& S, const Epi& E) {
;     ...
;             PG8_WAIT_L(8); PG8_BAR; PG8_WAIT_L(0); PG8_MMA(0, 0, At, B0); PG8_BAR; PG8_SCHED;
;             PG8_LDB(B1, 1, 1); PG8_STAGE(PG8_SB(1, 0), b3, voffB);
;             PG8_BAR; PG8_WAIT_L(0); PG8_MMA(0, 1, At, B1); PG8_BAR;
;             PG8_LDA(At, 1, 1); PG8_STAGE(PG8_SA(1, 0), a3, voffA);
;             PG8_BAR; PG8_WAIT_L(0); PG8_MMA(1, 0, At, B0); PG8_BAR; PG8_SCHED;
;             PG8_STAGE(PG8_SB(1, 1), b3 + hstep, voffB);
;             PG8_WAIT_V(6); PG8_BAR; PG8_MMA(1, 1, At, B1); PG8_BAR;
	s_waitcnt lgkmcnt(7)
	v_mfma_f32_16x16x32_bf16 v[126:129], v[130:133], v[146:149], v[126:129]
	v_mfma_f32_16x16x32_bf16 v[62:65], v[138:141], v[146:149], v[62:65]
	s_waitcnt lgkmcnt(5)
	v_mfma_f32_16x16x32_bf16 v[118:121], v[130:133], v[154:157], v[118:121]
	v_mfma_f32_16x16x32_bf16 v[54:57], v[138:141], v[154:157], v[54:57]
	s_waitcnt lgkmcnt(3)
	v_mfma_f32_16x16x32_bf16 v[110:113], v[130:133], v[162:165], v[110:113]
	v_mfma_f32_16x16x32_bf16 v[44:47], v[138:141], v[162:165], v[44:47]
	s_waitcnt lgkmcnt(1)
	v_mfma_f32_16x16x32_bf16 v[102:105], v[130:133], v[170:173], v[102:105]
	v_mfma_f32_16x16x32_bf16 v[36:39], v[138:141], v[170:173], v[36:39]
	v_mfma_f32_16x16x32_bf16 v[126:129], v[134:137], v[150:153], v[126:129]
	v_mfma_f32_16x16x32_bf16 v[62:65], v[142:145], v[150:153], v[62:65]
	v_mfma_f32_16x16x32_bf16 v[118:121], v[134:137], v[158:161], v[118:121]
	v_mfma_f32_16x16x32_bf16 v[54:57], v[142:145], v[158:161], v[54:57]
	v_mfma_f32_16x16x32_bf16 v[110:113], v[134:137], v[166:169], v[110:113]
	v_mfma_f32_16x16x32_bf16 v[44:47], v[142:145], v[166:169], v[44:47]
	s_waitcnt lgkmcnt(0)
	v_mfma_f32_16x16x32_bf16 v[102:105], v[134:137], v[188:191], v[102:105]
	v_mfma_f32_16x16x32_bf16 v[36:39], v[142:145], v[188:191], v[36:39]
	s_barrier
	s_add_i32 s16, 0, 0x1c000
	s_add_i32 s17, s22, s36
	v_add_u32_e32 v48, s16, v250
	v_lshl_add_u64 v[208:209], v[208:209], 0, s[0:1]
	s_mov_b32 m0, s17
	ds_read_b128 v[192:195], v48
	ds_read_b128 v[196:199], v48 offset:1024
	ds_read_b128 v[200:203], v48 offset:2048
	ds_read_b128 v[204:207], v48 offset:3072
	global_load_lds_dwordx4 v[208:209], off
	v_lshl_add_u64 v[208:209], v[210:211], 0, s[0:1]
	s_add_i32 m0, s17, 0x2000
	s_nop 0
	global_load_lds_dwordx4 v[208:209], off
	s_barrier
	s_waitcnt lgkmcnt(3)
	v_mfma_f32_16x16x32_bf16 v[122:125], v[192:195], v[146:149], v[122:125]
	s_waitcnt lgkmcnt(1)
	v_mfma_f32_16x16x32_bf16 v[58:61], v[200:203], v[146:149], v[58:61]
	v_mfma_f32_16x16x32_bf16 v[114:117], v[192:195], v[154:157], v[114:117]
	v_mfma_f32_16x16x32_bf16 v[50:53], v[200:203], v[154:157], v[50:53]
	v_mfma_f32_16x16x32_bf16 v[106:109], v[192:195], v[162:165], v[106:109]
	v_mfma_f32_16x16x32_bf16 v[40:43], v[200:203], v[162:165], v[40:43]
	v_mfma_f32_16x16x32_bf16 v[98:101], v[192:195], v[170:173], v[98:101]
	v_mfma_f32_16x16x32_bf16 v[32:35], v[200:203], v[170:173], v[32:35]
	v_mfma_f32_16x16x32_bf16 v[122:125], v[196:199], v[150:153], v[122:125]
	s_waitcnt lgkmcnt(0)
	v_mfma_f32_16x16x32_bf16 v[58:61], v[204:207], v[150:153], v[58:61]
	v_mfma_f32_16x16x32_bf16 v[114:117], v[196:199], v[158:161], v[114:117]
	v_mfma_f32_16x16x32_bf16 v[50:53], v[204:207], v[158:161], v[50:53]
	v_mfma_f32_16x16x32_bf16 v[106:109], v[196:199], v[166:169], v[106:109]
	v_mfma_f32_16x16x32_bf16 v[40:43], v[204:207], v[166:169], v[40:43]
	v_mfma_f32_16x16x32_bf16 v[98:101], v[196:199], v[188:191], v[98:101]
	v_mfma_f32_16x16x32_bf16 v[32:35], v[204:207], v[188:191], v[32:35]
	s_mov_b32 m0, s25
	v_lshl_add_u64 v[208:209], v[212:213], 0, s[0:1]
	s_barrier
	ds_read_b128 v[146:149], v242 offset:49152
	ds_read_b128 v[150:153], v242 offset:50176
	ds_read_b128 v[154:157], v242 offset:51200
	ds_read_b128 v[158:161], v242 offset:52224
	ds_read_b128 v[162:165], v242 offset:53248
	ds_read_b128 v[166:169], v242 offset:54272
	ds_read_b128 v[170:173], v242 offset:55296
	ds_read_b128 v[188:191], v242 offset:56320
	global_load_lds_dwordx4 v[208:209], off
	v_lshl_add_u64 v[208:209], v[214:215], 0, s[0:1]
	s_mov_b32 m0, s18
	s_nop 0
	global_load_lds_dwordx4 v[208:209], off
	s_barrier
	s_waitcnt lgkmcnt(7)
	v_mfma_f32_16x16x32_bf16 v[94:97], v[130:133], v[146:149], v[94:97]
	v_mfma_f32_16x16x32_bf16 v[28:31], v[138:141], v[146:149], v[28:31]
	s_waitcnt lgkmcnt(5)
	v_mfma_f32_16x16x32_bf16 v[86:89], v[130:133], v[154:157], v[86:89]
	v_mfma_f32_16x16x32_bf16 v[20:23], v[138:141], v[154:157], v[20:23]
	s_waitcnt lgkmcnt(3)
	v_mfma_f32_16x16x32_bf16 v[78:81], v[130:133], v[162:165], v[78:81]
	v_mfma_f32_16x16x32_bf16 v[12:15], v[138:141], v[162:165], v[12:15]
	s_waitcnt lgkmcnt(1)
	v_mfma_f32_16x16x32_bf16 v[70:73], v[130:133], v[170:173], v[70:73]
	v_mfma_f32_16x16x32_bf16 v[4:7], v[138:141], v[170:173], v[4:7]
	v_mfma_f32_16x16x32_bf16 v[94:97], v[134:137], v[150:153], v[94:97]
	v_mfma_f32_16x16x32_bf16 v[28:31], v[142:145], v[150:153], v[28:31]
	v_mfma_f32_16x16x32_bf16 v[86:89], v[134:137], v[158:161], v[86:89]
	v_mfma_f32_16x16x32_bf16 v[20:23], v[142:145], v[158:161], v[20:23]
	v_mfma_f32_16x16x32_bf16 v[78:81], v[134:137], v[166:169], v[78:81]
	v_mfma_f32_16x16x32_bf16 v[12:15], v[142:145], v[166:169], v[12:15]
	s_waitcnt lgkmcnt(0)
	v_mfma_f32_16x16x32_bf16 v[70:73], v[134:137], v[188:191], v[70:73]
	v_mfma_f32_16x16x32_bf16 v[4:7], v[142:145], v[188:191], v[4:7]
	s_barrier
	s_add_u32 s12, s12, 0x40080
	s_addc_u32 s13, s13, 0
	s_add_i32 s16, s16, s36
	v_lshl_add_u64 v[130:131], s[12:13], 0, v[178:179]
	s_mov_b32 m0, s16
	s_nop 0
	global_load_lds_dwordx4 v[130:131], off
	v_lshl_add_u64 v[130:131], s[12:13], 0, v[182:183]
	s_add_i32 m0, s16, 0x2000
	s_nop 0
	global_load_lds_dwordx4 v[130:131], off
	s_waitcnt vmcnt(6)
	s_barrier
	v_mfma_f32_16x16x32_bf16 v[90:93], v[192:195], v[146:149], v[90:93]
	v_mfma_f32_16x16x32_bf16 v[24:27], v[200:203], v[146:149], v[24:27]
	v_mfma_f32_16x16x32_bf16 v[82:85], v[192:195], v[154:157], v[82:85]
	v_mfma_f32_16x16x32_bf16 v[16:19], v[200:203], v[154:157], v[16:19]
	v_mfma_f32_16x16x32_bf16 v[74:77], v[192:195], v[162:165], v[74:77]
	v_mfma_f32_16x16x32_bf16 v[8:11], v[200:203], v[162:165], v[8:11]
	v_mfma_f32_16x16x32_bf16 v[66:69], v[192:195], v[170:173], v[66:69]
	v_mfma_f32_16x16x32_bf16 v[0:3], v[200:203], v[170:173], v[0:3]
	v_mfma_f32_16x16x32_bf16 v[90:93], v[196:199], v[150:153], v[90:93]
	v_mfma_f32_16x16x32_bf16 v[24:27], v[204:207], v[150:153], v[24:27]
	v_mfma_f32_16x16x32_bf16 v[82:85], v[196:199], v[158:161], v[82:85]
	v_mfma_f32_16x16x32_bf16 v[16:19], v[204:207], v[158:161], v[16:19]
	v_mfma_f32_16x16x32_bf16 v[74:77], v[196:199], v[166:169], v[74:77]
	v_mfma_f32_16x16x32_bf16 v[8:11], v[204:207], v[166:169], v[8:11]
	v_mfma_f32_16x16x32_bf16 v[66:69], v[196:199], v[188:191], v[66:69]
	v_mfma_f32_16x16x32_bf16 v[0:3], v[204:207], v[188:191], v[0:3]
	s_add_i32 s30, s30, 2
	s_add_u32 s6, s6, 0x100
	s_addc_u32 s7, s7, 0
	s_add_u32 s27, s27, 0x100
	s_addc_u32 s29, s29, 0
	s_cmp_gt_u32 s30, 13
	s_barrier
	s_cbranch_scc0 .LBB0_388
